# exact trims on top of the scan loader version: log range-scaling ops removed in the prep epilogue (identities for 1-k), NaN-canonicalising v_max x,x,x removed in the top-k sorting networks (identities
# speedup vs baseline: 1.0016x; 1.0016x over previous
; #define GAS __attribute__((address_space(1)))
; #define LAS __attribute__((address_space(3)))
; __device__ __forceinline__ void phase_topk_fast(LAS unsigned char* lds, const bf16* Q, const bf16* keysb  , int* EID, float* GATE, bool prestaged  ) {
;     ...
;                 for (int blk = 0; blk < 4; ++blk) {
; #pragma unroll
;                     for (int r = 0; r < 16; ++r) acc[blk][r] = 0.f;
; #pragma unroll
;                     for (int ks = 0; ks < 8; ++ks) { const bf16x8 a = *(const LAS bf16x8*)(lds + (p * 128 + 32 * blk + c) * 272 + (16 * ks + 8 * hh) * 2);
;                         acc[blk] = __builtin_amdgcn_mfma_f32_32x32x16_bf16(a, bq[ks], acc[blk], 0, 0, 0); }
;                 }
;                 __builtin_amdgcn_sched_barrier(0);
;                 { const int nit = (p == 0) ? it : it + 1; const int np = (p == 0) ? 1 : 0;
;                   const size_t ntok0 = (size_t)(rank * 8 + wave + 256 * (nit < 4 ? nit : 3)) * 32;
;                   int cq = c; asm volatile("" : "+v"(cq)); const bf16* qrow = Q + (ntok0 + cq) * 2048 + h * 256 + np * 128 + 8 * hh;
; #pragma unroll
;                   for (int ks = 0; ks < 8; ++ks) bq[ks] = *(const GAS bf16x8*)(qrow + 16 * ks); }
;                 __builtin_amdgcn_sched_barrier(0);
;                 float v[64];
; #pragma unroll
;                 for (int blk = 0; blk < 4; ++blk)
; #pragma unroll
;                     for (int r = 0; r < 16; ++r)
;                     { const float sv = acc[blk][r]; v[blk * 16 + r] = __uint_as_float((__float_as_uint(sv) & ~127u) | (unsigned)(32 * blk + (r & 3) + 8 * (r >> 2)) | (unsigned)(hh << 2)); }
.LBB0_844:
	s_waitcnt lgkmcnt(14)
	ds_read_b128 v[2:5], v103
	s_waitcnt lgkmcnt(6)
	ds_read_b128 v[18:21], v103 offset:32
	s_waitcnt vmcnt(7) lgkmcnt(1)
	v_mfma_f32_32x32x16_bf16 v[2:17], v[2:5], v[90:93], 0
	s_waitcnt vmcnt(6) lgkmcnt(0)
	v_mfma_f32_32x32x16_bf16 v[2:17], v[18:21], v[94:97], v[2:17]
	ds_read_b128 v[18:21], v103 offset:64
	ds_read_b128 v[22:25], v103 offset:96
	s_waitcnt vmcnt(5) lgkmcnt(1)
	v_mfma_f32_32x32x16_bf16 v[2:17], v[18:21], v[82:85], v[2:17]
	s_waitcnt vmcnt(4) lgkmcnt(0)
	v_mfma_f32_32x32x16_bf16 v[2:17], v[22:25], v[86:89], v[2:17]
	ds_read_b128 v[18:21], v103 offset:128
	ds_read_b128 v[22:25], v103 offset:160
	s_waitcnt vmcnt(3) lgkmcnt(1)
	v_mfma_f32_32x32x16_bf16 v[2:17], v[18:21], v[74:77], v[2:17]
	s_waitcnt vmcnt(2) lgkmcnt(0)
	v_mfma_f32_32x32x16_bf16 v[2:17], v[22:25], v[78:81], v[2:17]
	ds_read_b128 v[18:21], v103 offset:192
	ds_read_b128 v[22:25], v103 offset:224
	s_waitcnt vmcnt(1) lgkmcnt(1)
	v_mfma_f32_32x32x16_bf16 v[2:17], v[18:21], v[66:69], v[2:17]
	ds_read_b128 v[18:21], v103 offset:8704
	ds_read_b128 v[34:37], v103 offset:8736
	s_waitcnt vmcnt(0) lgkmcnt(2)
	v_mfma_f32_32x32x16_bf16 v[2:17], v[22:25], v[70:73], v[2:17]
	s_waitcnt lgkmcnt(1)
	v_mfma_f32_32x32x16_bf16 v[18:33], v[18:21], v[90:93], 0
	s_waitcnt lgkmcnt(0)
	v_mfma_f32_32x32x16_bf16 v[18:33], v[34:37], v[94:97], v[18:33]
	ds_read_b128 v[34:37], v103 offset:8768
	ds_read_b128 v[38:41], v103 offset:8800
	s_waitcnt lgkmcnt(1)
	v_mfma_f32_32x32x16_bf16 v[18:33], v[34:37], v[82:85], v[18:33]
	s_waitcnt lgkmcnt(0)
	v_mfma_f32_32x32x16_bf16 v[18:33], v[38:41], v[86:89], v[18:33]
	ds_read_b128 v[34:37], v103 offset:8832
	ds_read_b128 v[38:41], v103 offset:8864
	s_waitcnt lgkmcnt(1)
	v_mfma_f32_32x32x16_bf16 v[18:33], v[34:37], v[74:77], v[18:33]
	s_waitcnt lgkmcnt(0)
	v_mfma_f32_32x32x16_bf16 v[18:33], v[38:41], v[78:81], v[18:33]
	ds_read_b128 v[34:37], v103 offset:8896
	ds_read_b128 v[38:41], v103 offset:8928
	s_waitcnt lgkmcnt(1)
	v_mfma_f32_32x32x16_bf16 v[18:33], v[34:37], v[66:69], v[18:33]
	ds_read_b128 v[34:37], v103 offset:17408
	ds_read_b128 v[50:53], v103 offset:17440
	s_waitcnt lgkmcnt(2)
	v_mfma_f32_32x32x16_bf16 v[18:33], v[38:41], v[70:73], v[18:33]
	s_waitcnt lgkmcnt(1)
	v_mfma_f32_32x32x16_bf16 v[34:49], v[34:37], v[90:93], 0
	s_waitcnt lgkmcnt(0)
	v_mfma_f32_32x32x16_bf16 v[34:49], v[50:53], v[94:97], v[34:49]
	ds_read_b128 v[50:53], v103 offset:17472
	ds_read_b128 v[54:57], v103 offset:17504
	s_waitcnt lgkmcnt(1)
	v_mfma_f32_32x32x16_bf16 v[34:49], v[50:53], v[82:85], v[34:49]
	s_waitcnt lgkmcnt(0)
	v_mfma_f32_32x32x16_bf16 v[34:49], v[54:57], v[86:89], v[34:49]
	ds_read_b128 v[50:53], v103 offset:17536
	ds_read_b128 v[54:57], v103 offset:17568
	s_waitcnt lgkmcnt(1)
	v_mfma_f32_32x32x16_bf16 v[34:49], v[50:53], v[74:77], v[34:49]
	s_waitcnt lgkmcnt(0)
	v_mfma_f32_32x32x16_bf16 v[34:49], v[54:57], v[78:81], v[34:49]
	ds_read_b128 v[50:53], v103 offset:17600
	ds_read_b128 v[54:57], v103 offset:17632
	s_waitcnt lgkmcnt(1)
	v_mfma_f32_32x32x16_bf16 v[34:49], v[50:53], v[66:69], v[34:49]
	ds_read_b128 v[50:53], v103 offset:26112
	ds_read_b128 v[204:207], v103 offset:26144
	s_waitcnt lgkmcnt(2)
	v_mfma_f32_32x32x16_bf16 v[34:49], v[54:57], v[70:73], v[34:49]
	s_waitcnt lgkmcnt(1)
	v_mfma_f32_32x32x16_bf16 v[50:65], v[50:53], v[90:93], 0
	s_waitcnt lgkmcnt(0)
	v_mfma_f32_32x32x16_bf16 v[50:65], v[204:207], v[94:97], v[50:65]
	ds_read_b128 v[90:93], v103 offset:26176
	ds_read_b128 v[94:97], v103 offset:26208
	s_waitcnt lgkmcnt(1)
	v_mfma_f32_32x32x16_bf16 v[50:65], v[90:93], v[82:85], v[50:65]
	s_waitcnt lgkmcnt(0)
	v_mfma_f32_32x32x16_bf16 v[50:65], v[94:97], v[86:89], v[50:65]
	ds_read_b128 v[82:85], v103 offset:26240
	ds_read_b128 v[86:89], v103 offset:26272
	s_waitcnt lgkmcnt(1)
	v_mfma_f32_32x32x16_bf16 v[50:65], v[82:85], v[74:77], v[50:65]
	s_waitcnt lgkmcnt(0)
	v_mfma_f32_32x32x16_bf16 v[50:65], v[86:89], v[78:81], v[50:65]
	ds_read_b128 v[74:77], v103 offset:26304
	ds_read_b128 v[78:81], v103 offset:26336
	s_waitcnt lgkmcnt(1)
	v_mfma_f32_32x32x16_bf16 v[50:65], v[74:77], v[66:69], v[50:65]
	s_waitcnt lgkmcnt(0)
	v_mfma_f32_32x32x16_bf16 v[50:65], v[78:81], v[70:73], v[50:65]
	s_ashr_i32 s17, s16, 31
	v_mov_b32_e32 v66, v1
	s_lshl_b64 s[18:19], s[16:17], 17
	s_add_u32 s18, s64, s18
	v_ashrrev_i32_e32 v67, 31, v66
	s_addc_u32 s19, s65, s19
	v_lshlrev_b64 v[66:67], 12, v[66:67]
	v_lshl_add_u64 v[66:67], s[18:19], 0, v[66:67]
	v_lshl_add_u64 v[66:67], v[66:67], 0, s[6:7]
	v_lshl_add_u64 v[66:67], v[66:67], 0, v[98:99]
	global_load_dwordx4 v[94:97], v[66:67], off offset:256
	global_load_dwordx4 v[90:93], v[66:67], off offset:288
	global_load_dwordx4 v[86:89], v[66:67], off offset:320
	global_load_dwordx4 v[82:85], v[66:67], off offset:352
	global_load_dwordx4 v[78:81], v[66:67], off offset:384
	global_load_dwordx4 v[74:77], v[66:67], off offset:416
	global_load_dwordx4 v[70:73], v[66:67], off offset:448
	s_nop 0
	global_load_dwordx4 v[66:69], v[66:67], off offset:480
	v_and_or_b32 v2, v2, s26, v101
	v_and_or_b32 v3, v3, s26, v104
	v_and_or_b32 v4, v4, s26, v105
	v_and_or_b32 v5, v5, s26, v106
	v_and_or_b32 v6, v6, s26, v107
	v_and_or_b32 v7, v7, s26, v108
	v_and_or_b32 v8, v8, s26, v109
	v_and_or_b32 v9, v9, s26, v110
	v_and_or_b32 v10, v10, s26, v111
	v_and_or_b32 v11, v11, s26, v112
	v_and_or_b32 v12, v12, s26, v113
	v_and_or_b32 v13, v13, s26, v114
	v_and_or_b32 v14, v14, s26, v115
	v_and_or_b32 v15, v15, s26, v116
	v_and_or_b32 v16, v16, s26, v117
	v_and_or_b32 v17, v17, s26, v118
	v_and_or_b32 v18, v18, s26, v119
	v_and_or_b32 v19, v19, s26, v120
	v_and_or_b32 v20, v20, s26, v121
	v_and_or_b32 v21, v21, s26, v122
; __device__ __forceinline__ void phase_topk_fast(LAS unsigned char* lds, const bf16* Q, const bf16* keysb  , int* EID, float* GATE, bool prestaged  ) {
;     ...
;                     { const float sv = acc[blk][r]; v[blk * 16 + r] = __uint_as_float((__float_as_uint(sv) & ~127u) | (unsigned)(32 * blk + (r & 3) + 8 * (r >> 2)) | (unsigned)(hh << 2)); }
;                 __builtin_amdgcn_sched_barrier(0);
;                 bsort16_desc<0, 64>(v); bsort16_desc<16, 64>(v); bsort16_desc<32, 64>(v); bsort16_desc<48, 64>(v);
	v_and_or_b32 v22, v22, s26, v123
	v_and_or_b32 v23, v23, s26, v124
	v_and_or_b32 v24, v24, s26, v125
	v_and_or_b32 v25, v25, s26, v126
	v_and_or_b32 v26, v26, s26, v127
	v_and_or_b32 v27, v27, s26, v128
	v_and_or_b32 v28, v28, s26, v129
	v_and_or_b32 v29, v29, s26, v130
	v_and_or_b32 v30, v30, s26, v131
	v_and_or_b32 v31, v31, s26, v132
	v_and_or_b32 v32, v32, s26, v133
	v_and_or_b32 v33, v33, s26, v134
	v_and_or_b32 v34, v34, s26, v135
	v_and_or_b32 v35, v35, s26, v136
	v_and_or_b32 v36, v36, s26, v137
	v_and_or_b32 v37, v37, s26, v138
	v_and_or_b32 v38, v38, s26, v139
	v_and_or_b32 v39, v39, s26, v140
	v_and_or_b32 v40, v40, s26, v141
	v_and_or_b32 v41, v41, s26, v142
	v_and_or_b32 v42, v42, s26, v143
	v_and_or_b32 v43, v43, s26, v144
	v_and_or_b32 v44, v44, s26, v145
	v_and_or_b32 v45, v45, s26, v146
	v_and_or_b32 v46, v46, s26, v147
	v_and_or_b32 v47, v47, s26, v148
	v_and_or_b32 v48, v48, s26, v149
	v_and_or_b32 v49, v49, s26, v150
	v_and_or_b32 v50, v50, s26, v151
	v_and_or_b32 v51, v51, s26, v152
	v_and_or_b32 v52, v52, s26, v153
	v_and_or_b32 v53, v53, s26, v154
	v_and_or_b32 v54, v54, s26, v155
	v_and_or_b32 v55, v55, s26, v156
	v_and_or_b32 v56, v56, s26, v157
	v_and_or_b32 v57, v57, s26, v158
	v_and_or_b32 v58, v58, s26, v159
	v_and_or_b32 v59, v59, s26, v160
	v_and_or_b32 v60, v60, s26, v161
	v_and_or_b32 v61, v61, s26, v162
	v_and_or_b32 v62, v62, s26, v163
	v_and_or_b32 v63, v63, s26, v164
	v_and_or_b32 v64, v64, s26, v165
	v_and_or_b32 v65, v65, s26, v166
	v_max_f32_e32 v203, v2, v15
	v_min_f32_e32 v2, v2, v15
	v_max_f32_e32 v15, v3, v14
	v_min_f32_e32 v3, v3, v14
	v_max_f32_e32 v14, v17, v17
	v_max_f32_e32 v211, v18, v31
	v_min_f32_e32 v18, v18, v31
	v_max_f32_e32 v31, v19, v30
	v_min_f32_e32 v19, v19, v30
	v_max_f32_e32 v30, v33, v33
	v_max_f32_e32 v219, v34, v47
	v_min_f32_e32 v34, v34, v47
	v_max_f32_e32 v47, v35, v46
	v_min_f32_e32 v35, v35, v46
	v_max_f32_e32 v46, v49, v49
	v_max_f32_e32 v227, v50, v63
	v_min_f32_e32 v50, v50, v63
	v_max_f32_e32 v63, v51, v62
	v_min_f32_e32 v51, v51, v62
	v_max_f32_e32 v62, v65, v65
	v_max_f32_e32 v17, v4, v14
	v_min_f32_e32 v4, v4, v14
	v_max_f32_e32 v14, v16, v16
	v_max_f32_e32 v33, v20, v30
	v_min_f32_e32 v20, v20, v30
	v_max_f32_e32 v30, v32, v32
	v_max_f32_e32 v49, v36, v46
	v_min_f32_e32 v36, v36, v46
	v_max_f32_e32 v46, v48, v48
	v_max_f32_e32 v65, v52, v62
	v_min_f32_e32 v52, v52, v62
	v_max_f32_e32 v62, v64, v64
	v_max_f32_e32 v16, v5, v14
	v_min_f32_e32 v5, v5, v14
	v_max_f32_e32 v14, v6, v10
	v_min_f32_e32 v6, v6, v10
	v_max_f32_e32 v10, v7, v8
	v_min_f32_e32 v7, v7, v8
	v_max_f32_e32 v8, v13, v13
	v_max_f32_e32 v32, v21, v30
	v_min_f32_e32 v21, v21, v30
	v_max_f32_e32 v30, v22, v26
	v_min_f32_e32 v22, v22, v26
	v_max_f32_e32 v26, v23, v24
	v_min_f32_e32 v23, v23, v24
	v_max_f32_e32 v24, v29, v29
	v_max_f32_e32 v48, v37, v46
	v_min_f32_e32 v37, v37, v46
	v_max_f32_e32 v46, v38, v42
	v_min_f32_e32 v38, v38, v42
	v_max_f32_e32 v42, v39, v40
	v_min_f32_e32 v39, v39, v40
	v_max_f32_e32 v40, v45, v45
	v_max_f32_e32 v64, v53, v62
	v_min_f32_e32 v53, v53, v62
	v_max_f32_e32 v62, v54, v58
	v_min_f32_e32 v54, v54, v58
	v_max_f32_e32 v58, v55, v56
	v_min_f32_e32 v55, v55, v56
	v_max_f32_e32 v56, v61, v61
	v_max_f32_e32 v13, v9, v8
	v_min_f32_e32 v8, v9, v8
	v_max_f32_e32 v9, v12, v12
	v_max_f32_e32 v29, v25, v24
	v_min_f32_e32 v24, v25, v24
	v_max_f32_e32 v25, v28, v28
	v_max_f32_e32 v45, v41, v40
	v_min_f32_e32 v40, v41, v40
	v_max_f32_e32 v41, v44, v44
	v_max_f32_e32 v61, v57, v56
	v_min_f32_e32 v56, v57, v56
	v_max_f32_e32 v57, v60, v60
	v_max_f32_e32 v12, v11, v9
	v_min_f32_e32 v9, v11, v9
	v_max_f32_e32 v28, v27, v25
	v_min_f32_e32 v25, v27, v25
	v_max_f32_e32 v44, v43, v41
	v_min_f32_e32 v41, v43, v41
	v_max_f32_e32 v60, v59, v57
	v_min_f32_e32 v57, v59, v57
	v_max_f32_e32 v11, v203, v10
	v_min_f32_e32 v10, v203, v10
	v_max_f32_e32 v203, v15, v13
	v_min_f32_e32 v13, v15, v13
	v_max_f32_e32 v15, v17, v12
	v_min_f32_e32 v12, v17, v12
	v_max_f32_e32 v17, v16, v14
	v_min_f32_e32 v14, v16, v14
	v_max_f32_e32 v16, v7, v2
	v_min_f32_e32 v2, v7, v2
	v_max_f32_e32 v7, v6, v5
	v_min_f32_e32 v5, v6, v5
	v_max_f32_e32 v6, v9, v4
	v_min_f32_e32 v4, v9, v4
	v_max_f32_e32 v9, v8, v3
	v_min_f32_e32 v3, v8, v3
	v_max_f32_e32 v27, v211, v26
	v_min_f32_e32 v26, v211, v26
	v_max_f32_e32 v211, v31, v29
	v_min_f32_e32 v29, v31, v29
	v_max_f32_e32 v31, v33, v28
	v_min_f32_e32 v28, v33, v28
	v_max_f32_e32 v33, v32, v30
	v_min_f32_e32 v30, v32, v30
	v_max_f32_e32 v32, v23, v18
	v_min_f32_e32 v18, v23, v18
	v_max_f32_e32 v23, v22, v21
	v_min_f32_e32 v21, v22, v21
	v_max_f32_e32 v22, v25, v20
	v_min_f32_e32 v20, v25, v20
	v_max_f32_e32 v25, v24, v19
	v_min_f32_e32 v19, v24, v19
	v_max_f32_e32 v43, v219, v42
	v_min_f32_e32 v42, v219, v42
	v_max_f32_e32 v219, v47, v45
	v_min_f32_e32 v45, v47, v45
	v_max_f32_e32 v47, v49, v44
	v_min_f32_e32 v44, v49, v44
	v_max_f32_e32 v49, v48, v46
	v_min_f32_e32 v46, v48, v46
	v_max_f32_e32 v48, v39, v34
	v_min_f32_e32 v34, v39, v34
	v_max_f32_e32 v39, v38, v37
	v_min_f32_e32 v37, v38, v37
	v_max_f32_e32 v38, v41, v36
	v_min_f32_e32 v36, v41, v36
	v_max_f32_e32 v41, v40, v35
	v_min_f32_e32 v35, v40, v35
	v_max_f32_e32 v59, v227, v58
	v_min_f32_e32 v58, v227, v58
	v_max_f32_e32 v227, v63, v61
	v_min_f32_e32 v61, v63, v61
	v_max_f32_e32 v63, v65, v60
	v_min_f32_e32 v60, v65, v60
	v_max_f32_e32 v65, v64, v62
	v_min_f32_e32 v62, v64, v62
	v_max_f32_e32 v64, v55, v50
	v_min_f32_e32 v50, v55, v50
	v_max_f32_e32 v55, v54, v53
	v_min_f32_e32 v53, v54, v53
	v_max_f32_e32 v54, v57, v52
	v_min_f32_e32 v52, v57, v52
	v_max_f32_e32 v57, v56, v51
	v_min_f32_e32 v51, v56, v51
; __device__ __forceinline__ void phase_topk_fast(LAS unsigned char* lds, const bf16* Q, const bf16* keysb  , int* EID, float* GATE, bool prestaged  ) {
;     ...
;                 bsort16_desc<0, 64>(v); bsort16_desc<16, 64>(v); bsort16_desc<32, 64>(v); bsort16_desc<48, 64>(v);
	v_max_f32_e32 v8, v11, v203
	v_min_f32_e32 v11, v11, v203
	v_max_f32_e32 v203, v15, v17
	v_min_f32_e32 v15, v15, v17
	v_max_f32_e32 v17, v14, v10
	v_min_f32_e32 v10, v14, v10
	v_max_f32_e32 v14, v16, v7
	v_min_f32_e32 v7, v16, v7
	v_max_f32_e32 v16, v13, v12
	v_min_f32_e32 v12, v13, v12
	v_max_f32_e32 v13, v6, v9
	v_min_f32_e32 v6, v6, v9
	v_max_f32_e32 v9, v3, v2
	v_min_f32_e32 v2, v3, v2
	v_max_f32_e32 v3, v5, v4
	v_min_f32_e32 v4, v5, v4
	v_max_f32_e32 v24, v27, v211
	v_min_f32_e32 v27, v27, v211
	v_max_f32_e32 v211, v31, v33
	v_min_f32_e32 v31, v31, v33
	v_max_f32_e32 v33, v30, v26
	v_min_f32_e32 v26, v30, v26
	v_max_f32_e32 v30, v32, v23
	v_min_f32_e32 v23, v32, v23
	v_max_f32_e32 v32, v29, v28
	v_min_f32_e32 v28, v29, v28
	v_max_f32_e32 v29, v22, v25
	v_min_f32_e32 v22, v22, v25
	v_max_f32_e32 v25, v19, v18
	v_min_f32_e32 v18, v19, v18
	v_max_f32_e32 v19, v21, v20
	v_min_f32_e32 v20, v21, v20
	v_max_f32_e32 v40, v43, v219
	v_min_f32_e32 v43, v43, v219
	v_max_f32_e32 v219, v47, v49
	v_min_f32_e32 v47, v47, v49
	v_max_f32_e32 v49, v46, v42
	v_min_f32_e32 v42, v46, v42
	v_max_f32_e32 v46, v48, v39
	v_min_f32_e32 v39, v48, v39
	v_max_f32_e32 v48, v45, v44
	v_min_f32_e32 v44, v45, v44
	v_max_f32_e32 v45, v38, v41
	v_min_f32_e32 v38, v38, v41
	v_max_f32_e32 v41, v35, v34
	v_min_f32_e32 v34, v35, v34
	v_max_f32_e32 v35, v37, v36
	v_min_f32_e32 v36, v37, v36
	v_max_f32_e32 v56, v59, v227
	v_min_f32_e32 v59, v59, v227
	v_max_f32_e32 v227, v63, v65
	v_min_f32_e32 v63, v63, v65
	v_max_f32_e32 v65, v62, v58
	v_min_f32_e32 v58, v62, v58
	v_max_f32_e32 v62, v64, v55
	v_min_f32_e32 v55, v64, v55
	v_max_f32_e32 v64, v61, v60
	v_min_f32_e32 v60, v61, v60
	v_max_f32_e32 v61, v54, v57
	v_min_f32_e32 v54, v54, v57
	v_max_f32_e32 v57, v51, v50
	v_min_f32_e32 v50, v51, v50
	v_max_f32_e32 v51, v53, v52
	v_min_f32_e32 v52, v53, v52
	v_min_f32_e32 v5, v8, v203
	v_max_f32_e32 v204, v11, v15
	v_min_f32_e32 v11, v11, v15
	v_max_f32_e32 v15, v17, v13
	v_min_f32_e32 v13, v17, v13
	v_max_f32_e32 v17, v10, v6
	v_min_f32_e32 v6, v10, v6
	v_max_f32_e32 v10, v14, v16
	v_min_f32_e32 v14, v14, v16
	v_max_f32_e32 v16, v7, v12
	v_min_f32_e32 v7, v7, v12
	v_max_f32_e32 v12, v9, v3
	v_min_f32_e32 v3, v9, v3
	v_max_f32_e32 v9, v2, v4
	v_min_f32_e32 v21, v24, v211
	v_max_f32_e32 v212, v27, v31
	v_min_f32_e32 v27, v27, v31
	v_max_f32_e32 v31, v33, v29
	v_min_f32_e32 v29, v33, v29
	v_max_f32_e32 v33, v26, v22
	v_min_f32_e32 v22, v26, v22
	v_max_f32_e32 v26, v30, v32
	v_min_f32_e32 v30, v30, v32
	v_max_f32_e32 v32, v23, v28
	v_min_f32_e32 v23, v23, v28
	v_max_f32_e32 v28, v25, v19
	v_min_f32_e32 v19, v25, v19
	v_max_f32_e32 v25, v18, v20
	v_min_f32_e32 v37, v40, v219
	v_max_f32_e32 v220, v43, v47
	v_min_f32_e32 v43, v43, v47
	v_max_f32_e32 v47, v49, v45
	v_min_f32_e32 v45, v49, v45
	v_max_f32_e32 v49, v42, v38
	v_min_f32_e32 v38, v42, v38
	v_max_f32_e32 v42, v46, v48
	v_min_f32_e32 v46, v46, v48
	v_max_f32_e32 v48, v39, v44
	v_min_f32_e32 v39, v39, v44
	v_max_f32_e32 v44, v41, v35
	v_min_f32_e32 v35, v41, v35
	v_max_f32_e32 v41, v34, v36
	v_min_f32_e32 v53, v56, v227
	v_max_f32_e32 v228, v59, v63
	v_min_f32_e32 v59, v59, v63
	v_max_f32_e32 v63, v65, v61
	v_min_f32_e32 v61, v65, v61
	v_max_f32_e32 v65, v58, v54
	v_min_f32_e32 v54, v58, v54
	v_max_f32_e32 v58, v62, v64
	v_min_f32_e32 v62, v62, v64
	v_max_f32_e32 v64, v55, v60
	v_min_f32_e32 v55, v55, v60
	v_max_f32_e32 v60, v57, v51
	v_min_f32_e32 v51, v57, v51
	v_max_f32_e32 v57, v50, v52
	v_min_f32_e32 v2, v2, v4
	v_max_f32_e32 v4, v204, v5
	v_min_f32_e32 v5, v204, v5
	v_max_f32_e32 v204, v11, v12
	v_min_f32_e32 v11, v11, v12
	v_max_f32_e32 v12, v15, v10
	v_min_f32_e32 v10, v15, v10
	v_max_f32_e32 v15, v17, v14
	v_min_f32_e32 v14, v17, v14
	v_max_f32_e32 v17, v16, v13
	v_min_f32_e32 v13, v16, v13
	v_max_f32_e32 v16, v7, v6
	v_min_f32_e32 v6, v7, v6
	v_max_f32_e32 v7, v9, v3
	v_min_f32_e32 v18, v18, v20
	v_max_f32_e32 v20, v212, v21
	v_min_f32_e32 v21, v212, v21
	v_max_f32_e32 v212, v27, v28
	v_min_f32_e32 v27, v27, v28
	v_max_f32_e32 v28, v31, v26
	v_min_f32_e32 v26, v31, v26
	v_max_f32_e32 v31, v33, v30
	v_min_f32_e32 v30, v33, v30
	v_max_f32_e32 v33, v32, v29
	v_min_f32_e32 v29, v32, v29
	v_max_f32_e32 v32, v23, v22
	v_min_f32_e32 v22, v23, v22
	v_max_f32_e32 v23, v25, v19
	v_min_f32_e32 v34, v34, v36
	v_max_f32_e32 v36, v220, v37
	v_min_f32_e32 v37, v220, v37
	v_max_f32_e32 v220, v43, v44
	v_min_f32_e32 v43, v43, v44
	v_max_f32_e32 v44, v47, v42
	v_min_f32_e32 v42, v47, v42
	v_max_f32_e32 v47, v49, v46
	v_min_f32_e32 v46, v49, v46
	v_max_f32_e32 v49, v48, v45
	v_min_f32_e32 v45, v48, v45
	v_max_f32_e32 v48, v39, v38
	v_min_f32_e32 v38, v39, v38
	v_max_f32_e32 v39, v41, v35
	v_min_f32_e32 v50, v50, v52
	v_max_f32_e32 v52, v228, v53
	v_min_f32_e32 v53, v228, v53
	v_max_f32_e32 v228, v59, v60
	v_min_f32_e32 v59, v59, v60
	v_max_f32_e32 v60, v63, v58
	v_min_f32_e32 v58, v63, v58
	v_max_f32_e32 v63, v65, v62
	v_min_f32_e32 v62, v65, v62
	v_max_f32_e32 v65, v64, v61
	v_min_f32_e32 v61, v64, v61
	v_max_f32_e32 v64, v55, v54
	v_min_f32_e32 v54, v55, v54
	v_max_f32_e32 v55, v57, v51
	v_min_f32_e32 v3, v9, v3
	v_max_f32_e32 v205, v5, v10
	v_min_f32_e32 v5, v5, v10
	v_max_f32_e32 v10, v15, v17
	v_min_f32_e32 v15, v15, v17
	v_max_f32_e32 v17, v14, v13
	v_min_f32_e32 v13, v14, v13
	v_max_f32_e32 v14, v16, v7
	v_min_f32_e32 v19, v25, v19
	v_max_f32_e32 v213, v21, v26
	v_min_f32_e32 v21, v21, v26
	v_max_f32_e32 v26, v31, v33
	v_min_f32_e32 v31, v31, v33
	v_max_f32_e32 v33, v30, v29
	v_min_f32_e32 v29, v30, v29
	v_max_f32_e32 v30, v32, v23
	v_min_f32_e32 v35, v41, v35
	v_max_f32_e32 v221, v37, v42
	v_min_f32_e32 v37, v37, v42
; __device__ __forceinline__ void phase_topk_fast(LAS unsigned char* lds, const bf16* Q, const bf16* keysb  , int* EID, float* GATE, bool prestaged  ) {
;     ...
;                 bsort16_desc<0, 64>(v); bsort16_desc<16, 64>(v); bsort16_desc<32, 64>(v); bsort16_desc<48, 64>(v);
;                 merge_top16<0, 16, 64>(v); merge_top16<32, 48, 64>(v); merge_top16<0, 32, 64>(v);
	v_max_f32_e32 v42, v47, v49
	v_min_f32_e32 v47, v47, v49
	v_max_f32_e32 v49, v46, v45
	v_min_f32_e32 v45, v46, v45
	v_max_f32_e32 v46, v48, v39
	v_min_f32_e32 v51, v57, v51
	v_max_f32_e32 v229, v53, v58
	v_min_f32_e32 v53, v53, v58
	v_max_f32_e32 v58, v63, v65
	v_min_f32_e32 v63, v63, v65
	v_max_f32_e32 v65, v62, v61
	v_min_f32_e32 v61, v62, v61
	v_max_f32_e32 v62, v64, v55
	v_min_f32_e32 v7, v16, v7
	v_max_f32_e32 v16, v6, v3
	v_max_f32_e32 v206, v204, v5
	v_min_f32_e32 v5, v204, v5
	v_max_f32_e32 v204, v14, v11
	v_min_f32_e32 v11, v14, v11
	v_min_f32_e32 v23, v32, v23
	v_max_f32_e32 v32, v22, v19
	v_max_f32_e32 v214, v212, v21
	v_min_f32_e32 v21, v212, v21
	v_max_f32_e32 v212, v30, v27
	v_min_f32_e32 v27, v30, v27
	v_min_f32_e32 v39, v48, v39
	v_max_f32_e32 v48, v38, v35
	v_max_f32_e32 v222, v220, v37
	v_min_f32_e32 v37, v220, v37
	v_max_f32_e32 v220, v46, v43
	v_min_f32_e32 v43, v46, v43
	v_min_f32_e32 v55, v64, v55
	v_max_f32_e32 v64, v54, v51
	v_max_f32_e32 v230, v228, v53
	v_min_f32_e32 v53, v228, v53
	v_max_f32_e32 v228, v62, v59
	v_min_f32_e32 v59, v62, v59
	v_min_f32_e32 v9, v4, v12
	v_max_f32_e32 v14, v16, v7
	v_min_f32_e32 v7, v16, v7
	v_max_f32_e32 v16, v206, v10
	v_min_f32_e32 v10, v206, v10
	v_max_f32_e32 v206, v5, v15
	v_min_f32_e32 v5, v5, v15
	v_max_f32_e32 v15, v17, v204
	v_min_f32_e32 v17, v17, v204
	v_max_f32_e32 v204, v13, v11
	v_min_f32_e32 v25, v20, v28
	v_max_f32_e32 v30, v32, v23
	v_min_f32_e32 v23, v32, v23
	v_max_f32_e32 v32, v214, v26
	v_min_f32_e32 v26, v214, v26
	v_max_f32_e32 v214, v21, v31
	v_min_f32_e32 v21, v21, v31
	v_max_f32_e32 v31, v33, v212
	v_min_f32_e32 v33, v33, v212
	v_max_f32_e32 v212, v29, v27
	v_min_f32_e32 v41, v36, v44
	v_max_f32_e32 v46, v48, v39
	v_min_f32_e32 v39, v48, v39
	v_max_f32_e32 v48, v222, v42
	v_min_f32_e32 v42, v222, v42
	v_max_f32_e32 v222, v37, v47
	v_min_f32_e32 v37, v37, v47
	v_max_f32_e32 v47, v49, v220
	v_min_f32_e32 v49, v49, v220
	v_max_f32_e32 v220, v45, v43
	v_min_f32_e32 v57, v52, v60
	v_max_f32_e32 v62, v64, v55
	v_min_f32_e32 v55, v64, v55
	v_max_f32_e32 v64, v230, v58
	v_min_f32_e32 v58, v230, v58
	v_max_f32_e32 v230, v53, v63
	v_min_f32_e32 v53, v53, v63
	v_max_f32_e32 v63, v65, v228
	v_min_f32_e32 v65, v65, v228
	v_max_f32_e32 v228, v61, v59
	v_min_f32_e32 v3, v6, v3
	v_min_f32_e32 v6, v205, v9
	v_min_f32_e32 v11, v13, v11
	v_min_f32_e32 v207, v10, v206
	v_max_f32_e32 v208, v15, v5
	v_min_f32_e32 v5, v15, v5
	v_max_f32_e32 v15, v17, v204
	v_min_f32_e32 v19, v22, v19
	v_min_f32_e32 v22, v213, v25
	v_min_f32_e32 v27, v29, v27
	v_min_f32_e32 v215, v26, v214
	v_max_f32_e32 v216, v31, v21
	v_min_f32_e32 v21, v31, v21
	v_max_f32_e32 v31, v33, v212
	v_min_f32_e32 v35, v38, v35
	v_min_f32_e32 v38, v221, v41
	v_min_f32_e32 v43, v45, v43
	v_min_f32_e32 v223, v42, v222
	v_max_f32_e32 v224, v47, v37
	v_min_f32_e32 v37, v47, v37
	v_max_f32_e32 v47, v49, v220
	v_min_f32_e32 v51, v54, v51
	v_min_f32_e32 v54, v229, v57
	v_min_f32_e32 v59, v61, v59
	v_min_f32_e32 v231, v58, v230
	v_max_f32_e32 v232, v63, v53
	v_min_f32_e32 v53, v63, v53
	v_max_f32_e32 v63, v65, v228
	v_min_f32_e32 v13, v16, v6
	v_min_f32_e32 v17, v17, v204
	v_min_f32_e32 v204, v14, v11
	v_min_f32_e32 v209, v207, v208
	v_min_f32_e32 v210, v5, v15
	v_min_f32_e32 v29, v32, v22
	v_min_f32_e32 v33, v33, v212
	v_min_f32_e32 v212, v30, v27
	v_min_f32_e32 v217, v215, v216
	v_min_f32_e32 v218, v21, v31
	v_min_f32_e32 v45, v48, v38
	v_min_f32_e32 v49, v49, v220
	v_min_f32_e32 v220, v46, v43
	v_min_f32_e32 v225, v223, v224
	v_min_f32_e32 v226, v37, v47
	v_min_f32_e32 v61, v64, v54
	v_min_f32_e32 v65, v65, v228
	v_min_f32_e32 v228, v62, v59
	v_min_f32_e32 v233, v231, v232
	v_min_f32_e32 v234, v53, v63
	v_max3_f32 v8, v8, v203, v18
	v_max3_f32 v4, v4, v12, v19
	v_max3_f32 v9, v205, v9, v23
	v_max3_f32 v6, v16, v6, v212
	v_max3_f32 v12, v13, v30, v27
	v_max3_f32 v10, v10, v206, v33
	v_max3_f32 v13, v207, v208, v218
	v_max3_f32 v16, v209, v21, v31
	v_max3_f32 v5, v5, v15, v217
	v_max3_f32 v15, v210, v215, v216
	v_max3_f32 v17, v17, v26, v214
	v_max3_f32 v11, v14, v11, v29
	v_max3_f32 v14, v204, v32, v22
	v_max3_f32 v7, v7, v213, v25
	v_max3_f32 v3, v3, v20, v28
	v_max3_f32 v2, v2, v24, v211
	v_max3_f32 v26, v40, v219, v50
	v_max3_f32 v27, v36, v44, v51
	v_max3_f32 v28, v221, v41, v55
	v_max3_f32 v29, v48, v38, v228
	v_max3_f32 v30, v45, v62, v59
	v_max3_f32 v31, v42, v222, v65
	v_max3_f32 v32, v223, v224, v234
	v_max3_f32 v33, v225, v53, v63
	v_max3_f32 v36, v37, v47, v233
	v_max3_f32 v37, v226, v231, v232
	v_max3_f32 v38, v49, v58, v230
	v_max3_f32 v40, v46, v43, v61
	v_max3_f32 v41, v220, v64, v54
	v_max3_f32 v39, v39, v229, v57
	v_max3_f32 v35, v35, v52, v60
	v_max3_f32 v34, v34, v56, v227
	v_max_f32_e32 v18, v8, v5
	v_min_f32_e32 v5, v8, v5
	v_max_f32_e32 v8, v4, v15
	v_min_f32_e32 v4, v4, v15
	v_max_f32_e32 v15, v9, v17
	v_min_f32_e32 v9, v9, v17
	v_max_f32_e32 v17, v6, v11
	v_min_f32_e32 v6, v6, v11
	v_max_f32_e32 v11, v12, v14
	v_min_f32_e32 v12, v12, v14
	v_max_f32_e32 v14, v10, v7
	v_min_f32_e32 v7, v10, v7
	v_max_f32_e32 v10, v13, v3
	v_min_f32_e32 v3, v13, v3
	v_max_f32_e32 v13, v16, v2
	v_min_f32_e32 v2, v16, v2
	v_max_f32_e32 v42, v26, v36
	v_min_f32_e32 v26, v26, v36
	v_max_f32_e32 v36, v27, v37
	v_min_f32_e32 v27, v27, v37
	v_max_f32_e32 v37, v28, v38
	v_min_f32_e32 v28, v28, v38
	v_max_f32_e32 v38, v29, v40
	v_min_f32_e32 v29, v29, v40
	v_max_f32_e32 v40, v30, v41
	v_min_f32_e32 v30, v30, v41
	v_max_f32_e32 v41, v31, v39
	v_min_f32_e32 v31, v31, v39
	v_max_f32_e32 v39, v32, v35
	v_min_f32_e32 v32, v32, v35
	v_max_f32_e32 v35, v33, v34
	v_min_f32_e32 v33, v33, v34
	v_max_f32_e32 v16, v18, v11
; __device__ __forceinline__ void phase_topk_fast(LAS unsigned char* lds, const bf16* Q, const bf16* keysb  , int* EID, float* GATE, bool prestaged  ) {
;     ...
;                 merge_top16<0, 16, 64>(v); merge_top16<32, 48, 64>(v); merge_top16<0, 32, 64>(v);
;                 float o[16];
; #pragma unroll
;                 for (int i = 0; i < 16; ++i) o[i] = __shfl_xor(v[i], 32);
; #pragma unroll
;                 for (int i = 0; i < 16; ++i) v[i] = fmaxf(v[i], o[15 - i]);
;                 bmerge16_desc<0, 64>(v);
	v_min_f32_e32 v11, v18, v11
	v_max_f32_e32 v18, v8, v14
	v_min_f32_e32 v8, v8, v14
	v_max_f32_e32 v14, v15, v10
	v_min_f32_e32 v10, v15, v10
	v_max_f32_e32 v15, v17, v13
	v_min_f32_e32 v13, v17, v13
	v_max_f32_e32 v17, v5, v12
	v_min_f32_e32 v5, v5, v12
	v_max_f32_e32 v12, v4, v7
	v_min_f32_e32 v4, v4, v7
	v_max_f32_e32 v7, v9, v3
	v_min_f32_e32 v3, v9, v3
	v_max_f32_e32 v9, v6, v2
	v_min_f32_e32 v2, v6, v2
	v_max_f32_e32 v34, v42, v40
	v_min_f32_e32 v40, v42, v40
	v_max_f32_e32 v42, v36, v41
	v_min_f32_e32 v36, v36, v41
	v_max_f32_e32 v41, v37, v39
	v_min_f32_e32 v37, v37, v39
	v_max_f32_e32 v39, v38, v35
	v_min_f32_e32 v35, v38, v35
	v_max_f32_e32 v38, v26, v30
	v_min_f32_e32 v26, v26, v30
	v_max_f32_e32 v30, v27, v31
	v_min_f32_e32 v27, v27, v31
	v_max_f32_e32 v31, v28, v32
	v_min_f32_e32 v28, v28, v32
	v_max_f32_e32 v32, v29, v33
	v_min_f32_e32 v29, v29, v33
	v_max_f32_e32 v6, v16, v14
	v_min_f32_e32 v14, v16, v14
	v_max_f32_e32 v16, v18, v15
	v_min_f32_e32 v15, v18, v15
	v_max_f32_e32 v18, v11, v10
	v_min_f32_e32 v10, v11, v10
	v_max_f32_e32 v11, v8, v13
	v_min_f32_e32 v8, v8, v13
	v_max_f32_e32 v13, v17, v7
	v_min_f32_e32 v7, v17, v7
	v_max_f32_e32 v17, v12, v9
	v_min_f32_e32 v9, v12, v9
	v_max_f32_e32 v12, v5, v3
	v_min_f32_e32 v3, v5, v3
	v_max_f32_e32 v5, v4, v2
	v_min_f32_e32 v2, v4, v2
	v_max_f32_e32 v33, v34, v41
	v_min_f32_e32 v34, v34, v41
	v_max_f32_e32 v41, v42, v39
	v_min_f32_e32 v39, v42, v39
	v_max_f32_e32 v42, v40, v37
	v_min_f32_e32 v37, v40, v37
	v_max_f32_e32 v40, v36, v35
	v_min_f32_e32 v35, v36, v35
	v_max_f32_e32 v36, v38, v31
	v_min_f32_e32 v31, v38, v31
	v_max_f32_e32 v38, v30, v32
	v_min_f32_e32 v30, v30, v32
	v_max_f32_e32 v32, v26, v28
	v_min_f32_e32 v26, v26, v28
	v_max_f32_e32 v28, v27, v29
	v_min_f32_e32 v27, v27, v29
	v_min_f32_e32 v4, v6, v16
	v_min_f32_e32 v19, v14, v15
	v_min_f32_e32 v20, v18, v11
	v_min_f32_e32 v21, v10, v8
	v_min_f32_e32 v22, v13, v17
	v_min_f32_e32 v23, v7, v9
	v_min_f32_e32 v24, v12, v5
	v_min_f32_e32 v25, v3, v2
	v_min_f32_e32 v29, v33, v41
	v_min_f32_e32 v43, v34, v39
	v_min_f32_e32 v44, v42, v40
	v_min_f32_e32 v45, v37, v35
	v_min_f32_e32 v46, v36, v38
	v_min_f32_e32 v47, v31, v30
	v_min_f32_e32 v48, v32, v28
	v_min_f32_e32 v49, v26, v27
	v_max3_f32 v6, v6, v16, v49
	v_max3_f32 v4, v4, v26, v27
	v_max3_f32 v14, v14, v15, v48
	v_max3_f32 v15, v19, v32, v28
	v_max3_f32 v11, v18, v11, v47
	v_max3_f32 v16, v20, v31, v30
	v_max3_f32 v8, v10, v8, v46
	v_max3_f32 v10, v21, v36, v38
	v_max3_f32 v13, v13, v17, v45
	v_max3_f32 v17, v22, v37, v35
	v_max3_f32 v7, v7, v9, v44
	v_max3_f32 v9, v23, v42, v40
	v_max3_f32 v5, v12, v5, v43
	v_max3_f32 v12, v24, v34, v39
	v_max3_f32 v2, v3, v2, v29
	v_max3_f32 v3, v25, v33, v41
	v_max_f32_e32 v18, v6, v13
	v_min_f32_e32 v6, v6, v13
	v_max_f32_e32 v13, v4, v17
	v_min_f32_e32 v4, v4, v17
	v_max_f32_e32 v17, v14, v7
	v_min_f32_e32 v7, v14, v7
	v_max_f32_e32 v14, v15, v9
	v_min_f32_e32 v9, v15, v9
	v_max_f32_e32 v15, v11, v5
	v_min_f32_e32 v5, v11, v5
	v_max_f32_e32 v11, v16, v12
	v_min_f32_e32 v12, v16, v12
	v_max_f32_e32 v16, v8, v2
	v_min_f32_e32 v2, v8, v2
	v_max_f32_e32 v8, v10, v3
	v_min_f32_e32 v3, v10, v3
	v_max_f32_e32 v10, v18, v15
	v_min_f32_e32 v15, v18, v15
	v_max_f32_e32 v18, v13, v11
	v_min_f32_e32 v11, v13, v11
	v_max_f32_e32 v13, v17, v16
	v_min_f32_e32 v16, v17, v16
	v_max_f32_e32 v17, v14, v8
	v_min_f32_e32 v8, v14, v8
	v_max_f32_e32 v14, v6, v5
	v_min_f32_e32 v5, v6, v5
	v_max_f32_e32 v6, v4, v12
	v_min_f32_e32 v4, v4, v12
	v_max_f32_e32 v12, v7, v2
	v_min_f32_e32 v2, v7, v2
	v_max_f32_e32 v7, v9, v3
	v_min_f32_e32 v3, v9, v3
	v_max_f32_e32 v9, v10, v13
	v_min_f32_e32 v10, v10, v13
	v_max_f32_e32 v13, v18, v17
	v_min_f32_e32 v17, v18, v17
	v_max_f32_e32 v18, v15, v16
	v_min_f32_e32 v15, v15, v16
	v_max_f32_e32 v16, v11, v8
	v_min_f32_e32 v8, v11, v8
	v_max_f32_e32 v11, v14, v12
	v_min_f32_e32 v12, v14, v12
	v_max_f32_e32 v14, v6, v7
	v_min_f32_e32 v6, v6, v7
	v_max_f32_e32 v7, v5, v2
	v_min_f32_e32 v2, v5, v2
	v_max_f32_e32 v5, v4, v3
	v_min_f32_e32 v3, v4, v3
	v_and_b32_e32 v19, 64, v200
	v_max_f32_e32 v4, v9, v13
	v_min_f32_e32 v9, v9, v13
	v_max_f32_e32 v13, v10, v17
	v_min_f32_e32 v10, v10, v17
	v_max_f32_e32 v17, v18, v16
	v_min_f32_e32 v16, v18, v16
	v_max_f32_e32 v18, v15, v8
	v_min_f32_e32 v8, v15, v8
	v_max_f32_e32 v15, v11, v14
	v_min_f32_e32 v11, v11, v14
	v_max_f32_e32 v14, v12, v6
	v_min_f32_e32 v6, v12, v6
	v_max_f32_e32 v12, v7, v5
	v_min_f32_e32 v5, v7, v5
	v_max_f32_e32 v7, v2, v3
	v_min_f32_e32 v2, v2, v3
	v_xor_b32_e32 v3, 32, v200
	v_add_u32_e32 v19, 64, v19
	v_cmp_lt_i32_e32 vcc, v3, v19
	s_nop 1
	v_cndmask_b32_e32 v3, v200, v3, vcc
	v_lshlrev_b32_e32 v203, 2, v3
	ds_bpermute_b32 v29, v203, v2
	ds_bpermute_b32 v31, v203, v7
	ds_bpermute_b32 v33, v203, v5
	ds_bpermute_b32 v32, v203, v12
	ds_bpermute_b32 v3, v203, v4
	ds_bpermute_b32 v19, v203, v9
	ds_bpermute_b32 v20, v203, v13
	ds_bpermute_b32 v21, v203, v10
	ds_bpermute_b32 v22, v203, v17
	ds_bpermute_b32 v23, v203, v16
	ds_bpermute_b32 v24, v203, v18
	ds_bpermute_b32 v25, v203, v8
	ds_bpermute_b32 v26, v203, v15
	ds_bpermute_b32 v27, v203, v11
	ds_bpermute_b32 v28, v203, v14
	ds_bpermute_b32 v30, v203, v6
	s_waitcnt lgkmcnt(14)
	v_max_f32_e32 v4, v4, v29
	v_max_f32_e32 v29, v31, v31
	v_max_f32_e32 v9, v9, v29
	s_waitcnt lgkmcnt(13)
	v_max_f32_e32 v29, v33, v33
	v_max_f32_e32 v13, v13, v29
	s_waitcnt lgkmcnt(12)
	v_max_f32_e32 v29, v32, v32
	v_max_f32_e32 v10, v10, v29
	s_waitcnt lgkmcnt(0)
; #define LAS __attribute__((address_space(3)))
; __device__ __forceinline__ void phase_topk_fast(LAS unsigned char* lds, const bf16* Q, const bf16* keysb  , int* EID, float* GATE, bool prestaged  ) {
;     ...
;                 for (int blk = 0; blk < 4; ++blk) {
; #pragma unroll
;                     for (int r = 0; r < 16; ++r) acc[blk][r] = 0.f;
; #pragma unroll
;                     for (int ks = 0; ks < 8; ++ks) { const bf16x8 a = *(const LAS bf16x8*)(lds + (p * 128 + 32 * blk + c) * 272 + (16 * ks + 8 * hh) * 2);
;                         acc[blk] = __builtin_amdgcn_mfma_f32_32x32x16_bf16(a, bq[ks], acc[blk], 0, 0, 0); }
;     ...
;                 for (int i = 0; i < 16; ++i) o[i] = __shfl_xor(v[i], 32);
; #pragma unroll
;                 for (int i = 0; i < 16; ++i) v[i] = fmaxf(v[i], o[15 - i]);
;                 bmerge16_desc<0, 64>(v);
; #pragma unroll
;                 for (int i = 0; i < 16; ++i) { if (p == 0) ta[i] = v[i]; else tb[i] = v[i]; }
	v_max_f32_e32 v29, v30, v30
	v_max_f32_e32 v17, v17, v29
	v_max_f32_e32 v16, v16, v28
	v_max_f32_e32 v18, v18, v27
	v_max_f32_e32 v8, v8, v26
	v_max_f32_e32 v15, v15, v25
	v_max_f32_e32 v11, v11, v24
	v_max_f32_e32 v14, v14, v23
	v_max_f32_e32 v6, v6, v22
	v_max_f32_e32 v12, v12, v21
	v_max_f32_e32 v5, v5, v20
	v_max_f32_e32 v7, v7, v19
	v_max_f32_e32 v2, v2, v3
	v_max_f32_e32 v3, v4, v15
	v_min_f32_e32 v4, v4, v15
	v_max_f32_e32 v15, v9, v11
	v_min_f32_e32 v9, v9, v11
	v_max_f32_e32 v11, v13, v14
	v_min_f32_e32 v13, v13, v14
	v_max_f32_e32 v14, v10, v6
	v_min_f32_e32 v6, v10, v6
	v_max_f32_e32 v10, v17, v12
	v_min_f32_e32 v12, v17, v12
	v_max_f32_e32 v17, v16, v5
	v_min_f32_e32 v5, v16, v5
	v_max_f32_e32 v16, v18, v7
	v_min_f32_e32 v7, v18, v7
	v_max_f32_e32 v18, v8, v2
	v_min_f32_e32 v2, v8, v2
	v_max_f32_e32 v8, v3, v10
	v_min_f32_e32 v3, v3, v10
	v_max_f32_e32 v10, v15, v17
	v_min_f32_e32 v15, v15, v17
	v_max_f32_e32 v17, v11, v16
	v_min_f32_e32 v11, v11, v16
	v_max_f32_e32 v16, v14, v18
	v_min_f32_e32 v14, v14, v18
	v_max_f32_e32 v18, v4, v12
	v_min_f32_e32 v4, v4, v12
	v_max_f32_e32 v12, v9, v5
	v_min_f32_e32 v5, v9, v5
	v_max_f32_e32 v9, v13, v7
	v_min_f32_e32 v7, v13, v7
	v_max_f32_e32 v13, v6, v2
	v_min_f32_e32 v2, v6, v2
	v_max_f32_e32 v6, v8, v17
	v_min_f32_e32 v8, v8, v17
	v_max_f32_e32 v17, v10, v16
	v_min_f32_e32 v10, v10, v16
	v_max_f32_e32 v16, v3, v11
	v_min_f32_e32 v3, v3, v11
	v_max_f32_e32 v11, v15, v14
	v_min_f32_e32 v14, v15, v14
	v_max_f32_e32 v15, v18, v9
	v_min_f32_e32 v9, v18, v9
	v_max_f32_e32 v18, v12, v13
	v_min_f32_e32 v12, v12, v13
	v_max_f32_e32 v13, v4, v7
	v_min_f32_e32 v4, v4, v7
	v_max_f32_e32 v7, v5, v2
	v_min_f32_e32 v2, v5, v2
	v_max_f32_e32 v219, v6, v17
	v_min_f32_e32 v205, v6, v17
	v_max_f32_e32 v204, v8, v10
	v_min_f32_e32 v217, v8, v10
	v_max_f32_e32 v218, v16, v11
	v_min_f32_e32 v215, v16, v11
	v_max_f32_e32 v216, v3, v14
	v_min_f32_e32 v213, v3, v14
	v_max_f32_e32 v214, v15, v18
	v_min_f32_e32 v211, v15, v18
	v_max_f32_e32 v212, v9, v12
	v_min_f32_e32 v209, v9, v12
	v_max_f32_e32 v210, v13, v7
	v_min_f32_e32 v208, v13, v7
	v_max_f32_e32 v207, v4, v2
	v_min_f32_e32 v206, v4, v2
	ds_read_b128 v[2:5], v103 offset:34816
	ds_read_b128 v[18:21], v103 offset:34848
	s_waitcnt vmcnt(7) lgkmcnt(1)
	v_mfma_f32_32x32x16_bf16 v[2:17], v[2:5], v[94:97], 0
	s_waitcnt vmcnt(6) lgkmcnt(0)
	v_mfma_f32_32x32x16_bf16 v[2:17], v[18:21], v[90:93], v[2:17]
	ds_read_b128 v[18:21], v103 offset:34880
	ds_read_b128 v[22:25], v103 offset:34912
	s_waitcnt vmcnt(5) lgkmcnt(1)
	v_mfma_f32_32x32x16_bf16 v[2:17], v[18:21], v[86:89], v[2:17]
	s_waitcnt vmcnt(4) lgkmcnt(0)
	v_mfma_f32_32x32x16_bf16 v[2:17], v[22:25], v[82:85], v[2:17]
	ds_read_b128 v[18:21], v103 offset:34944
	ds_read_b128 v[22:25], v103 offset:34976
	s_waitcnt vmcnt(3) lgkmcnt(1)
	v_mfma_f32_32x32x16_bf16 v[2:17], v[18:21], v[78:81], v[2:17]
	s_waitcnt vmcnt(2) lgkmcnt(0)
	v_mfma_f32_32x32x16_bf16 v[2:17], v[22:25], v[74:77], v[2:17]
	ds_read_b128 v[18:21], v103 offset:35008
	ds_read_b128 v[22:25], v103 offset:35040
	s_waitcnt vmcnt(1) lgkmcnt(1)
	v_mfma_f32_32x32x16_bf16 v[2:17], v[18:21], v[70:73], v[2:17]
	ds_read_b128 v[18:21], v103 offset:43520
	ds_read_b128 v[34:37], v103 offset:43552
	s_waitcnt vmcnt(0) lgkmcnt(2)
	v_mfma_f32_32x32x16_bf16 v[2:17], v[22:25], v[66:69], v[2:17]
	s_waitcnt lgkmcnt(1)
	v_mfma_f32_32x32x16_bf16 v[18:33], v[18:21], v[94:97], 0
	s_waitcnt lgkmcnt(0)
	v_mfma_f32_32x32x16_bf16 v[18:33], v[34:37], v[90:93], v[18:33]
	ds_read_b128 v[34:37], v103 offset:43584
	ds_read_b128 v[38:41], v103 offset:43616
	s_waitcnt lgkmcnt(1)
	v_mfma_f32_32x32x16_bf16 v[18:33], v[34:37], v[86:89], v[18:33]
	s_waitcnt lgkmcnt(0)
	v_mfma_f32_32x32x16_bf16 v[18:33], v[38:41], v[82:85], v[18:33]
	ds_read_b128 v[34:37], v103 offset:43648
	ds_read_b128 v[38:41], v103 offset:43680
	s_waitcnt lgkmcnt(1)
	v_mfma_f32_32x32x16_bf16 v[18:33], v[34:37], v[78:81], v[18:33]
	s_waitcnt lgkmcnt(0)
	v_mfma_f32_32x32x16_bf16 v[18:33], v[38:41], v[74:77], v[18:33]
	ds_read_b128 v[34:37], v103 offset:43712
	ds_read_b128 v[38:41], v103 offset:43744
	s_waitcnt lgkmcnt(1)
	v_mfma_f32_32x32x16_bf16 v[18:33], v[34:37], v[70:73], v[18:33]
	ds_read_b128 v[34:37], v103 offset:52224
	ds_read_b128 v[50:53], v103 offset:52256
	s_waitcnt lgkmcnt(2)
	v_mfma_f32_32x32x16_bf16 v[18:33], v[38:41], v[66:69], v[18:33]
	s_waitcnt lgkmcnt(1)
	v_mfma_f32_32x32x16_bf16 v[34:49], v[34:37], v[94:97], 0
	s_waitcnt lgkmcnt(0)
	v_mfma_f32_32x32x16_bf16 v[34:49], v[50:53], v[90:93], v[34:49]
	ds_read_b128 v[50:53], v103 offset:52288
	ds_read_b128 v[54:57], v103 offset:52320
	s_waitcnt lgkmcnt(1)
	v_mfma_f32_32x32x16_bf16 v[34:49], v[50:53], v[86:89], v[34:49]
	s_waitcnt lgkmcnt(0)
	v_mfma_f32_32x32x16_bf16 v[34:49], v[54:57], v[82:85], v[34:49]
	ds_read_b128 v[50:53], v103 offset:52352
	ds_read_b128 v[54:57], v103 offset:52384
	s_waitcnt lgkmcnt(1)
	v_mfma_f32_32x32x16_bf16 v[34:49], v[50:53], v[78:81], v[34:49]
	s_waitcnt lgkmcnt(0)
	v_mfma_f32_32x32x16_bf16 v[34:49], v[54:57], v[74:77], v[34:49]
	ds_read_b128 v[50:53], v103 offset:52416
	ds_read_b128 v[54:57], v103 offset:52448
	s_waitcnt lgkmcnt(1)
	v_mfma_f32_32x32x16_bf16 v[34:49], v[50:53], v[70:73], v[34:49]
	ds_read_b128 v[50:53], v103 offset:60928
	ds_read_b128 v[220:223], v103 offset:60960
	s_waitcnt lgkmcnt(2)
	v_mfma_f32_32x32x16_bf16 v[34:49], v[54:57], v[66:69], v[34:49]
	s_waitcnt lgkmcnt(1)
	v_mfma_f32_32x32x16_bf16 v[50:65], v[50:53], v[94:97], 0
	s_waitcnt lgkmcnt(0)
	v_mfma_f32_32x32x16_bf16 v[50:65], v[220:223], v[90:93], v[50:65]
	ds_read_b128 v[90:93], v103 offset:60992
	ds_read_b128 v[94:97], v103 offset:61024
	s_waitcnt lgkmcnt(1)
; #define GAS __attribute__((address_space(1)))
; #define LAS __attribute__((address_space(3)))
; __device__ __forceinline__ void phase_topk_fast(LAS unsigned char* lds, const bf16* Q, const bf16* keysb  , int* EID, float* GATE, bool prestaged  ) {
;     ...
;                 for (int blk = 0; blk < 4; ++blk) {
; #pragma unroll
;                     for (int r = 0; r < 16; ++r) acc[blk][r] = 0.f;
; #pragma unroll
;                     for (int ks = 0; ks < 8; ++ks) { const bf16x8 a = *(const LAS bf16x8*)(lds + (p * 128 + 32 * blk + c) * 272 + (16 * ks + 8 * hh) * 2);
;                         acc[blk] = __builtin_amdgcn_mfma_f32_32x32x16_bf16(a, bq[ks], acc[blk], 0, 0, 0); }
;                 }
;                 __builtin_amdgcn_sched_barrier(0);
;                 { const int nit = (p == 0) ? it : it + 1; const int np = (p == 0) ? 1 : 0;
;                   const size_t ntok0 = (size_t)(rank * 8 + wave + 256 * (nit < 4 ? nit : 3)) * 32;
;                   int cq = c; asm volatile("" : "+v"(cq)); const bf16* qrow = Q + (ntok0 + cq) * 2048 + h * 256 + np * 128 + 8 * hh;
; #pragma unroll
;                   for (int ks = 0; ks < 8; ++ks) bq[ks] = *(const GAS bf16x8*)(qrow + 16 * ks); }
;                 __builtin_amdgcn_sched_barrier(0);
;                 float v[64];
; #pragma unroll
;                 for (int blk = 0; blk < 4; ++blk)
; #pragma unroll
;                     for (int r = 0; r < 16; ++r)
;                     { const float sv = acc[blk][r]; v[blk * 16 + r] = __uint_as_float((__float_as_uint(sv) & ~127u) | (unsigned)(32 * blk + (r & 3) + 8 * (r >> 2)) | (unsigned)(hh << 2)); }
;                 __builtin_amdgcn_sched_barrier(0);
;                 bsort16_desc<0, 64>(v); bsort16_desc<16, 64>(v); bsort16_desc<32, 64>(v); bsort16_desc<48, 64>(v);
	v_mfma_f32_32x32x16_bf16 v[50:65], v[90:93], v[86:89], v[50:65]
	s_waitcnt lgkmcnt(0)
	v_mfma_f32_32x32x16_bf16 v[50:65], v[94:97], v[82:85], v[50:65]
	ds_read_b128 v[82:85], v103 offset:61056
	ds_read_b128 v[86:89], v103 offset:61088
	s_waitcnt lgkmcnt(1)
	v_mfma_f32_32x32x16_bf16 v[50:65], v[82:85], v[78:81], v[50:65]
	s_waitcnt lgkmcnt(0)
	v_mfma_f32_32x32x16_bf16 v[50:65], v[86:89], v[74:77], v[50:65]
	ds_read_b128 v[74:77], v103 offset:61120
	ds_read_b128 v[78:81], v103 offset:61152
	s_waitcnt lgkmcnt(1)
	v_mfma_f32_32x32x16_bf16 v[50:65], v[74:77], v[70:73], v[50:65]
	s_waitcnt lgkmcnt(0)
	v_mfma_f32_32x32x16_bf16 v[50:65], v[78:81], v[66:69], v[50:65]
	s_min_u32 s3, s2, 3
	s_lshl_b32 s3, s3, 8
	s_add_i32 s18, s3, s10
	s_ashr_i32 s19, s18, 31
	v_mov_b32_e32 v66, v1
	s_lshl_b64 s[18:19], s[18:19], 17
	s_add_u32 s18, s64, s18
	v_ashrrev_i32_e32 v67, 31, v66
	s_addc_u32 s19, s65, s19
	v_lshlrev_b64 v[66:67], 12, v[66:67]
	v_lshl_add_u64 v[66:67], s[18:19], 0, v[66:67]
	v_lshl_add_u64 v[66:67], v[66:67], 0, s[6:7]
	v_lshl_add_u64 v[70:71], v[66:67], 0, v[98:99]
	global_load_dwordx4 v[90:93], v[70:71], off
	global_load_dwordx4 v[94:97], v[70:71], off offset:32
	global_load_dwordx4 v[82:85], v[70:71], off offset:64
	global_load_dwordx4 v[86:89], v[70:71], off offset:96
	global_load_dwordx4 v[74:77], v[70:71], off offset:128
	global_load_dwordx4 v[78:81], v[70:71], off offset:160
	global_load_dwordx4 v[66:69], v[70:71], off offset:192
	s_nop 0
	global_load_dwordx4 v[70:73], v[70:71], off offset:224
	v_and_or_b32 v2, v2, s26, v101
	v_and_or_b32 v3, v3, s26, v104
	v_and_or_b32 v4, v4, s26, v105
	v_and_or_b32 v5, v5, s26, v106
	v_and_or_b32 v6, v6, s26, v107
	v_and_or_b32 v7, v7, s26, v108
	v_and_or_b32 v8, v8, s26, v109
	v_and_or_b32 v9, v9, s26, v110
	v_and_or_b32 v10, v10, s26, v111
	v_and_or_b32 v11, v11, s26, v112
	v_and_or_b32 v12, v12, s26, v113
	v_and_or_b32 v13, v13, s26, v114
	v_and_or_b32 v14, v14, s26, v115
	v_and_or_b32 v15, v15, s26, v116
	v_and_or_b32 v16, v16, s26, v117
	v_and_or_b32 v17, v17, s26, v118
	v_and_or_b32 v18, v18, s26, v119
	v_and_or_b32 v19, v19, s26, v120
	v_and_or_b32 v20, v20, s26, v121
	v_and_or_b32 v21, v21, s26, v122
	v_and_or_b32 v22, v22, s26, v123
	v_and_or_b32 v23, v23, s26, v124
	v_and_or_b32 v24, v24, s26, v125
	v_and_or_b32 v25, v25, s26, v126
	v_and_or_b32 v26, v26, s26, v127
	v_and_or_b32 v27, v27, s26, v128
	v_and_or_b32 v28, v28, s26, v129
	v_and_or_b32 v29, v29, s26, v130
	v_and_or_b32 v30, v30, s26, v131
	v_and_or_b32 v31, v31, s26, v132
	v_and_or_b32 v32, v32, s26, v133
	v_and_or_b32 v33, v33, s26, v134
	v_and_or_b32 v34, v34, s26, v135
	v_and_or_b32 v35, v35, s26, v136
	v_and_or_b32 v36, v36, s26, v137
	v_and_or_b32 v37, v37, s26, v138
	v_and_or_b32 v38, v38, s26, v139
	v_and_or_b32 v39, v39, s26, v140
	v_and_or_b32 v40, v40, s26, v141
	v_and_or_b32 v41, v41, s26, v142
	v_and_or_b32 v42, v42, s26, v143
	v_and_or_b32 v43, v43, s26, v144
	v_and_or_b32 v44, v44, s26, v145
	v_and_or_b32 v45, v45, s26, v146
	v_and_or_b32 v46, v46, s26, v147
	v_and_or_b32 v47, v47, s26, v148
	v_and_or_b32 v48, v48, s26, v149
	v_and_or_b32 v49, v49, s26, v150
	v_and_or_b32 v50, v50, s26, v151
	v_and_or_b32 v51, v51, s26, v152
	v_and_or_b32 v52, v52, s26, v153
	v_and_or_b32 v53, v53, s26, v154
	v_and_or_b32 v54, v54, s26, v155
	v_and_or_b32 v55, v55, s26, v156
	v_and_or_b32 v56, v56, s26, v157
	v_and_or_b32 v57, v57, s26, v158
	v_and_or_b32 v58, v58, s26, v159
	v_and_or_b32 v59, v59, s26, v160
	v_and_or_b32 v60, v60, s26, v161
	v_and_or_b32 v61, v61, s26, v162
	v_and_or_b32 v62, v62, s26, v163
	v_and_or_b32 v63, v63, s26, v164
	v_and_or_b32 v64, v64, s26, v165
	v_and_or_b32 v65, v65, s26, v166
	v_max_f32_e32 v220, v2, v15
	v_min_f32_e32 v2, v2, v15
	v_max_f32_e32 v15, v3, v14
	v_min_f32_e32 v3, v3, v14
	v_max_f32_e32 v14, v17, v17
	v_max_f32_e32 v228, v18, v31
	v_min_f32_e32 v18, v18, v31
	v_max_f32_e32 v31, v19, v30
	v_min_f32_e32 v19, v19, v30
	v_max_f32_e32 v30, v33, v33
	v_max_f32_e32 v236, v34, v47
	v_min_f32_e32 v34, v34, v47
	v_max_f32_e32 v47, v35, v46
	v_min_f32_e32 v35, v35, v46
	v_max_f32_e32 v46, v49, v49
	v_max_f32_e32 v244, v50, v63
	v_min_f32_e32 v50, v50, v63
	v_max_f32_e32 v63, v51, v62
	v_min_f32_e32 v51, v51, v62
	v_max_f32_e32 v62, v65, v65
	v_max_f32_e32 v17, v4, v14
	v_min_f32_e32 v4, v4, v14
	v_max_f32_e32 v14, v16, v16
	v_max_f32_e32 v33, v20, v30
	v_min_f32_e32 v20, v20, v30
	v_max_f32_e32 v30, v32, v32
	v_max_f32_e32 v49, v36, v46
	v_min_f32_e32 v36, v36, v46
	v_max_f32_e32 v46, v48, v48
	v_max_f32_e32 v65, v52, v62
	v_min_f32_e32 v52, v52, v62
	v_max_f32_e32 v62, v64, v64
	v_max_f32_e32 v16, v5, v14
	v_min_f32_e32 v5, v5, v14
	v_max_f32_e32 v14, v6, v10
	v_min_f32_e32 v6, v6, v10
	v_max_f32_e32 v10, v7, v8
	v_min_f32_e32 v7, v7, v8
	v_max_f32_e32 v8, v13, v13
	v_max_f32_e32 v32, v21, v30
	v_min_f32_e32 v21, v21, v30
	v_max_f32_e32 v30, v22, v26
	v_min_f32_e32 v22, v22, v26
	v_max_f32_e32 v26, v23, v24
	v_min_f32_e32 v23, v23, v24
	v_max_f32_e32 v24, v29, v29
	v_max_f32_e32 v48, v37, v46
	v_min_f32_e32 v37, v37, v46
	v_max_f32_e32 v46, v38, v42
	v_min_f32_e32 v38, v38, v42
	v_max_f32_e32 v42, v39, v40
	v_min_f32_e32 v39, v39, v40
	v_max_f32_e32 v40, v45, v45
	v_max_f32_e32 v64, v53, v62
	v_min_f32_e32 v53, v53, v62
	v_max_f32_e32 v62, v54, v58
	v_min_f32_e32 v54, v54, v58
	v_max_f32_e32 v58, v55, v56
	v_min_f32_e32 v55, v55, v56
	v_max_f32_e32 v56, v61, v61
	v_max_f32_e32 v13, v9, v8
	v_min_f32_e32 v8, v9, v8
	v_max_f32_e32 v9, v12, v12
	v_max_f32_e32 v29, v25, v24
	v_min_f32_e32 v24, v25, v24
	v_max_f32_e32 v25, v28, v28
	v_max_f32_e32 v45, v41, v40
	v_min_f32_e32 v40, v41, v40
; __device__ __forceinline__ void phase_topk_fast(LAS unsigned char* lds, const bf16* Q, const bf16* keysb  , int* EID, float* GATE, bool prestaged  ) {
;     ...
;                 bsort16_desc<0, 64>(v); bsort16_desc<16, 64>(v); bsort16_desc<32, 64>(v); bsort16_desc<48, 64>(v);
	v_max_f32_e32 v41, v44, v44
	v_max_f32_e32 v61, v57, v56
	v_min_f32_e32 v56, v57, v56
	v_max_f32_e32 v57, v60, v60
	v_max_f32_e32 v12, v11, v9
	v_min_f32_e32 v9, v11, v9
	v_max_f32_e32 v28, v27, v25
	v_min_f32_e32 v25, v27, v25
	v_max_f32_e32 v44, v43, v41
	v_min_f32_e32 v41, v43, v41
	v_max_f32_e32 v60, v59, v57
	v_min_f32_e32 v57, v59, v57
	v_max_f32_e32 v11, v220, v10
	v_min_f32_e32 v10, v220, v10
	v_max_f32_e32 v220, v15, v13
	v_min_f32_e32 v13, v15, v13
	v_max_f32_e32 v15, v17, v12
	v_min_f32_e32 v12, v17, v12
	v_max_f32_e32 v17, v16, v14
	v_min_f32_e32 v14, v16, v14
	v_max_f32_e32 v16, v7, v2
	v_min_f32_e32 v2, v7, v2
	v_max_f32_e32 v7, v6, v5
	v_min_f32_e32 v5, v6, v5
	v_max_f32_e32 v6, v9, v4
	v_min_f32_e32 v4, v9, v4
	v_max_f32_e32 v9, v8, v3
	v_min_f32_e32 v3, v8, v3
	v_max_f32_e32 v27, v228, v26
	v_min_f32_e32 v26, v228, v26
	v_max_f32_e32 v228, v31, v29
	v_min_f32_e32 v29, v31, v29
	v_max_f32_e32 v31, v33, v28
	v_min_f32_e32 v28, v33, v28
	v_max_f32_e32 v33, v32, v30
	v_min_f32_e32 v30, v32, v30
	v_max_f32_e32 v32, v23, v18
	v_min_f32_e32 v18, v23, v18
	v_max_f32_e32 v23, v22, v21
	v_min_f32_e32 v21, v22, v21
	v_max_f32_e32 v22, v25, v20
	v_min_f32_e32 v20, v25, v20
	v_max_f32_e32 v25, v24, v19
	v_min_f32_e32 v19, v24, v19
	v_max_f32_e32 v43, v236, v42
	v_min_f32_e32 v42, v236, v42
	v_max_f32_e32 v236, v47, v45
	v_min_f32_e32 v45, v47, v45
	v_max_f32_e32 v47, v49, v44
	v_min_f32_e32 v44, v49, v44
	v_max_f32_e32 v49, v48, v46
	v_min_f32_e32 v46, v48, v46
	v_max_f32_e32 v48, v39, v34
	v_min_f32_e32 v34, v39, v34
	v_max_f32_e32 v39, v38, v37
	v_min_f32_e32 v37, v38, v37
	v_max_f32_e32 v38, v41, v36
	v_min_f32_e32 v36, v41, v36
	v_max_f32_e32 v41, v40, v35
	v_min_f32_e32 v35, v40, v35
	v_max_f32_e32 v59, v244, v58
	v_min_f32_e32 v58, v244, v58
	v_max_f32_e32 v244, v63, v61
	v_min_f32_e32 v61, v63, v61
	v_max_f32_e32 v63, v65, v60
	v_min_f32_e32 v60, v65, v60
	v_max_f32_e32 v65, v64, v62
	v_min_f32_e32 v62, v64, v62
	v_max_f32_e32 v64, v55, v50
	v_min_f32_e32 v50, v55, v50
	v_max_f32_e32 v55, v54, v53
	v_min_f32_e32 v53, v54, v53
	v_max_f32_e32 v54, v57, v52
	v_min_f32_e32 v52, v57, v52
	v_max_f32_e32 v57, v56, v51
	v_min_f32_e32 v51, v56, v51
	v_max_f32_e32 v8, v11, v220
	v_min_f32_e32 v11, v11, v220
	v_max_f32_e32 v220, v15, v17
	v_min_f32_e32 v15, v15, v17
	v_max_f32_e32 v17, v14, v10
	v_min_f32_e32 v10, v14, v10
	v_max_f32_e32 v14, v16, v7
	v_min_f32_e32 v7, v16, v7
	v_max_f32_e32 v16, v13, v12
	v_min_f32_e32 v12, v13, v12
	v_max_f32_e32 v13, v6, v9
	v_min_f32_e32 v6, v6, v9
	v_max_f32_e32 v9, v3, v2
	v_min_f32_e32 v2, v3, v2
	v_max_f32_e32 v3, v5, v4
	v_min_f32_e32 v4, v5, v4
	v_max_f32_e32 v24, v27, v228
	v_min_f32_e32 v27, v27, v228
	v_max_f32_e32 v228, v31, v33
	v_min_f32_e32 v31, v31, v33
	v_max_f32_e32 v33, v30, v26
	v_min_f32_e32 v26, v30, v26
	v_max_f32_e32 v30, v32, v23
	v_min_f32_e32 v23, v32, v23
	v_max_f32_e32 v32, v29, v28
	v_min_f32_e32 v28, v29, v28
	v_max_f32_e32 v29, v22, v25
	v_min_f32_e32 v22, v22, v25
	v_max_f32_e32 v25, v19, v18
	v_min_f32_e32 v18, v19, v18
	v_max_f32_e32 v19, v21, v20
	v_min_f32_e32 v20, v21, v20
	v_max_f32_e32 v40, v43, v236
	v_min_f32_e32 v43, v43, v236
	v_max_f32_e32 v236, v47, v49
	v_min_f32_e32 v47, v47, v49
	v_max_f32_e32 v49, v46, v42
	v_min_f32_e32 v42, v46, v42
	v_max_f32_e32 v46, v48, v39
	v_min_f32_e32 v39, v48, v39
	v_max_f32_e32 v48, v45, v44
	v_min_f32_e32 v44, v45, v44
	v_max_f32_e32 v45, v38, v41
	v_min_f32_e32 v38, v38, v41
	v_max_f32_e32 v41, v35, v34
	v_min_f32_e32 v34, v35, v34
	v_max_f32_e32 v35, v37, v36
	v_min_f32_e32 v36, v37, v36
	v_max_f32_e32 v56, v59, v244
	v_min_f32_e32 v59, v59, v244
	v_max_f32_e32 v244, v63, v65
	v_min_f32_e32 v63, v63, v65
	v_max_f32_e32 v65, v62, v58
	v_min_f32_e32 v58, v62, v58
	v_max_f32_e32 v62, v64, v55
	v_min_f32_e32 v55, v64, v55
	v_max_f32_e32 v64, v61, v60
	v_min_f32_e32 v60, v61, v60
	v_max_f32_e32 v61, v54, v57
	v_min_f32_e32 v54, v54, v57
	v_max_f32_e32 v57, v51, v50
	v_min_f32_e32 v50, v51, v50
	v_max_f32_e32 v51, v53, v52
	v_min_f32_e32 v52, v53, v52
	v_min_f32_e32 v5, v8, v220
	v_max_f32_e32 v221, v11, v15
	v_min_f32_e32 v11, v11, v15
	v_max_f32_e32 v15, v17, v13
	v_min_f32_e32 v13, v17, v13
	v_max_f32_e32 v17, v10, v6
	v_min_f32_e32 v6, v10, v6
	v_max_f32_e32 v10, v14, v16
	v_min_f32_e32 v14, v14, v16
	v_max_f32_e32 v16, v7, v12
	v_min_f32_e32 v7, v7, v12
	v_max_f32_e32 v12, v9, v3
	v_min_f32_e32 v3, v9, v3
	v_max_f32_e32 v9, v2, v4
	v_min_f32_e32 v21, v24, v228
	v_max_f32_e32 v229, v27, v31
	v_min_f32_e32 v27, v27, v31
	v_max_f32_e32 v31, v33, v29
	v_min_f32_e32 v29, v33, v29
	v_max_f32_e32 v33, v26, v22
	v_min_f32_e32 v22, v26, v22
	v_max_f32_e32 v26, v30, v32
	v_min_f32_e32 v30, v30, v32
	v_max_f32_e32 v32, v23, v28
	v_min_f32_e32 v23, v23, v28
	v_max_f32_e32 v28, v25, v19
	v_min_f32_e32 v19, v25, v19
	v_max_f32_e32 v25, v18, v20
	v_min_f32_e32 v37, v40, v236
	v_max_f32_e32 v237, v43, v47
	v_min_f32_e32 v43, v43, v47
	v_max_f32_e32 v47, v49, v45
	v_min_f32_e32 v45, v49, v45
	v_max_f32_e32 v49, v42, v38
	v_min_f32_e32 v38, v42, v38
	v_max_f32_e32 v42, v46, v48
	v_min_f32_e32 v46, v46, v48
	v_max_f32_e32 v48, v39, v44
	v_min_f32_e32 v39, v39, v44
	v_max_f32_e32 v44, v41, v35
	v_min_f32_e32 v35, v41, v35
	v_max_f32_e32 v41, v34, v36
	v_min_f32_e32 v53, v56, v244
	v_max_f32_e32 v245, v59, v63
	v_min_f32_e32 v59, v59, v63
	v_max_f32_e32 v63, v65, v61
	v_min_f32_e32 v61, v65, v61
	v_max_f32_e32 v65, v58, v54
	v_min_f32_e32 v54, v58, v54
	v_max_f32_e32 v58, v62, v64
	v_min_f32_e32 v62, v62, v64
	v_max_f32_e32 v64, v55, v60
	v_min_f32_e32 v55, v55, v60
	v_max_f32_e32 v60, v57, v51
	v_min_f32_e32 v51, v57, v51
	v_max_f32_e32 v57, v50, v52
; __device__ __forceinline__ void phase_topk_fast(LAS unsigned char* lds, const bf16* Q, const bf16* keysb  , int* EID, float* GATE, bool prestaged  ) {
;     ...
;                 bsort16_desc<0, 64>(v); bsort16_desc<16, 64>(v); bsort16_desc<32, 64>(v); bsort16_desc<48, 64>(v);
;                 merge_top16<0, 16, 64>(v); merge_top16<32, 48, 64>(v); merge_top16<0, 32, 64>(v);
	v_min_f32_e32 v2, v2, v4
	v_max_f32_e32 v4, v221, v5
	v_min_f32_e32 v5, v221, v5
	v_max_f32_e32 v221, v11, v12
	v_min_f32_e32 v11, v11, v12
	v_max_f32_e32 v12, v15, v10
	v_min_f32_e32 v10, v15, v10
	v_max_f32_e32 v15, v17, v14
	v_min_f32_e32 v14, v17, v14
	v_max_f32_e32 v17, v16, v13
	v_min_f32_e32 v13, v16, v13
	v_max_f32_e32 v16, v7, v6
	v_min_f32_e32 v6, v7, v6
	v_max_f32_e32 v7, v9, v3
	v_min_f32_e32 v18, v18, v20
	v_max_f32_e32 v20, v229, v21
	v_min_f32_e32 v21, v229, v21
	v_max_f32_e32 v229, v27, v28
	v_min_f32_e32 v27, v27, v28
	v_max_f32_e32 v28, v31, v26
	v_min_f32_e32 v26, v31, v26
	v_max_f32_e32 v31, v33, v30
	v_min_f32_e32 v30, v33, v30
	v_max_f32_e32 v33, v32, v29
	v_min_f32_e32 v29, v32, v29
	v_max_f32_e32 v32, v23, v22
	v_min_f32_e32 v22, v23, v22
	v_max_f32_e32 v23, v25, v19
	v_min_f32_e32 v34, v34, v36
	v_max_f32_e32 v36, v237, v37
	v_min_f32_e32 v37, v237, v37
	v_max_f32_e32 v237, v43, v44
	v_min_f32_e32 v43, v43, v44
	v_max_f32_e32 v44, v47, v42
	v_min_f32_e32 v42, v47, v42
	v_max_f32_e32 v47, v49, v46
	v_min_f32_e32 v46, v49, v46
	v_max_f32_e32 v49, v48, v45
	v_min_f32_e32 v45, v48, v45
	v_max_f32_e32 v48, v39, v38
	v_min_f32_e32 v38, v39, v38
	v_max_f32_e32 v39, v41, v35
	v_min_f32_e32 v50, v50, v52
	v_max_f32_e32 v52, v245, v53
	v_min_f32_e32 v53, v245, v53
	v_max_f32_e32 v245, v59, v60
	v_min_f32_e32 v59, v59, v60
	v_max_f32_e32 v60, v63, v58
	v_min_f32_e32 v58, v63, v58
	v_max_f32_e32 v63, v65, v62
	v_min_f32_e32 v62, v65, v62
	v_max_f32_e32 v65, v64, v61
	v_min_f32_e32 v61, v64, v61
	v_max_f32_e32 v64, v55, v54
	v_min_f32_e32 v54, v55, v54
	v_max_f32_e32 v55, v57, v51
	v_min_f32_e32 v3, v9, v3
	v_max_f32_e32 v222, v5, v10
	v_min_f32_e32 v5, v5, v10
	v_max_f32_e32 v10, v15, v17
	v_min_f32_e32 v15, v15, v17
	v_max_f32_e32 v17, v14, v13
	v_min_f32_e32 v13, v14, v13
	v_max_f32_e32 v14, v16, v7
	v_min_f32_e32 v19, v25, v19
	v_max_f32_e32 v230, v21, v26
	v_min_f32_e32 v21, v21, v26
	v_max_f32_e32 v26, v31, v33
	v_min_f32_e32 v31, v31, v33
	v_max_f32_e32 v33, v30, v29
	v_min_f32_e32 v29, v30, v29
	v_max_f32_e32 v30, v32, v23
	v_min_f32_e32 v35, v41, v35
	v_max_f32_e32 v238, v37, v42
	v_min_f32_e32 v37, v37, v42
	v_max_f32_e32 v42, v47, v49
	v_min_f32_e32 v47, v47, v49
	v_max_f32_e32 v49, v46, v45
	v_min_f32_e32 v45, v46, v45
	v_max_f32_e32 v46, v48, v39
	v_min_f32_e32 v51, v57, v51
	v_max_f32_e32 v246, v53, v58
	v_min_f32_e32 v53, v53, v58
	v_max_f32_e32 v58, v63, v65
	v_min_f32_e32 v63, v63, v65
	v_max_f32_e32 v65, v62, v61
	v_min_f32_e32 v61, v62, v61
	v_max_f32_e32 v62, v64, v55
	v_min_f32_e32 v7, v16, v7
	v_max_f32_e32 v16, v6, v3
	v_max_f32_e32 v223, v221, v5
	v_min_f32_e32 v5, v221, v5
	v_max_f32_e32 v221, v14, v11
	v_min_f32_e32 v11, v14, v11
	v_min_f32_e32 v23, v32, v23
	v_max_f32_e32 v32, v22, v19
	v_max_f32_e32 v231, v229, v21
	v_min_f32_e32 v21, v229, v21
	v_max_f32_e32 v229, v30, v27
	v_min_f32_e32 v27, v30, v27
	v_min_f32_e32 v39, v48, v39
	v_max_f32_e32 v48, v38, v35
	v_max_f32_e32 v239, v237, v37
	v_min_f32_e32 v37, v237, v37
	v_max_f32_e32 v237, v46, v43
	v_min_f32_e32 v43, v46, v43
	v_min_f32_e32 v55, v64, v55
	v_max_f32_e32 v64, v54, v51
	v_max_f32_e32 v247, v245, v53
	v_min_f32_e32 v53, v245, v53
	v_max_f32_e32 v245, v62, v59
	v_min_f32_e32 v59, v62, v59
	v_min_f32_e32 v9, v4, v12
	v_max_f32_e32 v14, v16, v7
	v_min_f32_e32 v7, v16, v7
	v_max_f32_e32 v16, v223, v10
	v_min_f32_e32 v10, v223, v10
	v_max_f32_e32 v223, v5, v15
	v_min_f32_e32 v5, v5, v15
	v_max_f32_e32 v15, v17, v221
	v_min_f32_e32 v17, v17, v221
	v_max_f32_e32 v221, v13, v11
	v_min_f32_e32 v25, v20, v28
	v_max_f32_e32 v30, v32, v23
	v_min_f32_e32 v23, v32, v23
	v_max_f32_e32 v32, v231, v26
	v_min_f32_e32 v26, v231, v26
	v_max_f32_e32 v231, v21, v31
	v_min_f32_e32 v21, v21, v31
	v_max_f32_e32 v31, v33, v229
	v_min_f32_e32 v33, v33, v229
	v_max_f32_e32 v229, v29, v27
	v_min_f32_e32 v41, v36, v44
	v_max_f32_e32 v46, v48, v39
	v_min_f32_e32 v39, v48, v39
	v_max_f32_e32 v48, v239, v42
	v_min_f32_e32 v42, v239, v42
	v_max_f32_e32 v239, v37, v47
	v_min_f32_e32 v37, v37, v47
	v_max_f32_e32 v47, v49, v237
	v_min_f32_e32 v49, v49, v237
	v_max_f32_e32 v237, v45, v43
	v_min_f32_e32 v57, v52, v60
	v_max_f32_e32 v62, v64, v55
	v_min_f32_e32 v55, v64, v55
	v_max_f32_e32 v64, v247, v58
	v_min_f32_e32 v58, v247, v58
	v_max_f32_e32 v247, v53, v63
	v_min_f32_e32 v53, v53, v63
	v_max_f32_e32 v63, v65, v245
	v_min_f32_e32 v65, v65, v245
	v_max_f32_e32 v245, v61, v59
	v_min_f32_e32 v3, v6, v3
	v_min_f32_e32 v6, v222, v9
	v_min_f32_e32 v11, v13, v11
	v_min_f32_e32 v224, v10, v223
	v_max_f32_e32 v225, v15, v5
	v_min_f32_e32 v5, v15, v5
	v_max_f32_e32 v15, v17, v221
	v_min_f32_e32 v19, v22, v19
	v_min_f32_e32 v22, v230, v25
	v_min_f32_e32 v27, v29, v27
	v_min_f32_e32 v232, v26, v231
	v_max_f32_e32 v233, v31, v21
	v_min_f32_e32 v21, v31, v21
	v_max_f32_e32 v31, v33, v229
	v_min_f32_e32 v35, v38, v35
	v_min_f32_e32 v38, v238, v41
	v_min_f32_e32 v43, v45, v43
	v_min_f32_e32 v240, v42, v239
	v_max_f32_e32 v241, v47, v37
	v_min_f32_e32 v37, v47, v37
	v_max_f32_e32 v47, v49, v237
	v_min_f32_e32 v51, v54, v51
	v_min_f32_e32 v54, v246, v57
	v_min_f32_e32 v59, v61, v59
	v_min_f32_e32 v248, v58, v247
	v_max_f32_e32 v249, v63, v53
	v_min_f32_e32 v53, v63, v53
	v_max_f32_e32 v63, v65, v245
	v_min_f32_e32 v13, v16, v6
	v_min_f32_e32 v17, v17, v221
	v_min_f32_e32 v221, v14, v11
	v_min_f32_e32 v226, v224, v225
	v_min_f32_e32 v227, v5, v15
	v_min_f32_e32 v29, v32, v22
	v_min_f32_e32 v33, v33, v229
	v_min_f32_e32 v229, v30, v27
	v_min_f32_e32 v234, v232, v233
	v_min_f32_e32 v235, v21, v31
	v_min_f32_e32 v45, v48, v38
	v_min_f32_e32 v49, v49, v237
	v_min_f32_e32 v237, v46, v43
; __device__ __forceinline__ void phase_topk_fast(LAS unsigned char* lds, const bf16* Q, const bf16* keysb  , int* EID, float* GATE, bool prestaged  ) {
;     ...
;                 merge_top16<0, 16, 64>(v); merge_top16<32, 48, 64>(v); merge_top16<0, 32, 64>(v);
	v_min_f32_e32 v242, v240, v241
	v_min_f32_e32 v243, v37, v47
	v_min_f32_e32 v61, v64, v54
	v_min_f32_e32 v65, v65, v245
	v_min_f32_e32 v245, v62, v59
	v_min_f32_e32 v250, v248, v249
	v_min_f32_e32 v251, v53, v63
	v_max3_f32 v8, v8, v220, v18
	v_max3_f32 v4, v4, v12, v19
	v_max3_f32 v9, v222, v9, v23
	v_max3_f32 v6, v16, v6, v229
	v_max3_f32 v12, v13, v30, v27
	v_max3_f32 v10, v10, v223, v33
	v_max3_f32 v13, v224, v225, v235
	v_max3_f32 v16, v226, v21, v31
	v_max3_f32 v5, v5, v15, v234
	v_max3_f32 v15, v227, v232, v233
	v_max3_f32 v17, v17, v26, v231
	v_max3_f32 v11, v14, v11, v29
	v_max3_f32 v14, v221, v32, v22
	v_max3_f32 v7, v7, v230, v25
	v_max3_f32 v3, v3, v20, v28
	v_max3_f32 v2, v2, v24, v228
	v_max3_f32 v26, v40, v236, v50
	v_max3_f32 v27, v36, v44, v51
	v_max3_f32 v28, v238, v41, v55
	v_max3_f32 v29, v48, v38, v245
	v_max3_f32 v30, v45, v62, v59
	v_max3_f32 v31, v42, v239, v65
	v_max3_f32 v32, v240, v241, v251
	v_max3_f32 v33, v242, v53, v63
	v_max3_f32 v36, v37, v47, v250
	v_max3_f32 v37, v243, v248, v249
	v_max3_f32 v38, v49, v58, v247
	v_max3_f32 v40, v46, v43, v61
	v_max3_f32 v41, v237, v64, v54
	v_max3_f32 v39, v39, v246, v57
	v_max3_f32 v35, v35, v52, v60
	v_max3_f32 v34, v34, v56, v244
	v_max_f32_e32 v18, v8, v5
	v_min_f32_e32 v5, v8, v5
	v_max_f32_e32 v8, v4, v15
	v_min_f32_e32 v4, v4, v15
	v_max_f32_e32 v15, v9, v17
	v_min_f32_e32 v9, v9, v17
	v_max_f32_e32 v17, v6, v11
	v_min_f32_e32 v6, v6, v11
	v_max_f32_e32 v11, v12, v14
	v_min_f32_e32 v12, v12, v14
	v_max_f32_e32 v14, v10, v7
	v_min_f32_e32 v7, v10, v7
	v_max_f32_e32 v10, v13, v3
	v_min_f32_e32 v3, v13, v3
	v_max_f32_e32 v13, v16, v2
	v_min_f32_e32 v2, v16, v2
	v_max_f32_e32 v42, v26, v36
	v_min_f32_e32 v26, v26, v36
	v_max_f32_e32 v36, v27, v37
	v_min_f32_e32 v27, v27, v37
	v_max_f32_e32 v37, v28, v38
	v_min_f32_e32 v28, v28, v38
	v_max_f32_e32 v38, v29, v40
	v_min_f32_e32 v29, v29, v40
	v_max_f32_e32 v40, v30, v41
	v_min_f32_e32 v30, v30, v41
	v_max_f32_e32 v41, v31, v39
	v_min_f32_e32 v31, v31, v39
	v_max_f32_e32 v39, v32, v35
	v_min_f32_e32 v32, v32, v35
	v_max_f32_e32 v35, v33, v34
	v_min_f32_e32 v33, v33, v34
	v_max_f32_e32 v16, v18, v11
	v_min_f32_e32 v11, v18, v11
	v_max_f32_e32 v18, v8, v14
	v_min_f32_e32 v8, v8, v14
	v_max_f32_e32 v14, v15, v10
	v_min_f32_e32 v10, v15, v10
	v_max_f32_e32 v15, v17, v13
	v_min_f32_e32 v13, v17, v13
	v_max_f32_e32 v17, v5, v12
	v_min_f32_e32 v5, v5, v12
	v_max_f32_e32 v12, v4, v7
	v_min_f32_e32 v4, v4, v7
	v_max_f32_e32 v7, v9, v3
	v_min_f32_e32 v3, v9, v3
	v_max_f32_e32 v9, v6, v2
	v_min_f32_e32 v2, v6, v2
	v_max_f32_e32 v34, v42, v40
	v_min_f32_e32 v40, v42, v40
	v_max_f32_e32 v42, v36, v41
	v_min_f32_e32 v36, v36, v41
	v_max_f32_e32 v41, v37, v39
	v_min_f32_e32 v37, v37, v39
	v_max_f32_e32 v39, v38, v35
	v_min_f32_e32 v35, v38, v35
	v_max_f32_e32 v38, v26, v30
	v_min_f32_e32 v26, v26, v30
	v_max_f32_e32 v30, v27, v31
	v_min_f32_e32 v27, v27, v31
	v_max_f32_e32 v31, v28, v32
	v_min_f32_e32 v28, v28, v32
	v_max_f32_e32 v32, v29, v33
	v_min_f32_e32 v29, v29, v33
	v_max_f32_e32 v6, v16, v14
	v_min_f32_e32 v14, v16, v14
	v_max_f32_e32 v16, v18, v15
	v_min_f32_e32 v15, v18, v15
	v_max_f32_e32 v18, v11, v10
	v_min_f32_e32 v10, v11, v10
	v_max_f32_e32 v11, v8, v13
	v_min_f32_e32 v8, v8, v13
	v_max_f32_e32 v13, v17, v7
	v_min_f32_e32 v7, v17, v7
	v_max_f32_e32 v17, v12, v9
	v_min_f32_e32 v9, v12, v9
	v_max_f32_e32 v12, v5, v3
	v_min_f32_e32 v3, v5, v3
	v_max_f32_e32 v5, v4, v2
	v_min_f32_e32 v2, v4, v2
	v_max_f32_e32 v33, v34, v41
	v_min_f32_e32 v34, v34, v41
	v_max_f32_e32 v41, v42, v39
	v_min_f32_e32 v39, v42, v39
	v_max_f32_e32 v42, v40, v37
	v_min_f32_e32 v37, v40, v37
	v_max_f32_e32 v40, v36, v35
	v_min_f32_e32 v35, v36, v35
	v_max_f32_e32 v36, v38, v31
	v_min_f32_e32 v31, v38, v31
	v_max_f32_e32 v38, v30, v32
	v_min_f32_e32 v30, v30, v32
	v_max_f32_e32 v32, v26, v28
	v_min_f32_e32 v26, v26, v28
	v_max_f32_e32 v28, v27, v29
	v_min_f32_e32 v27, v27, v29
	v_min_f32_e32 v4, v6, v16
	v_min_f32_e32 v19, v14, v15
	v_min_f32_e32 v20, v18, v11
	v_min_f32_e32 v21, v10, v8
	v_min_f32_e32 v22, v13, v17
	v_min_f32_e32 v23, v7, v9
	v_min_f32_e32 v24, v12, v5
	v_min_f32_e32 v25, v3, v2
	v_min_f32_e32 v29, v33, v41
	v_min_f32_e32 v43, v34, v39
	v_min_f32_e32 v44, v42, v40
	v_min_f32_e32 v45, v37, v35
	v_min_f32_e32 v46, v36, v38
	v_min_f32_e32 v47, v31, v30
	v_min_f32_e32 v48, v32, v28
	v_min_f32_e32 v49, v26, v27
	v_max3_f32 v6, v6, v16, v49
	v_max3_f32 v4, v4, v26, v27
	v_max3_f32 v14, v14, v15, v48
	v_max3_f32 v15, v19, v32, v28
	v_max3_f32 v11, v18, v11, v47
	v_max3_f32 v16, v20, v31, v30
	v_max3_f32 v8, v10, v8, v46
	v_max3_f32 v10, v21, v36, v38
	v_max3_f32 v13, v13, v17, v45
	v_max3_f32 v17, v22, v37, v35
	v_max3_f32 v7, v7, v9, v44
	v_max3_f32 v9, v23, v42, v40
	v_max3_f32 v5, v12, v5, v43
	v_max3_f32 v12, v24, v34, v39
	v_max3_f32 v2, v3, v2, v29
	v_max3_f32 v3, v25, v33, v41
	v_max_f32_e32 v18, v6, v13
	v_min_f32_e32 v6, v6, v13
	v_max_f32_e32 v13, v4, v17
	v_min_f32_e32 v4, v4, v17
	v_max_f32_e32 v17, v14, v7
	v_min_f32_e32 v7, v14, v7
	v_max_f32_e32 v14, v15, v9
	v_min_f32_e32 v9, v15, v9
	v_max_f32_e32 v15, v11, v5
	v_min_f32_e32 v5, v11, v5
	v_max_f32_e32 v11, v16, v12
	v_min_f32_e32 v12, v16, v12
	v_max_f32_e32 v16, v8, v2
	v_min_f32_e32 v2, v8, v2
	v_max_f32_e32 v8, v10, v3
	v_min_f32_e32 v3, v10, v3
	v_max_f32_e32 v10, v18, v15
	v_min_f32_e32 v15, v18, v15
	v_max_f32_e32 v18, v13, v11
	v_min_f32_e32 v11, v13, v11
	v_max_f32_e32 v13, v17, v16
	v_min_f32_e32 v16, v17, v16
	v_max_f32_e32 v17, v14, v8
	v_min_f32_e32 v8, v14, v8
	v_max_f32_e32 v14, v6, v5
	v_min_f32_e32 v5, v6, v5
	v_max_f32_e32 v6, v4, v12
	v_min_f32_e32 v4, v4, v12
; #define LAS __attribute__((address_space(3)))
; __device__ __forceinline__ void phase_topk_fast(LAS unsigned char* lds, const bf16* Q, const bf16* keysb  , int* EID, float* GATE, bool prestaged  ) {
;     ...
;                 for (int i = 0; i < 16; ++i) o[i] = __shfl_xor(v[i], 32);
; #pragma unroll
;                 for (int i = 0; i < 16; ++i) v[i] = fmaxf(v[i], o[15 - i]);
;                 bmerge16_desc<0, 64>(v);
; #pragma unroll
;                 for (int i = 0; i < 16; ++i) { if (p == 0) ta[i] = v[i]; else tb[i] = v[i]; }
;                 __builtin_amdgcn_sched_barrier(0);
;             }
;             float av[16], bv[16]; int ai[16], bi[16];
; #pragma unroll
;             for (int i = 0; i < 16; ++i) { const unsigned ua = __builtin_bit_cast(unsigned, ta[i]), ub = __builtin_bit_cast(unsigned, tb[i]);
;                 av[i] = __builtin_bit_cast(float, ua & ~127u); ai[i] = (int)(ua & 127u); bv[i] = __builtin_bit_cast(float, ub & ~127u); bi[i] = (int)(ub & 127u); }
;             LAS int* etab = (LAS int*)(lds + 69632 + wave * 8192) + c * 64;
; #pragma unroll
;             for (int s2 = 0; s2 < 32; ++s2) {
;                 const int p0 = (ai[pair_i(s2)] << 7) | bi[pair_j(s2)]; int p1 = 0;
;                 if (s2 + 32 < 50) p1 = (ai[pair_i(s2 + 32 < 50 ? s2 + 32 : 0)] << 7) | bi[pair_j(s2 + 32 < 50 ? s2 + 32 : 0)];
;                 etab[s2 + 32 * hh] = hh ? p1 : p0;
	v_max_f32_e32 v12, v7, v2
	v_min_f32_e32 v2, v7, v2
	v_max_f32_e32 v7, v9, v3
	v_min_f32_e32 v3, v9, v3
	v_max_f32_e32 v9, v10, v13
	v_min_f32_e32 v10, v10, v13
	v_max_f32_e32 v13, v18, v17
	v_min_f32_e32 v17, v18, v17
	v_max_f32_e32 v18, v15, v16
	v_min_f32_e32 v15, v15, v16
	v_max_f32_e32 v16, v11, v8
	v_min_f32_e32 v8, v11, v8
	v_max_f32_e32 v11, v14, v12
	v_min_f32_e32 v12, v14, v12
	v_max_f32_e32 v14, v6, v7
	v_min_f32_e32 v6, v6, v7
	v_max_f32_e32 v7, v5, v2
	v_min_f32_e32 v2, v5, v2
	v_max_f32_e32 v5, v4, v3
	v_min_f32_e32 v3, v4, v3
	v_max_f32_e32 v4, v9, v13
	v_min_f32_e32 v9, v9, v13
	v_max_f32_e32 v13, v10, v17
	v_min_f32_e32 v10, v10, v17
	v_max_f32_e32 v17, v18, v16
	v_min_f32_e32 v16, v18, v16
	v_max_f32_e32 v18, v15, v8
	v_min_f32_e32 v8, v15, v8
	v_max_f32_e32 v15, v11, v14
	v_min_f32_e32 v11, v11, v14
	v_max_f32_e32 v14, v12, v6
	v_min_f32_e32 v6, v12, v6
	v_max_f32_e32 v12, v7, v5
	v_min_f32_e32 v5, v7, v5
	v_max_f32_e32 v7, v2, v3
	v_min_f32_e32 v2, v2, v3
	ds_bpermute_b32 v29, v203, v2
	ds_bpermute_b32 v31, v203, v7
	ds_bpermute_b32 v33, v203, v5
	ds_bpermute_b32 v32, v203, v12
	ds_bpermute_b32 v3, v203, v4
	ds_bpermute_b32 v19, v203, v9
	ds_bpermute_b32 v20, v203, v13
	ds_bpermute_b32 v21, v203, v10
	ds_bpermute_b32 v22, v203, v17
	ds_bpermute_b32 v23, v203, v16
	ds_bpermute_b32 v24, v203, v18
	ds_bpermute_b32 v25, v203, v8
	ds_bpermute_b32 v26, v203, v15
	ds_bpermute_b32 v27, v203, v11
	ds_bpermute_b32 v28, v203, v14
	ds_bpermute_b32 v30, v203, v6
	s_waitcnt lgkmcnt(14)
	v_max_f32_e32 v4, v4, v29
	v_max_f32_e32 v29, v31, v31
	v_max_f32_e32 v9, v9, v29
	s_waitcnt lgkmcnt(13)
	v_max_f32_e32 v29, v33, v33
	v_max_f32_e32 v13, v13, v29
	s_waitcnt lgkmcnt(12)
	v_max_f32_e32 v29, v32, v32
	v_max_f32_e32 v10, v10, v29
	s_waitcnt lgkmcnt(0)
	v_max_f32_e32 v29, v30, v30
	v_max_f32_e32 v17, v17, v29
	v_max_f32_e32 v16, v16, v28
	v_max_f32_e32 v18, v18, v27
	v_max_f32_e32 v8, v8, v26
	v_max_f32_e32 v15, v15, v25
	v_max_f32_e32 v11, v11, v24
	v_max_f32_e32 v14, v14, v23
	v_max_f32_e32 v6, v6, v22
	v_max_f32_e32 v12, v12, v21
	v_max_f32_e32 v5, v5, v20
	v_max_f32_e32 v7, v7, v19
	v_max_f32_e32 v2, v2, v3
	v_max_f32_e32 v3, v4, v15
	v_min_f32_e32 v4, v4, v15
	v_max_f32_e32 v15, v9, v11
	v_min_f32_e32 v9, v9, v11
	v_max_f32_e32 v11, v13, v14
	v_min_f32_e32 v13, v13, v14
	v_max_f32_e32 v14, v10, v6
	v_min_f32_e32 v6, v10, v6
	v_max_f32_e32 v10, v17, v12
	v_min_f32_e32 v12, v17, v12
	v_max_f32_e32 v17, v16, v5
	v_min_f32_e32 v5, v16, v5
	v_max_f32_e32 v16, v18, v7
	v_min_f32_e32 v7, v18, v7
	v_max_f32_e32 v18, v8, v2
	v_min_f32_e32 v2, v8, v2
	v_max_f32_e32 v8, v3, v10
	v_min_f32_e32 v3, v3, v10
	v_max_f32_e32 v10, v15, v17
	v_min_f32_e32 v15, v15, v17
	v_max_f32_e32 v17, v11, v16
	v_min_f32_e32 v11, v11, v16
	v_max_f32_e32 v16, v14, v18
	v_min_f32_e32 v14, v14, v18
	v_max_f32_e32 v18, v4, v12
	v_min_f32_e32 v4, v4, v12
	v_max_f32_e32 v12, v9, v5
	v_min_f32_e32 v5, v9, v5
	v_max_f32_e32 v9, v13, v7
	v_min_f32_e32 v7, v13, v7
	v_max_f32_e32 v13, v6, v2
	v_min_f32_e32 v2, v6, v2
	v_max_f32_e32 v6, v8, v17
	v_min_f32_e32 v8, v8, v17
	v_max_f32_e32 v17, v10, v16
	v_min_f32_e32 v10, v10, v16
	v_max_f32_e32 v16, v3, v11
	v_min_f32_e32 v3, v3, v11
	v_max_f32_e32 v11, v15, v14
	v_min_f32_e32 v14, v15, v14
	v_max_f32_e32 v15, v18, v9
	v_min_f32_e32 v9, v18, v9
	v_max_f32_e32 v18, v12, v13
	v_min_f32_e32 v12, v12, v13
	v_max_f32_e32 v13, v4, v7
	v_min_f32_e32 v4, v4, v7
	v_max_f32_e32 v7, v5, v2
	v_min_f32_e32 v2, v5, v2
	v_max_f32_e32 v5, v6, v17
	v_min_f32_e32 v6, v6, v17
	v_max_f32_e32 v17, v8, v10
	v_min_f32_e32 v8, v8, v10
	v_max_f32_e32 v10, v16, v11
	v_min_f32_e32 v11, v16, v11
	v_max_f32_e32 v16, v3, v14
	v_min_f32_e32 v3, v3, v14
	v_max_f32_e32 v14, v15, v18
	v_min_f32_e32 v15, v15, v18
	v_max_f32_e32 v18, v9, v12
	v_min_f32_e32 v12, v9, v12
	v_max_f32_e32 v19, v13, v7
	v_min_f32_e32 v13, v13, v7
	v_max_f32_e32 v20, v4, v2
	v_min_f32_e32 v21, v4, v2
	v_and_b32_e32 v27, 0xffffff80, v3
	v_and_b32_e32 v28, 0x7f, v3
	v_lshlrev_b32_e32 v2, 7, v219
	v_and_b32_e32 v35, 0xffffff80, v5
	v_and_b32_e32 v36, 0xffffff80, v6
	v_and_b32_e32 v7, 0x7f, v6
	v_and_b32_e32 v6, 0x7f, v5
	v_lshlrev_b32_e32 v3, 7, v218
	v_lshlrev_b32_e32 v5, 7, v217
	v_and_b32_e32 v34, 0x3f80, v2
	v_and_b32_e32 v39, 0x7f, v8
	v_and_b32_e32 v41, 0x3f80, v3
	v_and_b32_e32 v42, 0x3f80, v5
	v_and_b32_e32 v25, 0xffffff80, v17
	v_and_b32_e32 v17, 0x7f, v17
	v_or_b32_e32 v2, v7, v34
	v_or_b32_e32 v4, v6, v34
	v_or_b32_e32 v3, v6, v41
	v_or_b32_e32 v5, v39, v42
	v_cndmask_b32_e64 v3, v3, v2, s[4:5]
	v_cndmask_b32_e64 v2, v5, v4, s[4:5]
	v_or_b32_e32 v4, v17, v34
	v_or_b32_e32 v5, v7, v41
	v_cndmask_b32_e64 v4, v5, v4, s[4:5]
	v_or_b32_e32 v5, v39, v34
	v_or_b32_e32 v41, v17, v41
	v_cndmask_b32_e64 v5, v41, v5, s[4:5]
	ds_write_b128 v201, v[2:5]
	v_lshlrev_b32_e32 v3, 7, v216
	v_lshlrev_b32_e32 v4, 7, v215
	v_and_b32_e32 v26, 0xffffff80, v10
	v_and_b32_e32 v10, 0x7f, v10
	v_and_b32_e32 v38, 0xffffff80, v8
	v_pk_mov_b32 v[8:9], v[6:7], v[6:7] op_sel:[1,0]
	v_and_b32_e32 v43, 0xffffff80, v11
	v_and_b32_e32 v11, 0x7f, v11
	v_and_b32_e32 v5, 0x3f80, v3
	v_and_b32_e32 v3, 0x3f80, v4
	v_or_b32_e32 v2, v10, v34
	v_and_b32_e32 v45, 0xffffff80, v16
	v_and_b32_e32 v16, 0x7f, v16
	v_or_b32_e32 v4, v6, v3
	v_or_b32_e32 v46, v11, v34
	v_or_b32_e32 v3, v8, v3
	v_cndmask_b32_e64 v2, v4, v2, s[4:5]
	v_or_b32_e32 v4, v16, v34
	v_or_b32_e32 v47, v9, v5
	v_cndmask_b32_e64 v3, v3, v46, s[4:5]
	v_or_b32_e32 v46, v28, v34
	v_or_b32_e32 v5, v7, v5
	v_cndmask_b32_e64 v4, v47, v4, s[4:5]
	v_cndmask_b32_e64 v5, v5, v46, s[4:5]
	ds_write_b128 v201, v[2:5] offset:16
	v_and_b32_e32 v47, 0xffffff80, v18
; #define LAS __attribute__((address_space(3)))
; __device__ __forceinline__ void phase_topk_fast(LAS unsigned char* lds, const bf16* Q, const bf16* keysb  , int* EID, float* GATE, bool prestaged  ) {
;     ...
;             LAS int* etab = (LAS int*)(lds + 69632 + wave * 8192) + c * 64;
; #pragma unroll
;             for (int s2 = 0; s2 < 32; ++s2) {
;                 const int p0 = (ai[pair_i(s2)] << 7) | bi[pair_j(s2)]; int p1 = 0;
;                 if (s2 + 32 < 50) p1 = (ai[pair_i(s2 + 32 < 50 ? s2 + 32 : 0)] << 7) | bi[pair_j(s2 + 32 < 50 ? s2 + 32 : 0)];
;                 etab[s2 + 32 * hh] = hh ? p1 : p0;
;             }
;             __builtin_amdgcn_sched_barrier(0);
;             float ck[32];
; #pragma unroll
;             for (int s2 = 0; s2 < 32; ++s2) {
;                 const float k0 = av[pair_i(s2)] + bv[pair_j(s2)]; float k1 = -3.0e38f;
;                 if (s2 + 32 < 50) k1 = av[pair_i(s2 + 32 < 50 ? s2 + 32 : 0)] + bv[pair_j(s2 + 32 < 50 ? s2 + 32 : 0)];
;                 const float kk = hh ? k1 : k0;
;                 ck[s2] = __uint_as_float((__float_as_uint(kk) & ~63u) | (unsigned)(s2 + 32 * hh));
	v_and_b32_e32 v3, 0x7f, v18
	v_lshlrev_b32_e32 v18, 7, v213
	v_and_b32_e32 v46, 0xffffff80, v15
	v_and_b32_e32 v4, 0x7f, v15
	v_lshlrev_b32_e32 v15, 7, v214
	v_and_b32_e32 v18, 0x3f80, v18
	v_and_or_b32 v2, v14, s27, v34
	v_and_b32_e32 v15, 0x3f80, v15
	v_or_b32_e32 v48, v6, v18
	v_cndmask_b32_e64 v2, v48, v2, s[4:5]
	v_or_b32_e32 v3, v3, v34
	v_or_b32_e32 v48, v4, v34
	v_or_b32_e32 v4, v9, v15
	v_or_b32_e32 v8, v8, v18
	v_cndmask_b32_e64 v4, v4, v3, s[4:5]
	v_cndmask_b32_e64 v3, v8, v48, s[4:5]
	v_lshlrev_b32_e32 v18, 7, v211
	ds_write_b96 v201, v[2:4] offset:32
	v_and_b32_e32 v4, 0xffffff80, v12
	v_and_b32_e32 v12, 0x7f, v12
	v_lshlrev_b32_e32 v15, 7, v212
	v_and_b32_e32 v18, 0x3f80, v18
	v_and_b32_e32 v9, 0x7f, v19
	v_or_b32_e32 v12, v12, v34
	v_and_b32_e32 v15, 0x3f80, v15
	v_or_b32_e32 v18, v6, v18
	v_and_b32_e32 v8, 0xffffff80, v19
	v_or_b32_e32 v9, v9, v34
	v_or_b32_e32 v15, v6, v15
	v_cndmask_b32_e64 v12, v18, v12, s[4:5]
	v_and_b32_e32 v18, 0xffffff80, v20
	v_and_b32_e32 v19, 0x7f, v20
	v_lshlrev_b32_e32 v20, 7, v210
	v_lshlrev_b32_e32 v48, 7, v209
	v_cndmask_b32_e64 v9, v15, v9, s[4:5]
	v_and_b32_e32 v15, 0xffffff80, v13
	v_and_b32_e32 v13, 0x7f, v13
	v_and_b32_e32 v20, 0x3f80, v20
	v_and_b32_e32 v48, 0x3f80, v48
	v_or_b32_e32 v19, v19, v34
	v_or_b32_e32 v13, v13, v34
	v_or_b32_e32 v20, v6, v20
	v_or_b32_e32 v48, v6, v48
	v_cndmask_b32_e64 v19, v20, v19, s[4:5]
	v_cndmask_b32_e64 v13, v48, v13, s[4:5]
	ds_write2_b32 v201, v13, v19 offset0:13 offset1:14
	v_lshlrev_b32_e32 v19, 7, v208
	v_and_or_b32 v13, v21, s27, v34
	v_and_or_b32 v19, v19, s28, v6
	v_cndmask_b32_e64 v13, v19, v13, s[4:5]
	v_lshlrev_b32_e32 v19, 7, v205
	v_lshlrev_b32_e32 v20, 7, v207
	v_and_b32_e32 v19, 0x3f80, v19
	v_and_b32_e32 v20, 0x3f80, v20
	v_cndmask_b32_e64 v20, v20, v19, s[4:5]
	v_or_b32_e32 v20, v6, v20
	ds_write2_b32 v201, v13, v20 offset0:15 offset1:16
	v_lshlrev_b32_e32 v20, 7, v206
	v_or_b32_e32 v13, v7, v19
	v_and_or_b32 v20, v20, s28, v6
	v_cndmask_b32_e64 v13, v20, v13, s[4:5]
	v_or_b32_e32 v20, v17, v19
	v_cndmask_b32_e64 v20, 0, v20, s[4:5]
	ds_write2_b32 v201, v13, v20 offset0:17 offset1:18
	v_or_b32_e32 v13, v39, v19
	v_or_b32_e32 v20, v10, v19
	v_cndmask_b32_e64 v13, 0, v13, s[4:5]
	v_cndmask_b32_e64 v20, 0, v20, s[4:5]
	ds_write2_b32 v201, v13, v20 offset0:19 offset1:20
	v_or_b32_e32 v11, v11, v19
	v_or_b32_e32 v13, v16, v19
	v_cndmask_b32_e64 v11, 0, v11, s[4:5]
	v_cndmask_b32_e64 v13, 0, v13, s[4:5]
	ds_write2_b32 v201, v11, v13 offset0:21 offset1:22
	v_lshlrev_b32_e32 v13, 7, v204
	v_and_b32_e32 v13, 0x3f80, v13
	v_or_b32_e32 v11, v28, v19
	v_or_b32_e32 v16, v6, v13
	v_cndmask_b32_e64 v11, 0, v11, s[4:5]
	v_cndmask_b32_e64 v16, 0, v16, s[4:5]
	ds_write2_b32 v201, v11, v16 offset0:23 offset1:24
	v_or_b32_e32 v11, v7, v13
	v_or_b32_e32 v16, v17, v13
	v_or_b32_e32 v6, v6, v42
	v_or_b32_e32 v7, v7, v42
	v_cndmask_b32_e64 v11, 0, v11, s[4:5]
	v_cndmask_b32_e64 v16, 0, v16, s[4:5]
	v_cndmask_b32_e64 v6, 0, v6, s[4:5]
	v_cndmask_b32_e64 v7, 0, v7, s[4:5]
	ds_write2_b32 v201, v11, v16 offset0:25 offset1:26
	v_or_b32_e32 v11, v39, v13
	v_or_b32_e32 v10, v10, v13
	ds_write2_b32 v201, v6, v7 offset0:29 offset1:30
	v_or_b32_e32 v6, v17, v42
	v_and_b32_e32 v22, 0xffffff80, v219
	v_and_b32_e32 v23, 0xffffff80, v205
	v_and_b32_e32 v24, 0xffffff80, v204
	v_and_b32_e32 v29, 0xffffff80, v14
	v_and_b32_e32 v30, 0xffffff80, v208
	v_and_b32_e32 v31, 0xffffff80, v207
	v_and_b32_e32 v32, 0xffffff80, v206
	v_and_b32_e32 v33, 0xffffff80, v21
	v_and_b32_e32 v5, 0xffffff80, v213
	v_and_b32_e32 v14, 0xffffff80, v214
	v_and_b32_e32 v2, 0xffffff80, v211
	v_and_b32_e32 v3, 0xffffff80, v212
	ds_write2_b32 v201, v12, v9 offset0:11 offset1:12
	v_and_b32_e32 v9, 0xffffff80, v209
	v_and_b32_e32 v12, 0xffffff80, v210
	v_cndmask_b32_e64 v11, 0, v11, s[4:5]
	v_cndmask_b32_e64 v10, 0, v10, s[4:5]
	v_cndmask_b32_e64 v6, 0, v6, s[4:5]
	v_and_b32_e32 v37, 0xffffff80, v217
	v_and_b32_e32 v40, 0xffffff80, v218
	v_and_b32_e32 v41, 0xffffff80, v215
	v_and_b32_e32 v44, 0xffffff80, v216
	ds_write2_b32 v201, v11, v10 offset0:27 offset1:28
	ds_write_b32 v201, v6 offset:124
	v_add_f32_e32 v6, v22, v35
	v_add_f32_e32 v7, v37, v38
	v_cndmask_b32_e64 v6, v7, v6, s[4:5]
	v_add_f32_e32 v7, v22, v36
	v_add_f32_e32 v10, v40, v35
	v_cndmask_b32_e64 v7, v10, v7, s[4:5]
	v_add_f32_e32 v10, v22, v25
	v_add_f32_e32 v11, v40, v36
	v_cndmask_b32_e64 v10, v11, v10, s[4:5]
	v_add_f32_e32 v11, v22, v38
	v_add_f32_e32 v13, v40, v25
	v_cndmask_b32_e64 v11, v13, v11, s[4:5]
	v_add_f32_e32 v13, v22, v26
	v_add_f32_e32 v16, v41, v35
	v_cndmask_b32_e64 v13, v16, v13, s[4:5]
	v_add_f32_e32 v16, v22, v43
	v_add_f32_e32 v17, v41, v36
	v_cndmask_b32_e64 v16, v17, v16, s[4:5]
	v_add_f32_e32 v17, v22, v45
	v_add_f32_e32 v19, v44, v35
	v_add_f32_e32 v4, v22, v4
	v_add_f32_e32 v2, v2, v35
	v_cndmask_b32_e64 v17, v19, v17, s[4:5]
	v_add_f32_e32 v19, v22, v27
	v_add_f32_e32 v20, v44, v36
	v_cndmask_b32_e64 v2, v2, v4, s[4:5]
	v_add_f32_e32 v4, v22, v8
	v_add_f32_e32 v3, v3, v35
	v_cndmask_b32_e64 v19, v20, v19, s[4:5]
	v_add_f32_e32 v20, v22, v29
	v_add_f32_e32 v21, v5, v35
	v_cndmask_b32_e64 v3, v3, v4, s[4:5]
	v_add_f32_e32 v4, v22, v15
	v_add_f32_e32 v8, v9, v35
	v_cndmask_b32_e64 v20, v21, v20, s[4:5]
	v_add_f32_e32 v21, v22, v46
	v_add_f32_e32 v5, v5, v36
	v_cndmask_b32_e64 v4, v8, v4, s[4:5]
	v_add_f32_e32 v8, v22, v18
	v_add_f32_e32 v9, v12, v35
	v_cndmask_b32_e64 v5, v5, v21, s[4:5]
	v_add_f32_e32 v21, v22, v47
	v_add_f32_e32 v14, v14, v35
	v_cndmask_b32_e64 v8, v9, v8, s[4:5]
	v_add_f32_e32 v9, v22, v33
	v_add_f32_e32 v12, v30, v35
	v_add_f32_e32 v15, v23, v36
	v_add_f32_e32 v18, v32, v35
; __device__ __forceinline__ void phase_topk_fast(LAS unsigned char* lds, const bf16* Q, const bf16* keysb  , int* EID, float* GATE, bool prestaged  ) {
;     ...
;             float ck[32];
; #pragma unroll
;             for (int s2 = 0; s2 < 32; ++s2) {
;                 const float k0 = av[pair_i(s2)] + bv[pair_j(s2)]; float k1 = -3.0e38f;
;                 if (s2 + 32 < 50) k1 = av[pair_i(s2 + 32 < 50 ? s2 + 32 : 0)] + bv[pair_j(s2 + 32 < 50 ? s2 + 32 : 0)];
;                 const float kk = hh ? k1 : k0;
;                 ck[s2] = __uint_as_float((__float_as_uint(kk) & ~63u) | (unsigned)(s2 + 32 * hh));
;             }
;             __builtin_amdgcn_sched_barrier(0);
;             bsort16_desc<0, 32>(ck); bsort16_desc<16, 32>(ck);
	v_cndmask_b32_e64 v14, v14, v21, s[4:5]
	v_cndmask_b32_e64 v9, v12, v9, s[4:5]
	v_cndmask_b32_e64 v12, v31, v23, s[4:5]
	v_cndmask_b32_e64 v15, v18, v15, s[4:5]
	v_add_f32_e32 v18, v23, v25
	v_add_f32_e32 v21, v23, v38
	v_add_f32_e32 v22, v23, v26
	v_add_f32_e32 v28, v23, v43
	v_add_f32_e32 v29, v23, v45
	v_add_f32_e32 v23, v23, v27
	v_add_f32_e32 v27, v24, v35
	v_add_f32_e32 v30, v24, v36
	v_add_f32_e32 v31, v24, v25
	v_add_f32_e32 v32, v24, v38
	v_add_f32_e32 v24, v24, v26
	v_add_f32_e32 v26, v37, v35
	v_add_f32_e32 v33, v37, v36
	v_add_f32_e32 v25, v37, v25
	v_and_b32_e32 v18, 0xffffffc0, v18
	v_and_b32_e32 v21, 0xffffffc0, v21
	v_and_b32_e32 v22, 0xffffffc0, v22
	v_and_b32_e32 v28, 0xffffffc0, v28
	v_and_b32_e32 v29, 0xffffffc0, v29
	v_and_b32_e32 v23, 0xffffffc0, v23
	v_and_b32_e32 v27, 0xffffffc0, v27
	v_and_b32_e32 v30, 0xffffffc0, v30
	v_and_b32_e32 v31, 0xffffffc0, v31
	v_and_b32_e32 v32, 0xffffffc0, v32
	v_and_b32_e32 v24, 0xffffffc0, v24
	v_and_b32_e32 v26, 0xffffffc0, v26
	v_and_b32_e32 v33, 0xffffffc0, v33
	v_and_b32_e32 v25, 0xffffffc0, v25
	v_add_f32_e32 v12, v12, v35
	v_cndmask_b32_e64 v18, v202, v18, s[4:5]
	v_cndmask_b32_e64 v21, v202, v21, s[4:5]
	v_cndmask_b32_e64 v22, v202, v22, s[4:5]
	v_cndmask_b32_e64 v28, v202, v28, s[4:5]
	v_cndmask_b32_e64 v29, v202, v29, s[4:5]
	v_cndmask_b32_e64 v23, v202, v23, s[4:5]
	v_cndmask_b32_e64 v27, v202, v27, s[4:5]
	v_cndmask_b32_e64 v30, v202, v30, s[4:5]
	v_cndmask_b32_e64 v31, v202, v31, s[4:5]
	v_cndmask_b32_e64 v32, v202, v32, s[4:5]
	v_cndmask_b32_e64 v24, v202, v24, s[4:5]
	v_cndmask_b32_e64 v26, v202, v26, s[4:5]
	v_cndmask_b32_e64 v33, v202, v33, s[4:5]
	v_cndmask_b32_e64 v25, v202, v25, s[4:5]
	v_and_or_b32 v6, v6, s29, v102
	v_and_or_b32 v7, v7, s29, v168
	v_and_or_b32 v10, v10, s29, v169
	v_and_or_b32 v11, v11, s29, v170
	v_and_or_b32 v13, v13, s29, v171
	v_and_or_b32 v16, v16, s29, v172
	v_and_or_b32 v17, v17, s29, v173
	v_and_or_b32 v19, v19, s29, v174
	v_and_or_b32 v20, v20, s29, v175
	v_and_or_b32 v5, v5, s29, v176
	v_and_or_b32 v14, v14, s29, v177
	v_and_or_b32 v2, v2, s29, v178
	v_and_or_b32 v3, v3, s29, v179
	v_and_or_b32 v4, v4, s29, v180
	v_and_or_b32 v8, v8, s29, v181
	v_and_or_b32 v9, v9, s29, v182
	v_and_or_b32 v12, v12, s29, v183
	v_and_or_b32 v15, v15, s29, v184
	v_or_b32_e32 v18, v18, v185
	v_or_b32_e32 v21, v21, v187
	v_or_b32_e32 v22, v22, v188
	v_or_b32_e32 v28, v28, v189
	v_or_b32_e32 v29, v29, v190
	v_or_b32_e32 v23, v23, v191
	v_or_b32_e32 v27, v27, v192
	v_or_b32_e32 v30, v30, v193
	v_or_b32_e32 v31, v31, v194
	v_or_b32_e32 v32, v32, v195
	v_or_b32_e32 v24, v24, v196
	v_or_b32_e32 v26, v26, v197
	v_or_b32_e32 v33, v33, v198
	v_or_b32_e32 v25, v25, v199
	v_max_f32_e32 v34, v6, v4
	v_min_f32_e32 v4, v6, v4
	v_max_f32_e32 v6, v7, v7
	v_max_f32_e32 v42, v12, v26
	v_min_f32_e32 v12, v12, v26
	v_max_f32_e32 v26, v15, v24
	v_min_f32_e32 v15, v15, v24
	v_max_f32_e32 v24, v25, v25
	v_max_f32_e32 v7, v6, v3
	v_min_f32_e32 v3, v6, v3
	v_max_f32_e32 v6, v9, v9
	v_max_f32_e32 v9, v10, v10
	v_max_f32_e32 v25, v18, v24
	v_min_f32_e32 v18, v18, v24
	v_max_f32_e32 v24, v33, v33
	v_max_f32_e32 v10, v9, v6
	v_min_f32_e32 v6, v9, v6
	v_max_f32_e32 v9, v11, v11
	v_max_f32_e32 v33, v21, v24
	v_min_f32_e32 v21, v21, v24
	v_max_f32_e32 v24, v27, v27
	v_max_f32_e32 v11, v9, v8
	v_min_f32_e32 v8, v9, v8
	v_max_f32_e32 v9, v20, v20
	v_max_f32_e32 v27, v22, v24
	v_min_f32_e32 v22, v22, v24
	v_max_f32_e32 v24, v29, v29
	v_max_f32_e32 v20, v13, v9
	v_min_f32_e32 v9, v13, v9
	v_max_f32_e32 v13, v17, v17
	v_max_f32_e32 v29, v28, v24
	v_min_f32_e32 v24, v28, v24
	v_max_f32_e32 v28, v32, v32
	v_max_f32_e32 v17, v16, v13
	v_min_f32_e32 v13, v16, v13
	v_max_f32_e32 v16, v19, v19
	v_max_f32_e32 v32, v23, v28
	v_min_f32_e32 v23, v23, v28
	v_max_f32_e32 v28, v31, v31
	v_max_f32_e32 v19, v16, v2
	v_min_f32_e32 v2, v16, v2
	v_max_f32_e32 v16, v5, v14
	v_min_f32_e32 v5, v5, v14
	v_max_f32_e32 v31, v30, v28
	v_min_f32_e32 v28, v30, v28
	v_max_f32_e32 v14, v34, v17
	v_min_f32_e32 v17, v34, v17
	v_max_f32_e32 v34, v7, v19
	v_min_f32_e32 v7, v7, v19
	v_max_f32_e32 v19, v10, v16
	v_min_f32_e32 v10, v10, v16
	v_max_f32_e32 v16, v11, v20
	v_min_f32_e32 v11, v11, v20
	v_max_f32_e32 v20, v13, v4
	v_min_f32_e32 v4, v13, v4
	v_max_f32_e32 v13, v9, v8
	v_min_f32_e32 v8, v9, v8
	v_max_f32_e32 v9, v5, v6
	v_min_f32_e32 v5, v5, v6
	v_max_f32_e32 v6, v2, v3
	v_min_f32_e32 v2, v2, v3
	v_max_f32_e32 v30, v42, v29
	v_min_f32_e32 v29, v42, v29
	v_max_f32_e32 v42, v26, v32
	v_min_f32_e32 v26, v26, v32
	v_max_f32_e32 v32, v25, v31
	v_min_f32_e32 v25, v25, v31
	v_max_f32_e32 v31, v33, v27
	v_min_f32_e32 v27, v33, v27
	v_max_f32_e32 v33, v24, v12
	v_min_f32_e32 v12, v24, v12
	v_max_f32_e32 v24, v22, v21
	v_min_f32_e32 v21, v22, v21
	v_max_f32_e32 v22, v28, v18
	v_min_f32_e32 v18, v28, v18
	v_max_f32_e32 v28, v23, v15
	v_min_f32_e32 v15, v23, v15
	v_max_f32_e32 v3, v14, v34
	v_min_f32_e32 v14, v14, v34
	v_max_f32_e32 v34, v19, v16
	v_min_f32_e32 v16, v19, v16
	v_max_f32_e32 v19, v11, v17
	v_min_f32_e32 v11, v11, v17
	v_max_f32_e32 v17, v20, v13
	v_min_f32_e32 v13, v20, v13
	v_max_f32_e32 v20, v7, v10
	v_min_f32_e32 v7, v7, v10
	v_max_f32_e32 v10, v9, v6
	v_min_f32_e32 v6, v9, v6
	v_max_f32_e32 v9, v2, v4
	v_min_f32_e32 v2, v2, v4
	v_max_f32_e32 v4, v8, v5
	v_min_f32_e32 v5, v8, v5
	v_max_f32_e32 v23, v30, v42
	v_min_f32_e32 v30, v30, v42
	v_max_f32_e32 v42, v32, v31
	v_min_f32_e32 v31, v32, v31
	v_max_f32_e32 v32, v27, v29
	v_min_f32_e32 v27, v27, v29
	v_max_f32_e32 v29, v33, v24
	v_min_f32_e32 v24, v33, v24
	v_max_f32_e32 v33, v26, v25
	v_min_f32_e32 v25, v26, v25
	v_max_f32_e32 v26, v22, v28
	v_min_f32_e32 v22, v22, v28
; __device__ __forceinline__ void phase_topk_fast(LAS unsigned char* lds, const bf16* Q, const bf16* keysb  , int* EID, float* GATE, bool prestaged  ) {
;     ...
;             bsort16_desc<0, 32>(ck); bsort16_desc<16, 32>(ck);
;             merge_top16<0, 16, 32>(ck);
;             { float ok[16];
; #pragma unroll
;               for (int i = 0; i < 16; ++i) ok[i] = __shfl_xor(ck[i], 32);
	v_max_f32_e32 v28, v15, v12
	v_min_f32_e32 v12, v15, v12
	v_max_f32_e32 v15, v21, v18
	v_min_f32_e32 v18, v21, v18
	v_min_f32_e32 v8, v3, v34
	v_max_f32_e32 v35, v14, v16
	v_min_f32_e32 v14, v14, v16
	v_max_f32_e32 v16, v19, v10
	v_min_f32_e32 v10, v19, v10
	v_max_f32_e32 v19, v11, v6
	v_min_f32_e32 v6, v11, v6
	v_max_f32_e32 v11, v17, v20
	v_min_f32_e32 v17, v17, v20
	v_max_f32_e32 v20, v13, v7
	v_min_f32_e32 v7, v13, v7
	v_max_f32_e32 v13, v9, v4
	v_min_f32_e32 v4, v9, v4
	v_max_f32_e32 v9, v2, v5
	v_min_f32_e32 v21, v23, v42
	v_max_f32_e32 v43, v30, v31
	v_min_f32_e32 v30, v30, v31
	v_max_f32_e32 v31, v32, v26
	v_min_f32_e32 v26, v32, v26
	v_max_f32_e32 v32, v27, v22
	v_min_f32_e32 v22, v27, v22
	v_max_f32_e32 v27, v29, v33
	v_min_f32_e32 v29, v29, v33
	v_max_f32_e32 v33, v24, v25
	v_min_f32_e32 v24, v24, v25
	v_max_f32_e32 v25, v28, v15
	v_min_f32_e32 v15, v28, v15
	v_max_f32_e32 v28, v12, v18
	v_min_f32_e32 v2, v2, v5
	v_max_f32_e32 v5, v35, v8
	v_min_f32_e32 v8, v35, v8
	v_max_f32_e32 v35, v14, v13
	v_min_f32_e32 v13, v14, v13
	v_max_f32_e32 v14, v16, v11
	v_min_f32_e32 v11, v16, v11
	v_max_f32_e32 v16, v19, v17
	v_min_f32_e32 v17, v19, v17
	v_max_f32_e32 v19, v20, v10
	v_min_f32_e32 v10, v20, v10
	v_max_f32_e32 v20, v7, v6
	v_min_f32_e32 v6, v7, v6
	v_max_f32_e32 v7, v9, v4
	v_min_f32_e32 v12, v12, v18
	v_max_f32_e32 v18, v43, v21
	v_min_f32_e32 v21, v43, v21
	v_max_f32_e32 v43, v30, v25
	v_min_f32_e32 v25, v30, v25
	v_max_f32_e32 v30, v31, v27
	v_min_f32_e32 v27, v31, v27
	v_max_f32_e32 v31, v32, v29
	v_min_f32_e32 v29, v32, v29
	v_max_f32_e32 v32, v33, v26
	v_min_f32_e32 v26, v33, v26
	v_max_f32_e32 v33, v24, v22
	v_min_f32_e32 v22, v24, v22
	v_max_f32_e32 v24, v28, v15
	v_min_f32_e32 v4, v9, v4
	v_max_f32_e32 v36, v8, v11
	v_min_f32_e32 v8, v8, v11
	v_max_f32_e32 v11, v16, v19
	v_min_f32_e32 v16, v16, v19
	v_max_f32_e32 v19, v17, v10
	v_min_f32_e32 v10, v17, v10
	v_max_f32_e32 v17, v20, v7
	v_min_f32_e32 v15, v28, v15
	v_max_f32_e32 v44, v21, v27
	v_min_f32_e32 v21, v21, v27
	v_max_f32_e32 v27, v31, v32
	v_min_f32_e32 v31, v31, v32
	v_max_f32_e32 v32, v29, v26
	v_min_f32_e32 v26, v29, v26
	v_max_f32_e32 v29, v33, v24
	v_min_f32_e32 v7, v20, v7
	v_max_f32_e32 v20, v6, v4
	v_max_f32_e32 v37, v35, v8
	v_min_f32_e32 v8, v35, v8
	v_max_f32_e32 v35, v17, v13
	v_min_f32_e32 v13, v17, v13
	v_min_f32_e32 v24, v33, v24
	v_max_f32_e32 v33, v22, v15
	v_max_f32_e32 v45, v43, v21
	v_min_f32_e32 v21, v43, v21
	v_max_f32_e32 v43, v29, v25
	v_min_f32_e32 v25, v29, v25
	v_min_f32_e32 v9, v5, v14
	v_max_f32_e32 v17, v20, v7
	v_min_f32_e32 v7, v20, v7
	v_max_f32_e32 v20, v37, v11
	v_min_f32_e32 v11, v37, v11
	v_max_f32_e32 v37, v8, v16
	v_min_f32_e32 v8, v8, v16
	v_max_f32_e32 v16, v19, v35
	v_min_f32_e32 v19, v19, v35
	v_max_f32_e32 v35, v10, v13
	v_min_f32_e32 v28, v18, v30
	v_max_f32_e32 v29, v33, v24
	v_min_f32_e32 v24, v33, v24
	v_max_f32_e32 v33, v45, v27
	v_min_f32_e32 v27, v45, v27
	v_max_f32_e32 v45, v21, v31
	v_min_f32_e32 v21, v21, v31
	v_max_f32_e32 v31, v32, v43
	v_min_f32_e32 v32, v32, v43
	v_max_f32_e32 v43, v26, v25
	v_min_f32_e32 v4, v6, v4
	v_min_f32_e32 v6, v36, v9
	v_min_f32_e32 v10, v10, v13
	v_min_f32_e32 v38, v11, v37
	v_max_f32_e32 v39, v16, v8
	v_min_f32_e32 v8, v16, v8
	v_max_f32_e32 v16, v19, v35
	v_min_f32_e32 v15, v22, v15
	v_min_f32_e32 v22, v44, v28
	v_min_f32_e32 v25, v26, v25
	v_min_f32_e32 v46, v27, v45
	v_max_f32_e32 v47, v31, v21
	v_min_f32_e32 v21, v31, v21
	v_max_f32_e32 v31, v32, v43
	v_min_f32_e32 v13, v20, v6
	v_min_f32_e32 v19, v19, v35
	v_min_f32_e32 v35, v17, v10
	v_min_f32_e32 v40, v38, v39
	v_min_f32_e32 v41, v8, v16
	v_min_f32_e32 v26, v33, v22
	v_min_f32_e32 v32, v32, v43
	v_min_f32_e32 v43, v29, v25
	v_min_f32_e32 v48, v46, v47
	v_min_f32_e32 v49, v21, v31
	v_max3_f32 v3, v3, v34, v12
	v_max3_f32 v5, v5, v14, v15
	v_max3_f32 v9, v36, v9, v24
	v_max3_f32 v6, v20, v6, v43
	v_max3_f32 v12, v13, v29, v25
	v_max3_f32 v11, v11, v37, v32
	v_max3_f32 v13, v38, v39, v49
	v_max3_f32 v14, v40, v21, v31
	v_max3_f32 v8, v8, v16, v48
	v_max3_f32 v15, v41, v46, v47
	v_max3_f32 v16, v19, v27, v45
	v_max3_f32 v10, v17, v10, v26
	v_max3_f32 v17, v35, v33, v22
	v_max3_f32 v7, v7, v44, v28
	v_max3_f32 v4, v4, v18, v30
	v_max3_f32 v2, v2, v23, v42
	v_max_f32_e32 v18, v3, v8
	v_min_f32_e32 v3, v3, v8
	v_max_f32_e32 v8, v5, v15
	v_min_f32_e32 v5, v5, v15
	v_max_f32_e32 v15, v9, v16
	v_min_f32_e32 v9, v9, v16
	v_max_f32_e32 v16, v6, v10
	v_min_f32_e32 v6, v6, v10
	v_max_f32_e32 v10, v12, v17
	v_min_f32_e32 v12, v12, v17
	v_max_f32_e32 v17, v11, v7
	v_min_f32_e32 v7, v11, v7
	v_max_f32_e32 v11, v13, v4
	v_min_f32_e32 v4, v13, v4
	v_max_f32_e32 v13, v14, v2
	v_min_f32_e32 v2, v14, v2
	v_max_f32_e32 v14, v18, v10
	v_min_f32_e32 v10, v18, v10
	v_max_f32_e32 v18, v8, v17
	v_min_f32_e32 v8, v8, v17
	v_max_f32_e32 v17, v15, v11
	v_min_f32_e32 v11, v15, v11
	v_max_f32_e32 v15, v16, v13
	v_min_f32_e32 v13, v16, v13
	v_max_f32_e32 v16, v3, v12
	v_min_f32_e32 v3, v3, v12
	v_max_f32_e32 v12, v5, v7
	v_min_f32_e32 v5, v5, v7
	v_max_f32_e32 v7, v9, v4
	v_min_f32_e32 v4, v9, v4
	v_max_f32_e32 v9, v6, v2
	v_min_f32_e32 v2, v6, v2
	v_max_f32_e32 v6, v14, v17
	v_min_f32_e32 v14, v14, v17
	v_max_f32_e32 v17, v18, v15
	v_min_f32_e32 v15, v18, v15
	v_max_f32_e32 v18, v10, v11
	v_min_f32_e32 v10, v10, v11
	v_max_f32_e32 v11, v8, v13
	v_min_f32_e32 v13, v8, v13
	v_max_f32_e32 v19, v16, v7
	v_min_f32_e32 v21, v16, v7
	v_max_f32_e32 v20, v12, v9
	v_min_f32_e32 v9, v12, v9
	v_max_f32_e32 v24, v3, v4
	v_min_f32_e32 v4, v3, v4
	v_max_f32_e32 v26, v5, v2
	v_min_f32_e32 v5, v5, v2
	v_max_f32_e32 v23, v6, v17
	v_min_f32_e32 v8, v6, v17
	v_max_f32_e32 v16, v14, v15
	v_min_f32_e32 v3, v14, v15
	v_max_f32_e32 v22, v18, v11
	v_min_f32_e32 v7, v18, v11
	v_max_f32_e32 v15, v10, v13
	v_min_f32_e32 v2, v10, v13
	v_max_f32_e32 v28, v19, v20
	v_min_f32_e32 v12, v19, v20
	v_max_f32_e32 v20, v21, v9
	v_min_f32_e32 v6, v21, v9
	v_max_f32_e32 v25, v24, v26
	v_min_f32_e32 v9, v24, v26
	v_max_f32_e32 v17, v4, v5
	v_min_f32_e32 v4, v4, v5
	ds_bpermute_b32 v5, v203, v23
	ds_bpermute_b32 v21, v203, v8
	ds_bpermute_b32 v13, v203, v16
	ds_bpermute_b32 v29, v203, v3
	ds_bpermute_b32 v10, v203, v22
	ds_bpermute_b32 v26, v203, v7
	ds_bpermute_b32 v18, v203, v15
	ds_bpermute_b32 v31, v203, v2
	ds_bpermute_b32 v11, v203, v28
	ds_bpermute_b32 v27, v203, v12
	ds_bpermute_b32 v19, v203, v20
	ds_bpermute_b32 v32, v203, v6
	ds_bpermute_b32 v14, v203, v25
	ds_bpermute_b32 v30, v203, v9
	ds_bpermute_b32 v24, v203, v17
	ds_bpermute_b32 v33, v203, v4
	s_and_saveexec_b64 s[18:19], s[4:5]
	s_cbranch_execz .LBB0_843
; #define GAS __attribute__((address_space(1)))
; __device__ __forceinline__ void phase_topk_fast(LAS unsigned char* lds, const bf16* Q, const bf16* keysb  , int* EID, float* GATE, bool prestaged  ) {
;     ...
;             { float ok[16];
; #pragma unroll
;               for (int i = 0; i < 16; ++i) ok[i] = __shfl_xor(ck[i], 32);
; #pragma unroll
;               for (int i = 0; i < 16; ++i) ck[i] = fmaxf(ck[i], ok[15 - i]); }
;             bmerge16_desc<0, 32>(ck);
;             int cp[16];
; #pragma unroll
;             for (int i = 0; i < 16; ++i) { const unsigned u = __float_as_uint(ck[i]); cp[i] = etab[u & 63u]; ck[i] = __uint_as_float(u & ~63u); }
;             float ex[16]; float sum = 0.f;
; #pragma unroll
;             for (int i = 0; i < 16; ++i) { ex[i] = __expf(ck[i] - ck[0]); sum += ex[i]; }
;             const float inv = 1.f / sum;
;             if (hh == 0) {
;                 int* eo = EID + (tok0 + c) * 128 + h * 16; float* go = GATE + (tok0 + c) * 128 + h * 16;
; #pragma unroll
;                 for (int i = 0; i < 4; ++i) { *(GAS v4u*)(eo + 4 * i) = (v4u){(unsigned)cp[4 * i], (unsigned)cp[4 * i + 1], (unsigned)cp[4 * i + 2], (unsigned)cp[4 * i + 3]};
;                     *(GAS f32x4*)(go + 4 * i) = (f32x4){ex[4 * i] * inv, ex[4 * i + 1] * inv, ex[4 * i + 2] * inv, ex[4 * i + 3] * inv}; }
	s_waitcnt lgkmcnt(1)
	s_waitcnt lgkmcnt(0)
	v_max_f32_e32 v8, v8, v24
	v_max_f32_e32 v12, v12, v18
	v_max_f32_e32 v7, v7, v19
	v_max_f32_e32 v9, v9, v13
	v_max_f32_e32 v3, v3, v14
	v_max_f32_e32 v6, v6, v10
	v_max_f32_e32 v2, v2, v11
	v_max_f32_e32 v4, v4, v5
	v_max_f32_e32 v23, v23, v33
	v_max_f32_e32 v28, v28, v31
	v_max_f32_e32 v22, v22, v32
	v_max_f32_e32 v25, v25, v29
	v_max_f32_e32 v16, v16, v30
	v_max_f32_e32 v20, v20, v26
	v_max_f32_e32 v15, v15, v27
	v_max_f32_e32 v17, v17, v21
	v_max_f32_e32 v18, v8, v12
	v_max_f32_e32 v13, v7, v9
	v_max_f32_e32 v10, v3, v6
	v_max_f32_e32 v5, v2, v4
	v_max_f32_e32 v31, v23, v28
	v_max_f32_e32 v29, v22, v25
	v_max_f32_e32 v26, v16, v20
	v_max_f32_e32 v21, v15, v17
	v_max_f32_e32 v19, v18, v13
	v_max_f32_e32 v11, v10, v5
	v_max_f32_e32 v32, v31, v29
	v_max_f32_e32 v27, v26, v21
	v_max_f32_e32 v14, v19, v11
	v_min_f32_e32 v11, v19, v11
	v_min_f32_e32 v19, v31, v29
	v_min_f32_e32 v21, v26, v21
	v_min_f32_e32 v13, v18, v13
	v_min_f32_e32 v5, v10, v5
	v_max_f32_e32 v30, v32, v27
	v_max_f32_e32 v10, v13, v5
	v_min_f32_e32 v18, v19, v21
	v_min_f32_e32 v5, v13, v5
	v_max_f32_e32 v35, v30, v14
	v_min_f32_e32 v14, v30, v14
	v_max_f32_e32 v13, v18, v5
	v_min_f32_e32 v30, v18, v5
	v_min_f32_e32 v5, v23, v28
	v_min_f32_e32 v18, v22, v25
	v_min_f32_e32 v16, v16, v20
	v_min_f32_e32 v15, v15, v17
	v_min_f32_e32 v8, v8, v12
	v_min_f32_e32 v7, v7, v9
	v_min_f32_e32 v3, v3, v6
	v_min_f32_e32 v2, v2, v4
	v_max_f32_e32 v26, v19, v21
	v_max_f32_e32 v19, v5, v18
	v_max_f32_e32 v17, v16, v15
	v_max_f32_e32 v9, v8, v7
	v_max_f32_e32 v4, v3, v2
	v_min_f32_e32 v5, v5, v18
	v_min_f32_e32 v15, v16, v15
	v_min_f32_e32 v7, v8, v7
	v_min_f32_e32 v2, v3, v2
	v_max_f32_e32 v16, v5, v15
	v_max_f32_e32 v3, v7, v2
	v_min_f32_e32 v5, v5, v15
	v_min_f32_e32 v2, v7, v2
	v_max_f32_e32 v7, v5, v2
	v_min_f32_e32 v2, v5, v2
	v_max_f32_e32 v8, v16, v3
	v_min_f32_e32 v3, v16, v3
	v_and_b32_e32 v16, 0xffffffc0, v35
	v_and_b32_e32 v5, 0xffffffc0, v2
	v_sub_f32_e32 v5, v5, v16
	v_mul_f32_e32 v5, 0x3fb8aa3b, v5
	v_and_b32_e32 v15, 0xffffffc0, v7
	v_exp_f32_e32 v21, v5
	v_and_b32_e32 v5, 63, v7
	v_sub_f32_e32 v15, v15, v16
	v_lshl_add_u32 v7, v5, 2, v167
	v_and_b32_e32 v5, 0xffffffc0, v8
	v_max_f32_e32 v20, v19, v17
	v_max_f32_e32 v6, v9, v4
	v_mul_f32_e32 v15, 0x3fb8aa3b, v15
	v_sub_f32_e32 v5, v5, v16
	v_max_f32_e32 v12, v20, v6
	v_min_f32_e32 v6, v20, v6
	v_exp_f32_e32 v20, v15
	v_and_b32_e32 v15, 0xffffffc0, v3
	v_mul_f32_e32 v5, 0x3fb8aa3b, v5
	v_exp_f32_e32 v22, v5
	v_sub_f32_e32 v5, v15, v16
	v_min_f32_e32 v17, v19, v17
	v_min_f32_e32 v4, v9, v4
	v_mul_f32_e32 v5, 0x3fb8aa3b, v5
	v_max_f32_e32 v9, v17, v4
	v_exp_f32_e32 v23, v5
	v_and_b32_e32 v5, 63, v8
	v_lshl_add_u32 v8, v5, 2, v167
	v_and_b32_e32 v5, 0xffffffc0, v9
	v_min_f32_e32 v4, v17, v4
	v_sub_f32_e32 v17, v16, v16
	v_sub_f32_e32 v5, v5, v16
	v_and_b32_e32 v24, 0xffffffc0, v14
	v_mul_f32_e32 v17, 0x3fb8aa3b, v17
	v_and_b32_e32 v15, 0xffffffc0, v4
	v_mul_f32_e32 v5, 0x3fb8aa3b, v5
	v_exp_f32_e32 v18, v17
	v_sub_f32_e32 v17, v24, v16
	v_exp_f32_e32 v24, v5
	v_sub_f32_e32 v5, v15, v16
	v_mul_f32_e32 v5, 0x3fb8aa3b, v5
	v_and_b32_e32 v4, 63, v4
	v_exp_f32_e32 v25, v5
	v_and_b32_e32 v5, 63, v9
	v_lshl_add_u32 v9, v4, 2, v167
	v_and_b32_e32 v4, 0xffffffc0, v12
	v_sub_f32_e32 v4, v4, v16
	v_lshl_add_u32 v15, v5, 2, v167
	v_and_b32_e32 v5, 0xffffffc0, v6
	v_mul_f32_e32 v4, 0x3fb8aa3b, v4
	v_max_f32_e32 v34, v26, v10
	v_min_f32_e32 v10, v26, v10
	v_exp_f32_e32 v26, v4
	v_sub_f32_e32 v4, v5, v16
	v_min_f32_e32 v27, v32, v27
	v_mul_f32_e32 v4, 0x3fb8aa3b, v4
	v_max_f32_e32 v36, v27, v11
	v_min_f32_e32 v11, v27, v11
	v_and_b32_e32 v2, 63, v2
	v_and_b32_e32 v3, 63, v3
	v_exp_f32_e32 v27, v4
	v_and_b32_e32 v4, 63, v12
	v_and_b32_e32 v5, 63, v6
	v_lshl_add_u32 v2, v2, 2, v167
	v_lshl_add_u32 v3, v3, 2, v167
	v_lshl_add_u32 v6, v5, 2, v167
	v_lshl_add_u32 v12, v4, 2, v167
	ds_read_b32 v5, v2
	ds_read_b32 v4, v7
	ds_read_b32 v3, v3
	ds_read_b32 v2, v8
	ds_read_b32 v9, v9
	ds_read_b32 v8, v15
	ds_read_b32 v7, v6
	ds_read_b32 v6, v12
	v_and_b32_e32 v12, 0xffffffc0, v13
	v_sub_f32_e32 v12, v12, v16
	v_and_b32_e32 v15, 0xffffffc0, v30
	v_mul_f32_e32 v12, 0x3fb8aa3b, v12
	v_exp_f32_e32 v28, v12
	v_sub_f32_e32 v12, v15, v16
	v_and_b32_e32 v15, 0xffffffc0, v34
	v_sub_f32_e32 v15, v15, v16
	v_mul_f32_e32 v12, 0x3fb8aa3b, v12
	v_and_b32_e32 v31, 0xffffffc0, v10
	v_mul_f32_e32 v15, 0x3fb8aa3b, v15
	v_exp_f32_e32 v29, v12
	v_and_b32_e32 v12, 63, v13
	v_and_b32_e32 v13, 63, v30
	v_exp_f32_e32 v30, v15
	v_sub_f32_e32 v15, v31, v16
	v_and_b32_e32 v31, 0xffffffc0, v36
	v_mul_f32_e32 v17, 0x3fb8aa3b, v17
	v_and_b32_e32 v33, 0xffffffc0, v11
	v_sub_f32_e32 v31, v31, v16
	v_exp_f32_e32 v19, v17
	v_mul_f32_e32 v31, 0x3fb8aa3b, v31
	v_sub_f32_e32 v16, v33, v16
	v_exp_f32_e32 v32, v31
	v_mul_f32_e32 v16, 0x3fb8aa3b, v16
	v_exp_f32_e32 v33, v16
	v_add_f32_e32 v17, 0, v18
	v_mul_f32_e32 v15, 0x3fb8aa3b, v15
	v_add_f32_e32 v17, v19, v17
	v_exp_f32_e32 v31, v15
	v_add_f32_e32 v16, v32, v17
	v_add_f32_e32 v16, v33, v16
	v_add_f32_e32 v16, v30, v16
	v_add_f32_e32 v16, v31, v16
	v_add_f32_e32 v16, v28, v16
	v_add_f32_e32 v16, v29, v16
	v_add_f32_e32 v16, v26, v16
	v_add_f32_e32 v16, v27, v16
	v_add_f32_e32 v16, v24, v16
	v_add_f32_e32 v16, v25, v16
	v_add_f32_e32 v16, v22, v16
	v_add_f32_e32 v16, v23, v16
	v_add_f32_e32 v16, v20, v16
	v_add_f32_e32 v16, v21, v16
	v_div_scale_f32 v17, s[34:35], v16, v16, 1.0
	v_and_b32_e32 v15, 63, v34
	v_rcp_f32_e32 v34, v17
	v_and_b32_e32 v11, 63, v11
	v_and_b32_e32 v10, 63, v10
	v_lshl_add_u32 v13, v13, 2, v167
	v_fma_f32 v37, -v17, v34, 1.0
	v_fmac_f32_e32 v34, v37, v34
	v_div_scale_f32 v37, vcc, 1.0, v16, 1.0
	v_mul_f32_e32 v38, v37, v34
	v_fma_f32 v39, -v17, v38, v37
	v_fmac_f32_e32 v38, v39, v34
	v_fma_f32 v17, -v17, v38, v37
	v_div_fmas_f32 v17, v17, v34, v38
	v_div_fixup_f32 v34, v17, v16, 1.0
	v_and_b32_e32 v16, 63, v36
	v_lshl_add_u32 v17, v11, 2, v167
	v_and_b32_e32 v11, 63, v14
	v_lshl_add_u32 v12, v12, 2, v167
	v_lshl_add_u32 v10, v10, 2, v167
	v_lshl_add_u32 v15, v15, 2, v167
	v_lshl_add_u32 v16, v16, 2, v167
	v_lshl_add_u32 v14, v11, 2, v167
	v_and_b32_e32 v11, 63, v35
	v_lshl_add_u32 v35, v11, 2, v167
	ds_read_b32 v13, v13
	ds_read_b32 v12, v12
	ds_read_b32 v11, v10
	ds_read_b32 v10, v15
	ds_read_b32 v17, v17
	ds_read_b32 v16, v16
	ds_read_b32 v15, v14
	ds_read_b32 v14, v35
	s_lshl_b64 s[34:35], s[16:17], 14
	v_lshl_or_b32 v36, v100, 2, s34
	v_mov_b32_e32 v37, s35
	v_lshl_add_u64 v[38:39], s[12:13], 0, v[36:37]
	v_lshl_add_u64 v[36:37], s[14:15], 0, v[36:37]
	s_waitcnt lgkmcnt(0)
; #define GAS __attribute__((address_space(1)))
; __device__ __forceinline__ void phase_topk_fast(LAS unsigned char* lds, const bf16* Q, const bf16* keysb  , int* EID, float* GATE, bool prestaged  ) {
;     ...
;             if (hh == 0) {
;                 int* eo = EID + (tok0 + c) * 128 + h * 16; float* go = GATE + (tok0 + c) * 128 + h * 16;
; #pragma unroll
;                 for (int i = 0; i < 4; ++i) { *(GAS v4u*)(eo + 4 * i) = (v4u){(unsigned)cp[4 * i], (unsigned)cp[4 * i + 1], (unsigned)cp[4 * i + 2], (unsigned)cp[4 * i + 3]};
;                     *(GAS f32x4*)(go + 4 * i) = (f32x4){ex[4 * i] * inv, ex[4 * i + 1] * inv, ex[4 * i + 2] * inv, ex[4 * i + 3] * inv}; }
	global_store_dwordx4 v[38:39], v[14:17], off
	s_nop 1
	v_pk_mul_f32 v[16:17], v[32:33], v[34:35] op_sel_hi:[1,0]
	v_pk_mul_f32 v[14:15], v[18:19], v[34:35] op_sel_hi:[1,0]
	global_store_dwordx4 v[36:37], v[14:17], off
	global_store_dwordx4 v[38:39], v[10:13], off offset:16
	s_nop 1
	v_pk_mul_f32 v[12:13], v[28:29], v[34:35] op_sel_hi:[1,0]
	v_pk_mul_f32 v[10:11], v[30:31], v[34:35] op_sel_hi:[1,0]
	global_store_dwordx4 v[36:37], v[10:13], off offset:16
	global_store_dwordx4 v[38:39], v[6:9], off offset:32
	s_nop 1
	v_pk_mul_f32 v[8:9], v[24:25], v[34:35] op_sel_hi:[1,0]
	v_pk_mul_f32 v[6:7], v[26:27], v[34:35] op_sel_hi:[1,0]
	global_store_dwordx4 v[36:37], v[6:9], off offset:32
	global_store_dwordx4 v[38:39], v[2:5], off offset:48
	s_nop 1
	v_pk_mul_f32 v[4:5], v[20:21], v[34:35] op_sel_hi:[1,0]
	v_pk_mul_f32 v[2:3], v[22:23], v[34:35] op_sel_hi:[1,0]
	global_store_dwordx4 v[36:37], v[2:5], off offset:48
	s_branch .LBB0_843

; #define GAS __attribute__((address_space(1)))
; #define LAS __attribute__((address_space(3)))
; __device__ __forceinline__ void phase_topk_fast(LAS unsigned char* lds, const bf16* Q, const bf16* keysb  , int* EID, float* GATE, bool prestaged  ) {
;     ...
;                 for (int blk = 0; blk < 4; ++blk) {
; #pragma unroll
;                     for (int r = 0; r < 16; ++r) acc[blk][r] = 0.f;
; #pragma unroll
;                     for (int ks = 0; ks < 8; ++ks) { const bf16x8 a = *(const LAS bf16x8*)(lds + (p * 128 + 32 * blk + c) * 272 + (16 * ks + 8 * hh) * 2);
;                         acc[blk] = __builtin_amdgcn_mfma_f32_32x32x16_bf16(a, bq[ks], acc[blk], 0, 0, 0); }
;                 }
;                 __builtin_amdgcn_sched_barrier(0);
;                 { const int nit = (p == 0) ? it : it + 1; const int np = (p == 0) ? 1 : 0;
;                   const size_t ntok0 = (size_t)(rank * 8 + wave + 256 * (nit < 4 ? nit : 3)) * 32;
;                   int cq = c; asm volatile("" : "+v"(cq)); const bf16* qrow = Q + (ntok0 + cq) * 2048 + h * 256 + np * 128 + 8 * hh;
; #pragma unroll
;                   for (int ks = 0; ks < 8; ++ks) bq[ks] = *(const GAS bf16x8*)(qrow + 16 * ks); }
;                 __builtin_amdgcn_sched_barrier(0);
;                 float v[64];
; #pragma unroll
;                 for (int blk = 0; blk < 4; ++blk)
; #pragma unroll
;                     for (int r = 0; r < 16; ++r)
;                     { const float sv = acc[blk][r]; v[blk * 16 + r] = __uint_as_float((__float_as_uint(sv) & ~127u) | (unsigned)(32 * blk + (r & 3) + 8 * (r >> 2)) | (unsigned)(hh << 2)); }
.LBB0_1810:
	s_waitcnt lgkmcnt(14)
	ds_read_b128 v[2:5], v103
	s_waitcnt lgkmcnt(6)
	ds_read_b128 v[18:21], v103 offset:32
	s_waitcnt vmcnt(7) lgkmcnt(1)
	v_mfma_f32_32x32x16_bf16 v[2:17], v[2:5], v[90:93], 0
	s_waitcnt vmcnt(6) lgkmcnt(0)
	v_mfma_f32_32x32x16_bf16 v[2:17], v[18:21], v[94:97], v[2:17]
	ds_read_b128 v[18:21], v103 offset:64
	ds_read_b128 v[22:25], v103 offset:96
	s_waitcnt vmcnt(5) lgkmcnt(1)
	v_mfma_f32_32x32x16_bf16 v[2:17], v[18:21], v[82:85], v[2:17]
	s_waitcnt vmcnt(4) lgkmcnt(0)
	v_mfma_f32_32x32x16_bf16 v[2:17], v[22:25], v[86:89], v[2:17]
	ds_read_b128 v[18:21], v103 offset:128
	ds_read_b128 v[22:25], v103 offset:160
	s_waitcnt vmcnt(3) lgkmcnt(1)
	v_mfma_f32_32x32x16_bf16 v[2:17], v[18:21], v[74:77], v[2:17]
	s_waitcnt vmcnt(2) lgkmcnt(0)
	v_mfma_f32_32x32x16_bf16 v[2:17], v[22:25], v[78:81], v[2:17]
	ds_read_b128 v[18:21], v103 offset:192
	ds_read_b128 v[22:25], v103 offset:224
	s_waitcnt vmcnt(1) lgkmcnt(1)
	v_mfma_f32_32x32x16_bf16 v[2:17], v[18:21], v[66:69], v[2:17]
	ds_read_b128 v[18:21], v103 offset:8704
	ds_read_b128 v[34:37], v103 offset:8736
	s_waitcnt vmcnt(0) lgkmcnt(2)
	v_mfma_f32_32x32x16_bf16 v[2:17], v[22:25], v[70:73], v[2:17]
	s_waitcnt lgkmcnt(1)
	v_mfma_f32_32x32x16_bf16 v[18:33], v[18:21], v[90:93], 0
	s_waitcnt lgkmcnt(0)
	v_mfma_f32_32x32x16_bf16 v[18:33], v[34:37], v[94:97], v[18:33]
	ds_read_b128 v[34:37], v103 offset:8768
	ds_read_b128 v[38:41], v103 offset:8800
	s_waitcnt lgkmcnt(1)
	v_mfma_f32_32x32x16_bf16 v[18:33], v[34:37], v[82:85], v[18:33]
	s_waitcnt lgkmcnt(0)
	v_mfma_f32_32x32x16_bf16 v[18:33], v[38:41], v[86:89], v[18:33]
	ds_read_b128 v[34:37], v103 offset:8832
	ds_read_b128 v[38:41], v103 offset:8864
	s_waitcnt lgkmcnt(1)
	v_mfma_f32_32x32x16_bf16 v[18:33], v[34:37], v[74:77], v[18:33]
	s_waitcnt lgkmcnt(0)
	v_mfma_f32_32x32x16_bf16 v[18:33], v[38:41], v[78:81], v[18:33]
	ds_read_b128 v[34:37], v103 offset:8896
	ds_read_b128 v[38:41], v103 offset:8928
	s_waitcnt lgkmcnt(1)
	v_mfma_f32_32x32x16_bf16 v[18:33], v[34:37], v[66:69], v[18:33]
	ds_read_b128 v[34:37], v103 offset:17408
	ds_read_b128 v[50:53], v103 offset:17440
	s_waitcnt lgkmcnt(2)
	v_mfma_f32_32x32x16_bf16 v[18:33], v[38:41], v[70:73], v[18:33]
	s_waitcnt lgkmcnt(1)
	v_mfma_f32_32x32x16_bf16 v[34:49], v[34:37], v[90:93], 0
	s_waitcnt lgkmcnt(0)
	v_mfma_f32_32x32x16_bf16 v[34:49], v[50:53], v[94:97], v[34:49]
	ds_read_b128 v[50:53], v103 offset:17472
	ds_read_b128 v[54:57], v103 offset:17504
	s_waitcnt lgkmcnt(1)
	v_mfma_f32_32x32x16_bf16 v[34:49], v[50:53], v[82:85], v[34:49]
	s_waitcnt lgkmcnt(0)
	v_mfma_f32_32x32x16_bf16 v[34:49], v[54:57], v[86:89], v[34:49]
	ds_read_b128 v[50:53], v103 offset:17536
	ds_read_b128 v[54:57], v103 offset:17568
	s_waitcnt lgkmcnt(1)
	v_mfma_f32_32x32x16_bf16 v[34:49], v[50:53], v[74:77], v[34:49]
	s_waitcnt lgkmcnt(0)
	v_mfma_f32_32x32x16_bf16 v[34:49], v[54:57], v[78:81], v[34:49]
	ds_read_b128 v[50:53], v103 offset:17600
	ds_read_b128 v[54:57], v103 offset:17632
	s_waitcnt lgkmcnt(1)
	v_mfma_f32_32x32x16_bf16 v[34:49], v[50:53], v[66:69], v[34:49]
	ds_read_b128 v[50:53], v103 offset:26112
	ds_read_b128 v[204:207], v103 offset:26144
	s_waitcnt lgkmcnt(2)
	v_mfma_f32_32x32x16_bf16 v[34:49], v[54:57], v[70:73], v[34:49]
	s_waitcnt lgkmcnt(1)
	v_mfma_f32_32x32x16_bf16 v[50:65], v[50:53], v[90:93], 0
	s_waitcnt lgkmcnt(0)
	v_mfma_f32_32x32x16_bf16 v[50:65], v[204:207], v[94:97], v[50:65]
	ds_read_b128 v[90:93], v103 offset:26176
	ds_read_b128 v[94:97], v103 offset:26208
	s_waitcnt lgkmcnt(1)
	v_mfma_f32_32x32x16_bf16 v[50:65], v[90:93], v[82:85], v[50:65]
	s_waitcnt lgkmcnt(0)
	v_mfma_f32_32x32x16_bf16 v[50:65], v[94:97], v[86:89], v[50:65]
	ds_read_b128 v[82:85], v103 offset:26240
	ds_read_b128 v[86:89], v103 offset:26272
	s_waitcnt lgkmcnt(1)
	v_mfma_f32_32x32x16_bf16 v[50:65], v[82:85], v[74:77], v[50:65]
	s_waitcnt lgkmcnt(0)
	v_mfma_f32_32x32x16_bf16 v[50:65], v[86:89], v[78:81], v[50:65]
	ds_read_b128 v[74:77], v103 offset:26304
	ds_read_b128 v[78:81], v103 offset:26336
	s_waitcnt lgkmcnt(1)
	v_mfma_f32_32x32x16_bf16 v[50:65], v[74:77], v[66:69], v[50:65]
	s_waitcnt lgkmcnt(0)
	v_mfma_f32_32x32x16_bf16 v[50:65], v[78:81], v[70:73], v[50:65]
	s_ashr_i32 s17, s16, 31
	v_mov_b32_e32 v66, v1
	s_lshl_b64 s[18:19], s[16:17], 17
	s_add_u32 s18, s20, s18
	v_ashrrev_i32_e32 v67, 31, v66
	s_addc_u32 s19, s21, s19
	v_lshlrev_b64 v[66:67], 12, v[66:67]
	v_lshl_add_u64 v[66:67], s[18:19], 0, v[66:67]
	v_lshl_add_u64 v[66:67], v[66:67], 0, s[6:7]
	v_lshl_add_u64 v[66:67], v[66:67], 0, v[98:99]
	global_load_dwordx4 v[94:97], v[66:67], off offset:256
	global_load_dwordx4 v[90:93], v[66:67], off offset:288
	global_load_dwordx4 v[86:89], v[66:67], off offset:320
	global_load_dwordx4 v[82:85], v[66:67], off offset:352
	global_load_dwordx4 v[78:81], v[66:67], off offset:384
	global_load_dwordx4 v[74:77], v[66:67], off offset:416
	global_load_dwordx4 v[70:73], v[66:67], off offset:448
	s_nop 0
	global_load_dwordx4 v[66:69], v[66:67], off offset:480
	v_and_or_b32 v2, v2, s28, v101
	v_and_or_b32 v3, v3, s28, v104
	v_and_or_b32 v4, v4, s28, v105
	v_and_or_b32 v5, v5, s28, v106
	v_and_or_b32 v6, v6, s28, v107
	v_and_or_b32 v7, v7, s28, v108
	v_and_or_b32 v8, v8, s28, v109
	v_and_or_b32 v9, v9, s28, v110
	v_and_or_b32 v10, v10, s28, v111
	v_and_or_b32 v11, v11, s28, v112
	v_and_or_b32 v12, v12, s28, v113
	v_and_or_b32 v13, v13, s28, v114
	v_and_or_b32 v14, v14, s28, v115
	v_and_or_b32 v15, v15, s28, v116
	v_and_or_b32 v16, v16, s28, v117
	v_and_or_b32 v17, v17, s28, v118
	v_and_or_b32 v18, v18, s28, v119
	v_and_or_b32 v19, v19, s28, v120
	v_and_or_b32 v20, v20, s28, v121
	v_and_or_b32 v21, v21, s28, v122
; #define CEF_D(a, b) { const float hi_ = fmaxf((a), (b)), lo_ = fminf((a), (b)); (a) = hi_; (b) = lo_; }
; template <int OFF, int NV> __device__ __forceinline__ void bsort16_desc(float (&v)[NV]) {
; #pragma unroll
;     for (int t = 0; t < 60; ++t) CEF_D(v[OFF + sn16_a(t)], v[OFF + sn16_b(t)])
; }
; __device__ __forceinline__ void phase_topk_fast(LAS unsigned char* lds, const bf16* Q, const bf16* keysb  , int* EID, float* GATE, bool prestaged  ) {
;     ...
;                     { const float sv = acc[blk][r]; v[blk * 16 + r] = __uint_as_float((__float_as_uint(sv) & ~127u) | (unsigned)(32 * blk + (r & 3) + 8 * (r >> 2)) | (unsigned)(hh << 2)); }
;                 __builtin_amdgcn_sched_barrier(0);
;                 bsort16_desc<0, 64>(v); bsort16_desc<16, 64>(v); bsort16_desc<32, 64>(v); bsort16_desc<48, 64>(v);
	v_and_or_b32 v22, v22, s28, v123
	v_and_or_b32 v23, v23, s28, v124
	v_and_or_b32 v24, v24, s28, v125
	v_and_or_b32 v25, v25, s28, v126
	v_and_or_b32 v26, v26, s28, v127
	v_and_or_b32 v27, v27, s28, v128
	v_and_or_b32 v28, v28, s28, v129
	v_and_or_b32 v29, v29, s28, v130
	v_and_or_b32 v30, v30, s28, v131
	v_and_or_b32 v31, v31, s28, v132
	v_and_or_b32 v32, v32, s28, v133
	v_and_or_b32 v33, v33, s28, v134
	v_and_or_b32 v34, v34, s28, v135
	v_and_or_b32 v35, v35, s28, v136
	v_and_or_b32 v36, v36, s28, v137
	v_and_or_b32 v37, v37, s28, v138
	v_and_or_b32 v38, v38, s28, v139
	v_and_or_b32 v39, v39, s28, v140
	v_and_or_b32 v40, v40, s28, v141
	v_and_or_b32 v41, v41, s28, v142
	v_and_or_b32 v42, v42, s28, v143
	v_and_or_b32 v43, v43, s28, v144
	v_and_or_b32 v44, v44, s28, v145
	v_and_or_b32 v45, v45, s28, v146
	v_and_or_b32 v46, v46, s28, v147
	v_and_or_b32 v47, v47, s28, v148
	v_and_or_b32 v48, v48, s28, v149
	v_and_or_b32 v49, v49, s28, v150
	v_and_or_b32 v50, v50, s28, v151
	v_and_or_b32 v51, v51, s28, v152
	v_and_or_b32 v52, v52, s28, v153
	v_and_or_b32 v53, v53, s28, v154
	v_and_or_b32 v54, v54, s28, v155
	v_and_or_b32 v55, v55, s28, v156
	v_and_or_b32 v56, v56, s28, v157
	v_and_or_b32 v57, v57, s28, v158
	v_and_or_b32 v58, v58, s28, v159
	v_and_or_b32 v59, v59, s28, v160
	v_and_or_b32 v60, v60, s28, v161
	v_and_or_b32 v61, v61, s28, v162
	v_and_or_b32 v62, v62, s28, v163
	v_and_or_b32 v63, v63, s28, v164
	v_and_or_b32 v64, v64, s28, v165
	v_and_or_b32 v65, v65, s28, v166
	v_max_f32_e32 v203, v2, v15
	v_min_f32_e32 v2, v2, v15
	v_max_f32_e32 v15, v3, v14
	v_min_f32_e32 v3, v3, v14
	v_max_f32_e32 v14, v17, v17
	v_max_f32_e32 v211, v18, v31
	v_min_f32_e32 v18, v18, v31
	v_max_f32_e32 v31, v19, v30
	v_min_f32_e32 v19, v19, v30
	v_max_f32_e32 v30, v33, v33
	v_max_f32_e32 v219, v34, v47
	v_min_f32_e32 v34, v34, v47
	v_max_f32_e32 v47, v35, v46
	v_min_f32_e32 v35, v35, v46
	v_max_f32_e32 v46, v49, v49
	v_max_f32_e32 v227, v50, v63
	v_min_f32_e32 v50, v50, v63
	v_max_f32_e32 v63, v51, v62
	v_min_f32_e32 v51, v51, v62
	v_max_f32_e32 v62, v65, v65
	v_max_f32_e32 v17, v4, v14
	v_min_f32_e32 v4, v4, v14
	v_max_f32_e32 v14, v16, v16
	v_max_f32_e32 v33, v20, v30
	v_min_f32_e32 v20, v20, v30
	v_max_f32_e32 v30, v32, v32
	v_max_f32_e32 v49, v36, v46
	v_min_f32_e32 v36, v36, v46
	v_max_f32_e32 v46, v48, v48
	v_max_f32_e32 v65, v52, v62
	v_min_f32_e32 v52, v52, v62
	v_max_f32_e32 v62, v64, v64
	v_max_f32_e32 v16, v5, v14
	v_min_f32_e32 v5, v5, v14
	v_max_f32_e32 v14, v6, v10
	v_min_f32_e32 v6, v6, v10
	v_max_f32_e32 v10, v7, v8
	v_min_f32_e32 v7, v7, v8
	v_max_f32_e32 v8, v13, v13
	v_max_f32_e32 v32, v21, v30
	v_min_f32_e32 v21, v21, v30
	v_max_f32_e32 v30, v22, v26
	v_min_f32_e32 v22, v22, v26
	v_max_f32_e32 v26, v23, v24
	v_min_f32_e32 v23, v23, v24
	v_max_f32_e32 v24, v29, v29
	v_max_f32_e32 v48, v37, v46
	v_min_f32_e32 v37, v37, v46
	v_max_f32_e32 v46, v38, v42
	v_min_f32_e32 v38, v38, v42
	v_max_f32_e32 v42, v39, v40
	v_min_f32_e32 v39, v39, v40
	v_max_f32_e32 v40, v45, v45
	v_max_f32_e32 v64, v53, v62
	v_min_f32_e32 v53, v53, v62
	v_max_f32_e32 v62, v54, v58
	v_min_f32_e32 v54, v54, v58
	v_max_f32_e32 v58, v55, v56
	v_min_f32_e32 v55, v55, v56
	v_max_f32_e32 v56, v61, v61
	v_max_f32_e32 v13, v9, v8
	v_min_f32_e32 v8, v9, v8
	v_max_f32_e32 v9, v12, v12
	v_max_f32_e32 v29, v25, v24
	v_min_f32_e32 v24, v25, v24
	v_max_f32_e32 v25, v28, v28
	v_max_f32_e32 v45, v41, v40
	v_min_f32_e32 v40, v41, v40
	v_max_f32_e32 v41, v44, v44
	v_max_f32_e32 v61, v57, v56
	v_min_f32_e32 v56, v57, v56
	v_max_f32_e32 v57, v60, v60
	v_max_f32_e32 v12, v11, v9
	v_min_f32_e32 v9, v11, v9
	v_max_f32_e32 v28, v27, v25
	v_min_f32_e32 v25, v27, v25
	v_max_f32_e32 v44, v43, v41
	v_min_f32_e32 v41, v43, v41
	v_max_f32_e32 v60, v59, v57
	v_min_f32_e32 v57, v59, v57
	v_max_f32_e32 v11, v203, v10
	v_min_f32_e32 v10, v203, v10
	v_max_f32_e32 v203, v15, v13
	v_min_f32_e32 v13, v15, v13
	v_max_f32_e32 v15, v17, v12
	v_min_f32_e32 v12, v17, v12
	v_max_f32_e32 v17, v16, v14
	v_min_f32_e32 v14, v16, v14
	v_max_f32_e32 v16, v7, v2
	v_min_f32_e32 v2, v7, v2
	v_max_f32_e32 v7, v6, v5
	v_min_f32_e32 v5, v6, v5
	v_max_f32_e32 v6, v9, v4
	v_min_f32_e32 v4, v9, v4
	v_max_f32_e32 v9, v8, v3
	v_min_f32_e32 v3, v8, v3
	v_max_f32_e32 v27, v211, v26
	v_min_f32_e32 v26, v211, v26
	v_max_f32_e32 v211, v31, v29
	v_min_f32_e32 v29, v31, v29
	v_max_f32_e32 v31, v33, v28
	v_min_f32_e32 v28, v33, v28
	v_max_f32_e32 v33, v32, v30
	v_min_f32_e32 v30, v32, v30
	v_max_f32_e32 v32, v23, v18
	v_min_f32_e32 v18, v23, v18
	v_max_f32_e32 v23, v22, v21
	v_min_f32_e32 v21, v22, v21
	v_max_f32_e32 v22, v25, v20
	v_min_f32_e32 v20, v25, v20
	v_max_f32_e32 v25, v24, v19
	v_min_f32_e32 v19, v24, v19
	v_max_f32_e32 v43, v219, v42
	v_min_f32_e32 v42, v219, v42
	v_max_f32_e32 v219, v47, v45
	v_min_f32_e32 v45, v47, v45
	v_max_f32_e32 v47, v49, v44
	v_min_f32_e32 v44, v49, v44
	v_max_f32_e32 v49, v48, v46
	v_min_f32_e32 v46, v48, v46
	v_max_f32_e32 v48, v39, v34
	v_min_f32_e32 v34, v39, v34
	v_max_f32_e32 v39, v38, v37
	v_min_f32_e32 v37, v38, v37
	v_max_f32_e32 v38, v41, v36
	v_min_f32_e32 v36, v41, v36
	v_max_f32_e32 v41, v40, v35
	v_min_f32_e32 v35, v40, v35
	v_max_f32_e32 v59, v227, v58
	v_min_f32_e32 v58, v227, v58
	v_max_f32_e32 v227, v63, v61
	v_min_f32_e32 v61, v63, v61
	v_max_f32_e32 v63, v65, v60
	v_min_f32_e32 v60, v65, v60
	v_max_f32_e32 v65, v64, v62
	v_min_f32_e32 v62, v64, v62
	v_max_f32_e32 v64, v55, v50
	v_min_f32_e32 v50, v55, v50
	v_max_f32_e32 v55, v54, v53
	v_min_f32_e32 v53, v54, v53
	v_max_f32_e32 v54, v57, v52
	v_min_f32_e32 v52, v57, v52
	v_max_f32_e32 v57, v56, v51
	v_min_f32_e32 v51, v56, v51
; #define CEF_D(a, b) { const float hi_ = fmaxf((a), (b)), lo_ = fminf((a), (b)); (a) = hi_; (b) = lo_; }
; template <int OFF, int NV> __device__ __forceinline__ void bsort16_desc(float (&v)[NV]) {
; #pragma unroll
;     for (int t = 0; t < 60; ++t) CEF_D(v[OFF + sn16_a(t)], v[OFF + sn16_b(t)])
; }
	v_max_f32_e32 v8, v11, v203
	v_min_f32_e32 v11, v11, v203
	v_max_f32_e32 v203, v15, v17
	v_min_f32_e32 v15, v15, v17
	v_max_f32_e32 v17, v14, v10
	v_min_f32_e32 v10, v14, v10
	v_max_f32_e32 v14, v16, v7
	v_min_f32_e32 v7, v16, v7
	v_max_f32_e32 v16, v13, v12
	v_min_f32_e32 v12, v13, v12
	v_max_f32_e32 v13, v6, v9
	v_min_f32_e32 v6, v6, v9
	v_max_f32_e32 v9, v3, v2
	v_min_f32_e32 v2, v3, v2
	v_max_f32_e32 v3, v5, v4
	v_min_f32_e32 v4, v5, v4
	v_max_f32_e32 v24, v27, v211
	v_min_f32_e32 v27, v27, v211
	v_max_f32_e32 v211, v31, v33
	v_min_f32_e32 v31, v31, v33
	v_max_f32_e32 v33, v30, v26
	v_min_f32_e32 v26, v30, v26
	v_max_f32_e32 v30, v32, v23
	v_min_f32_e32 v23, v32, v23
	v_max_f32_e32 v32, v29, v28
	v_min_f32_e32 v28, v29, v28
	v_max_f32_e32 v29, v22, v25
	v_min_f32_e32 v22, v22, v25
	v_max_f32_e32 v25, v19, v18
	v_min_f32_e32 v18, v19, v18
	v_max_f32_e32 v19, v21, v20
	v_min_f32_e32 v20, v21, v20
	v_max_f32_e32 v40, v43, v219
	v_min_f32_e32 v43, v43, v219
	v_max_f32_e32 v219, v47, v49
	v_min_f32_e32 v47, v47, v49
	v_max_f32_e32 v49, v46, v42
	v_min_f32_e32 v42, v46, v42
	v_max_f32_e32 v46, v48, v39
	v_min_f32_e32 v39, v48, v39
	v_max_f32_e32 v48, v45, v44
	v_min_f32_e32 v44, v45, v44
	v_max_f32_e32 v45, v38, v41
	v_min_f32_e32 v38, v38, v41
	v_max_f32_e32 v41, v35, v34
	v_min_f32_e32 v34, v35, v34
	v_max_f32_e32 v35, v37, v36
	v_min_f32_e32 v36, v37, v36
	v_max_f32_e32 v56, v59, v227
	v_min_f32_e32 v59, v59, v227
	v_max_f32_e32 v227, v63, v65
	v_min_f32_e32 v63, v63, v65
	v_max_f32_e32 v65, v62, v58
	v_min_f32_e32 v58, v62, v58
	v_max_f32_e32 v62, v64, v55
	v_min_f32_e32 v55, v64, v55
	v_max_f32_e32 v64, v61, v60
	v_min_f32_e32 v60, v61, v60
	v_max_f32_e32 v61, v54, v57
	v_min_f32_e32 v54, v54, v57
	v_max_f32_e32 v57, v51, v50
	v_min_f32_e32 v50, v51, v50
	v_max_f32_e32 v51, v53, v52
	v_min_f32_e32 v52, v53, v52
	v_min_f32_e32 v5, v8, v203
	v_max_f32_e32 v204, v11, v15
	v_min_f32_e32 v11, v11, v15
	v_max_f32_e32 v15, v17, v13
	v_min_f32_e32 v13, v17, v13
	v_max_f32_e32 v17, v10, v6
	v_min_f32_e32 v6, v10, v6
	v_max_f32_e32 v10, v14, v16
	v_min_f32_e32 v14, v14, v16
	v_max_f32_e32 v16, v7, v12
	v_min_f32_e32 v7, v7, v12
	v_max_f32_e32 v12, v9, v3
	v_min_f32_e32 v3, v9, v3
	v_max_f32_e32 v9, v2, v4
	v_min_f32_e32 v21, v24, v211
	v_max_f32_e32 v212, v27, v31
	v_min_f32_e32 v27, v27, v31
	v_max_f32_e32 v31, v33, v29
	v_min_f32_e32 v29, v33, v29
	v_max_f32_e32 v33, v26, v22
	v_min_f32_e32 v22, v26, v22
	v_max_f32_e32 v26, v30, v32
	v_min_f32_e32 v30, v30, v32
	v_max_f32_e32 v32, v23, v28
	v_min_f32_e32 v23, v23, v28
	v_max_f32_e32 v28, v25, v19
	v_min_f32_e32 v19, v25, v19
	v_max_f32_e32 v25, v18, v20
	v_min_f32_e32 v37, v40, v219
	v_max_f32_e32 v220, v43, v47
	v_min_f32_e32 v43, v43, v47
	v_max_f32_e32 v47, v49, v45
	v_min_f32_e32 v45, v49, v45
	v_max_f32_e32 v49, v42, v38
	v_min_f32_e32 v38, v42, v38
	v_max_f32_e32 v42, v46, v48
	v_min_f32_e32 v46, v46, v48
	v_max_f32_e32 v48, v39, v44
	v_min_f32_e32 v39, v39, v44
	v_max_f32_e32 v44, v41, v35
	v_min_f32_e32 v35, v41, v35
	v_max_f32_e32 v41, v34, v36
	v_min_f32_e32 v53, v56, v227
	v_max_f32_e32 v228, v59, v63
	v_min_f32_e32 v59, v59, v63
	v_max_f32_e32 v63, v65, v61
	v_min_f32_e32 v61, v65, v61
	v_max_f32_e32 v65, v58, v54
	v_min_f32_e32 v54, v58, v54
	v_max_f32_e32 v58, v62, v64
	v_min_f32_e32 v62, v62, v64
	v_max_f32_e32 v64, v55, v60
	v_min_f32_e32 v55, v55, v60
	v_max_f32_e32 v60, v57, v51
	v_min_f32_e32 v51, v57, v51
	v_max_f32_e32 v57, v50, v52
	v_min_f32_e32 v2, v2, v4
	v_max_f32_e32 v4, v204, v5
	v_min_f32_e32 v5, v204, v5
	v_max_f32_e32 v204, v11, v12
	v_min_f32_e32 v11, v11, v12
	v_max_f32_e32 v12, v15, v10
	v_min_f32_e32 v10, v15, v10
	v_max_f32_e32 v15, v17, v14
	v_min_f32_e32 v14, v17, v14
	v_max_f32_e32 v17, v16, v13
	v_min_f32_e32 v13, v16, v13
	v_max_f32_e32 v16, v7, v6
	v_min_f32_e32 v6, v7, v6
	v_max_f32_e32 v7, v9, v3
	v_min_f32_e32 v18, v18, v20
	v_max_f32_e32 v20, v212, v21
	v_min_f32_e32 v21, v212, v21
	v_max_f32_e32 v212, v27, v28
	v_min_f32_e32 v27, v27, v28
	v_max_f32_e32 v28, v31, v26
	v_min_f32_e32 v26, v31, v26
	v_max_f32_e32 v31, v33, v30
	v_min_f32_e32 v30, v33, v30
	v_max_f32_e32 v33, v32, v29
	v_min_f32_e32 v29, v32, v29
	v_max_f32_e32 v32, v23, v22
	v_min_f32_e32 v22, v23, v22
	v_max_f32_e32 v23, v25, v19
	v_min_f32_e32 v34, v34, v36
	v_max_f32_e32 v36, v220, v37
	v_min_f32_e32 v37, v220, v37
	v_max_f32_e32 v220, v43, v44
	v_min_f32_e32 v43, v43, v44
	v_max_f32_e32 v44, v47, v42
	v_min_f32_e32 v42, v47, v42
	v_max_f32_e32 v47, v49, v46
	v_min_f32_e32 v46, v49, v46
	v_max_f32_e32 v49, v48, v45
	v_min_f32_e32 v45, v48, v45
	v_max_f32_e32 v48, v39, v38
	v_min_f32_e32 v38, v39, v38
	v_max_f32_e32 v39, v41, v35
	v_min_f32_e32 v50, v50, v52
	v_max_f32_e32 v52, v228, v53
	v_min_f32_e32 v53, v228, v53
	v_max_f32_e32 v228, v59, v60
	v_min_f32_e32 v59, v59, v60
	v_max_f32_e32 v60, v63, v58
	v_min_f32_e32 v58, v63, v58
	v_max_f32_e32 v63, v65, v62
	v_min_f32_e32 v62, v65, v62
	v_max_f32_e32 v65, v64, v61
	v_min_f32_e32 v61, v64, v61
	v_max_f32_e32 v64, v55, v54
	v_min_f32_e32 v54, v55, v54
	v_max_f32_e32 v55, v57, v51
	v_min_f32_e32 v3, v9, v3
	v_max_f32_e32 v205, v5, v10
	v_min_f32_e32 v5, v5, v10
	v_max_f32_e32 v10, v15, v17
	v_min_f32_e32 v15, v15, v17
	v_max_f32_e32 v17, v14, v13
	v_min_f32_e32 v13, v14, v13
	v_max_f32_e32 v14, v16, v7
	v_min_f32_e32 v19, v25, v19
	v_max_f32_e32 v213, v21, v26
	v_min_f32_e32 v21, v21, v26
	v_max_f32_e32 v26, v31, v33
	v_min_f32_e32 v31, v31, v33
	v_max_f32_e32 v33, v30, v29
	v_min_f32_e32 v29, v30, v29
	v_max_f32_e32 v30, v32, v23
	v_min_f32_e32 v35, v41, v35
	v_max_f32_e32 v221, v37, v42
	v_min_f32_e32 v37, v37, v42
; #define CEF_D(a, b) { const float hi_ = fmaxf((a), (b)), lo_ = fminf((a), (b)); (a) = hi_; (b) = lo_; }
; template <int OA, int NV> __device__ __forceinline__ void bmerge16_desc(float (&v)[NV]) {
; #pragma unroll
;     for (int j = 8; j > 0; j >>= 1) {
; #pragma unroll
;         for (int i = 0; i < 16; ++i) { const int l = i ^ j; if (l > i) CEF_D(v[OA + i], v[OA + l]) }
;     }
; }
; template <int OA, int OB, int NV> __device__ __forceinline__ void merge_top16(float (&v)[NV]) {
; #pragma unroll
;     for (int i = 0; i < 16; ++i) v[OA + i] = fmaxf(v[OA + i], v[OB + 15 - i]);
;     bmerge16_desc<OA, NV>(v);
; }
; __device__ __forceinline__ void phase_topk_fast(LAS unsigned char* lds, const bf16* Q, const bf16* keysb  , int* EID, float* GATE, bool prestaged  ) {
;     ...
;                 bsort16_desc<0, 64>(v); bsort16_desc<16, 64>(v); bsort16_desc<32, 64>(v); bsort16_desc<48, 64>(v);
;                 merge_top16<0, 16, 64>(v); merge_top16<32, 48, 64>(v); merge_top16<0, 32, 64>(v);
	v_max_f32_e32 v42, v47, v49
	v_min_f32_e32 v47, v47, v49
	v_max_f32_e32 v49, v46, v45
	v_min_f32_e32 v45, v46, v45
	v_max_f32_e32 v46, v48, v39
	v_min_f32_e32 v51, v57, v51
	v_max_f32_e32 v229, v53, v58
	v_min_f32_e32 v53, v53, v58
	v_max_f32_e32 v58, v63, v65
	v_min_f32_e32 v63, v63, v65
	v_max_f32_e32 v65, v62, v61
	v_min_f32_e32 v61, v62, v61
	v_max_f32_e32 v62, v64, v55
	v_min_f32_e32 v7, v16, v7
	v_max_f32_e32 v16, v6, v3
	v_max_f32_e32 v206, v204, v5
	v_min_f32_e32 v5, v204, v5
	v_max_f32_e32 v204, v14, v11
	v_min_f32_e32 v11, v14, v11
	v_min_f32_e32 v23, v32, v23
	v_max_f32_e32 v32, v22, v19
	v_max_f32_e32 v214, v212, v21
	v_min_f32_e32 v21, v212, v21
	v_max_f32_e32 v212, v30, v27
	v_min_f32_e32 v27, v30, v27
	v_min_f32_e32 v39, v48, v39
	v_max_f32_e32 v48, v38, v35
	v_max_f32_e32 v222, v220, v37
	v_min_f32_e32 v37, v220, v37
	v_max_f32_e32 v220, v46, v43
	v_min_f32_e32 v43, v46, v43
	v_min_f32_e32 v55, v64, v55
	v_max_f32_e32 v64, v54, v51
	v_max_f32_e32 v230, v228, v53
	v_min_f32_e32 v53, v228, v53
	v_max_f32_e32 v228, v62, v59
	v_min_f32_e32 v59, v62, v59
	v_min_f32_e32 v9, v4, v12
	v_max_f32_e32 v14, v16, v7
	v_min_f32_e32 v7, v16, v7
	v_max_f32_e32 v16, v206, v10
	v_min_f32_e32 v10, v206, v10
	v_max_f32_e32 v206, v5, v15
	v_min_f32_e32 v5, v5, v15
	v_max_f32_e32 v15, v17, v204
	v_min_f32_e32 v17, v17, v204
	v_max_f32_e32 v204, v13, v11
	v_min_f32_e32 v25, v20, v28
	v_max_f32_e32 v30, v32, v23
	v_min_f32_e32 v23, v32, v23
	v_max_f32_e32 v32, v214, v26
	v_min_f32_e32 v26, v214, v26
	v_max_f32_e32 v214, v21, v31
	v_min_f32_e32 v21, v21, v31
	v_max_f32_e32 v31, v33, v212
	v_min_f32_e32 v33, v33, v212
	v_max_f32_e32 v212, v29, v27
	v_min_f32_e32 v41, v36, v44
	v_max_f32_e32 v46, v48, v39
	v_min_f32_e32 v39, v48, v39
	v_max_f32_e32 v48, v222, v42
	v_min_f32_e32 v42, v222, v42
	v_max_f32_e32 v222, v37, v47
	v_min_f32_e32 v37, v37, v47
	v_max_f32_e32 v47, v49, v220
	v_min_f32_e32 v49, v49, v220
	v_max_f32_e32 v220, v45, v43
	v_min_f32_e32 v57, v52, v60
	v_max_f32_e32 v62, v64, v55
	v_min_f32_e32 v55, v64, v55
	v_max_f32_e32 v64, v230, v58
	v_min_f32_e32 v58, v230, v58
	v_max_f32_e32 v230, v53, v63
	v_min_f32_e32 v53, v53, v63
	v_max_f32_e32 v63, v65, v228
	v_min_f32_e32 v65, v65, v228
	v_max_f32_e32 v228, v61, v59
	v_min_f32_e32 v3, v6, v3
	v_min_f32_e32 v6, v205, v9
	v_min_f32_e32 v11, v13, v11
	v_min_f32_e32 v207, v10, v206
	v_max_f32_e32 v208, v15, v5
	v_min_f32_e32 v5, v15, v5
	v_max_f32_e32 v15, v17, v204
	v_min_f32_e32 v19, v22, v19
	v_min_f32_e32 v22, v213, v25
	v_min_f32_e32 v27, v29, v27
	v_min_f32_e32 v215, v26, v214
	v_max_f32_e32 v216, v31, v21
	v_min_f32_e32 v21, v31, v21
	v_max_f32_e32 v31, v33, v212
	v_min_f32_e32 v35, v38, v35
	v_min_f32_e32 v38, v221, v41
	v_min_f32_e32 v43, v45, v43
	v_min_f32_e32 v223, v42, v222
	v_max_f32_e32 v224, v47, v37
	v_min_f32_e32 v37, v47, v37
	v_max_f32_e32 v47, v49, v220
	v_min_f32_e32 v51, v54, v51
	v_min_f32_e32 v54, v229, v57
	v_min_f32_e32 v59, v61, v59
	v_min_f32_e32 v231, v58, v230
	v_max_f32_e32 v232, v63, v53
	v_min_f32_e32 v53, v63, v53
	v_max_f32_e32 v63, v65, v228
	v_min_f32_e32 v13, v16, v6
	v_min_f32_e32 v17, v17, v204
	v_min_f32_e32 v204, v14, v11
	v_min_f32_e32 v209, v207, v208
	v_min_f32_e32 v210, v5, v15
	v_min_f32_e32 v29, v32, v22
	v_min_f32_e32 v33, v33, v212
	v_min_f32_e32 v212, v30, v27
	v_min_f32_e32 v217, v215, v216
	v_min_f32_e32 v218, v21, v31
	v_min_f32_e32 v45, v48, v38
	v_min_f32_e32 v49, v49, v220
	v_min_f32_e32 v220, v46, v43
	v_min_f32_e32 v225, v223, v224
	v_min_f32_e32 v226, v37, v47
	v_min_f32_e32 v61, v64, v54
	v_min_f32_e32 v65, v65, v228
	v_min_f32_e32 v228, v62, v59
	v_min_f32_e32 v233, v231, v232
	v_min_f32_e32 v234, v53, v63
	v_max3_f32 v8, v8, v203, v18
	v_max3_f32 v4, v4, v12, v19
	v_max3_f32 v9, v205, v9, v23
	v_max3_f32 v6, v16, v6, v212
	v_max3_f32 v12, v13, v30, v27
	v_max3_f32 v10, v10, v206, v33
	v_max3_f32 v13, v207, v208, v218
	v_max3_f32 v16, v209, v21, v31
	v_max3_f32 v5, v5, v15, v217
	v_max3_f32 v15, v210, v215, v216
	v_max3_f32 v17, v17, v26, v214
	v_max3_f32 v11, v14, v11, v29
	v_max3_f32 v14, v204, v32, v22
	v_max3_f32 v7, v7, v213, v25
	v_max3_f32 v3, v3, v20, v28
	v_max3_f32 v2, v2, v24, v211
	v_max3_f32 v26, v40, v219, v50
	v_max3_f32 v27, v36, v44, v51
	v_max3_f32 v28, v221, v41, v55
	v_max3_f32 v29, v48, v38, v228
	v_max3_f32 v30, v45, v62, v59
	v_max3_f32 v31, v42, v222, v65
	v_max3_f32 v32, v223, v224, v234
	v_max3_f32 v33, v225, v53, v63
	v_max3_f32 v36, v37, v47, v233
	v_max3_f32 v37, v226, v231, v232
	v_max3_f32 v38, v49, v58, v230
	v_max3_f32 v40, v46, v43, v61
	v_max3_f32 v41, v220, v64, v54
	v_max3_f32 v39, v39, v229, v57
	v_max3_f32 v35, v35, v52, v60
	v_max3_f32 v34, v34, v56, v227
	v_max_f32_e32 v18, v8, v5
	v_min_f32_e32 v5, v8, v5
	v_max_f32_e32 v8, v4, v15
	v_min_f32_e32 v4, v4, v15
	v_max_f32_e32 v15, v9, v17
	v_min_f32_e32 v9, v9, v17
	v_max_f32_e32 v17, v6, v11
	v_min_f32_e32 v6, v6, v11
	v_max_f32_e32 v11, v12, v14
	v_min_f32_e32 v12, v12, v14
	v_max_f32_e32 v14, v10, v7
	v_min_f32_e32 v7, v10, v7
	v_max_f32_e32 v10, v13, v3
	v_min_f32_e32 v3, v13, v3
	v_max_f32_e32 v13, v16, v2
	v_min_f32_e32 v2, v16, v2
	v_max_f32_e32 v42, v26, v36
	v_min_f32_e32 v26, v26, v36
	v_max_f32_e32 v36, v27, v37
	v_min_f32_e32 v27, v27, v37
	v_max_f32_e32 v37, v28, v38
	v_min_f32_e32 v28, v28, v38
	v_max_f32_e32 v38, v29, v40
	v_min_f32_e32 v29, v29, v40
	v_max_f32_e32 v40, v30, v41
	v_min_f32_e32 v30, v30, v41
	v_max_f32_e32 v41, v31, v39
	v_min_f32_e32 v31, v31, v39
	v_max_f32_e32 v39, v32, v35
	v_min_f32_e32 v32, v32, v35
	v_max_f32_e32 v35, v33, v34
	v_min_f32_e32 v33, v33, v34
	v_max_f32_e32 v16, v18, v11
; __device__ __forceinline__ void phase_topk_fast(LAS unsigned char* lds, const bf16* Q, const bf16* keysb  , int* EID, float* GATE, bool prestaged  ) {
;     ...
;                 bsort16_desc<0, 64>(v); bsort16_desc<16, 64>(v); bsort16_desc<32, 64>(v); bsort16_desc<48, 64>(v);
;                 merge_top16<0, 16, 64>(v); merge_top16<32, 48, 64>(v); merge_top16<0, 32, 64>(v);
;                 float o[16];
; #pragma unroll
;                 for (int i = 0; i < 16; ++i) o[i] = __shfl_xor(v[i], 32);
; #pragma unroll
;                 for (int i = 0; i < 16; ++i) v[i] = fmaxf(v[i], o[15 - i]);
;                 bmerge16_desc<0, 64>(v);
	v_min_f32_e32 v11, v18, v11
	v_max_f32_e32 v18, v8, v14
	v_min_f32_e32 v8, v8, v14
	v_max_f32_e32 v14, v15, v10
	v_min_f32_e32 v10, v15, v10
	v_max_f32_e32 v15, v17, v13
	v_min_f32_e32 v13, v17, v13
	v_max_f32_e32 v17, v5, v12
	v_min_f32_e32 v5, v5, v12
	v_max_f32_e32 v12, v4, v7
	v_min_f32_e32 v4, v4, v7
	v_max_f32_e32 v7, v9, v3
	v_min_f32_e32 v3, v9, v3
	v_max_f32_e32 v9, v6, v2
	v_min_f32_e32 v2, v6, v2
	v_max_f32_e32 v34, v42, v40
	v_min_f32_e32 v40, v42, v40
	v_max_f32_e32 v42, v36, v41
	v_min_f32_e32 v36, v36, v41
	v_max_f32_e32 v41, v37, v39
	v_min_f32_e32 v37, v37, v39
	v_max_f32_e32 v39, v38, v35
	v_min_f32_e32 v35, v38, v35
	v_max_f32_e32 v38, v26, v30
	v_min_f32_e32 v26, v26, v30
	v_max_f32_e32 v30, v27, v31
	v_min_f32_e32 v27, v27, v31
	v_max_f32_e32 v31, v28, v32
	v_min_f32_e32 v28, v28, v32
	v_max_f32_e32 v32, v29, v33
	v_min_f32_e32 v29, v29, v33
	v_max_f32_e32 v6, v16, v14
	v_min_f32_e32 v14, v16, v14
	v_max_f32_e32 v16, v18, v15
	v_min_f32_e32 v15, v18, v15
	v_max_f32_e32 v18, v11, v10
	v_min_f32_e32 v10, v11, v10
	v_max_f32_e32 v11, v8, v13
	v_min_f32_e32 v8, v8, v13
	v_max_f32_e32 v13, v17, v7
	v_min_f32_e32 v7, v17, v7
	v_max_f32_e32 v17, v12, v9
	v_min_f32_e32 v9, v12, v9
	v_max_f32_e32 v12, v5, v3
	v_min_f32_e32 v3, v5, v3
	v_max_f32_e32 v5, v4, v2
	v_min_f32_e32 v2, v4, v2
	v_max_f32_e32 v33, v34, v41
	v_min_f32_e32 v34, v34, v41
	v_max_f32_e32 v41, v42, v39
	v_min_f32_e32 v39, v42, v39
	v_max_f32_e32 v42, v40, v37
	v_min_f32_e32 v37, v40, v37
	v_max_f32_e32 v40, v36, v35
	v_min_f32_e32 v35, v36, v35
	v_max_f32_e32 v36, v38, v31
	v_min_f32_e32 v31, v38, v31
	v_max_f32_e32 v38, v30, v32
	v_min_f32_e32 v30, v30, v32
	v_max_f32_e32 v32, v26, v28
	v_min_f32_e32 v26, v26, v28
	v_max_f32_e32 v28, v27, v29
	v_min_f32_e32 v27, v27, v29
	v_min_f32_e32 v4, v6, v16
	v_min_f32_e32 v19, v14, v15
	v_min_f32_e32 v20, v18, v11
	v_min_f32_e32 v21, v10, v8
	v_min_f32_e32 v22, v13, v17
	v_min_f32_e32 v23, v7, v9
	v_min_f32_e32 v24, v12, v5
	v_min_f32_e32 v25, v3, v2
	v_min_f32_e32 v29, v33, v41
	v_min_f32_e32 v43, v34, v39
	v_min_f32_e32 v44, v42, v40
	v_min_f32_e32 v45, v37, v35
	v_min_f32_e32 v46, v36, v38
	v_min_f32_e32 v47, v31, v30
	v_min_f32_e32 v48, v32, v28
	v_min_f32_e32 v49, v26, v27
	v_max3_f32 v6, v6, v16, v49
	v_max3_f32 v4, v4, v26, v27
	v_max3_f32 v14, v14, v15, v48
	v_max3_f32 v15, v19, v32, v28
	v_max3_f32 v11, v18, v11, v47
	v_max3_f32 v16, v20, v31, v30
	v_max3_f32 v8, v10, v8, v46
	v_max3_f32 v10, v21, v36, v38
	v_max3_f32 v13, v13, v17, v45
	v_max3_f32 v17, v22, v37, v35
	v_max3_f32 v7, v7, v9, v44
	v_max3_f32 v9, v23, v42, v40
	v_max3_f32 v5, v12, v5, v43
	v_max3_f32 v12, v24, v34, v39
	v_max3_f32 v2, v3, v2, v29
	v_max3_f32 v3, v25, v33, v41
	v_max_f32_e32 v18, v6, v13
	v_min_f32_e32 v6, v6, v13
	v_max_f32_e32 v13, v4, v17
	v_min_f32_e32 v4, v4, v17
	v_max_f32_e32 v17, v14, v7
	v_min_f32_e32 v7, v14, v7
	v_max_f32_e32 v14, v15, v9
	v_min_f32_e32 v9, v15, v9
	v_max_f32_e32 v15, v11, v5
	v_min_f32_e32 v5, v11, v5
	v_max_f32_e32 v11, v16, v12
	v_min_f32_e32 v12, v16, v12
	v_max_f32_e32 v16, v8, v2
	v_min_f32_e32 v2, v8, v2
	v_max_f32_e32 v8, v10, v3
	v_min_f32_e32 v3, v10, v3
	v_max_f32_e32 v10, v18, v15
	v_min_f32_e32 v15, v18, v15
	v_max_f32_e32 v18, v13, v11
	v_min_f32_e32 v11, v13, v11
	v_max_f32_e32 v13, v17, v16
	v_min_f32_e32 v16, v17, v16
	v_max_f32_e32 v17, v14, v8
	v_min_f32_e32 v8, v14, v8
	v_max_f32_e32 v14, v6, v5
	v_min_f32_e32 v5, v6, v5
	v_max_f32_e32 v6, v4, v12
	v_min_f32_e32 v4, v4, v12
	v_max_f32_e32 v12, v7, v2
	v_min_f32_e32 v2, v7, v2
	v_max_f32_e32 v7, v9, v3
	v_min_f32_e32 v3, v9, v3
	v_max_f32_e32 v9, v10, v13
	v_min_f32_e32 v10, v10, v13
	v_max_f32_e32 v13, v18, v17
	v_min_f32_e32 v17, v18, v17
	v_max_f32_e32 v18, v15, v16
	v_min_f32_e32 v15, v15, v16
	v_max_f32_e32 v16, v11, v8
	v_min_f32_e32 v8, v11, v8
	v_max_f32_e32 v11, v14, v12
	v_min_f32_e32 v12, v14, v12
	v_max_f32_e32 v14, v6, v7
	v_min_f32_e32 v6, v6, v7
	v_max_f32_e32 v7, v5, v2
	v_min_f32_e32 v2, v5, v2
	v_max_f32_e32 v5, v4, v3
	v_min_f32_e32 v3, v4, v3
	v_and_b32_e32 v19, 64, v200
	v_max_f32_e32 v4, v9, v13
	v_min_f32_e32 v9, v9, v13
	v_max_f32_e32 v13, v10, v17
	v_min_f32_e32 v10, v10, v17
	v_max_f32_e32 v17, v18, v16
	v_min_f32_e32 v16, v18, v16
	v_max_f32_e32 v18, v15, v8
	v_min_f32_e32 v8, v15, v8
	v_max_f32_e32 v15, v11, v14
	v_min_f32_e32 v11, v11, v14
	v_max_f32_e32 v14, v12, v6
	v_min_f32_e32 v6, v12, v6
	v_max_f32_e32 v12, v7, v5
	v_min_f32_e32 v5, v7, v5
	v_max_f32_e32 v7, v2, v3
	v_min_f32_e32 v2, v2, v3
	v_xor_b32_e32 v3, 32, v200
	v_add_u32_e32 v19, 64, v19
	v_cmp_lt_i32_e32 vcc, v3, v19
	s_nop 1
	v_cndmask_b32_e32 v3, v200, v3, vcc
	v_lshlrev_b32_e32 v203, 2, v3
	ds_bpermute_b32 v29, v203, v2
	ds_bpermute_b32 v31, v203, v7
	ds_bpermute_b32 v33, v203, v5
	ds_bpermute_b32 v32, v203, v12
	ds_bpermute_b32 v3, v203, v4
	ds_bpermute_b32 v19, v203, v9
	ds_bpermute_b32 v20, v203, v13
	ds_bpermute_b32 v21, v203, v10
	ds_bpermute_b32 v22, v203, v17
	ds_bpermute_b32 v23, v203, v16
	ds_bpermute_b32 v24, v203, v18
	ds_bpermute_b32 v25, v203, v8
	ds_bpermute_b32 v26, v203, v15
	ds_bpermute_b32 v27, v203, v11
	ds_bpermute_b32 v28, v203, v14
	ds_bpermute_b32 v30, v203, v6
	s_waitcnt lgkmcnt(14)
	v_max_f32_e32 v4, v4, v29
	v_max_f32_e32 v29, v31, v31
	v_max_f32_e32 v9, v9, v29
	s_waitcnt lgkmcnt(13)
	v_max_f32_e32 v29, v33, v33
	v_max_f32_e32 v13, v13, v29
	s_waitcnt lgkmcnt(12)
	v_max_f32_e32 v29, v32, v32
	v_max_f32_e32 v10, v10, v29
	s_waitcnt lgkmcnt(0)
; #define LAS __attribute__((address_space(3)))
; __device__ __forceinline__ void phase_topk_fast(LAS unsigned char* lds, const bf16* Q, const bf16* keysb  , int* EID, float* GATE, bool prestaged  ) {
;     ...
;             for (int p = 0; p < 2; ++p) {
;                 f32x16 acc[4];
; #pragma unroll
;                 for (int blk = 0; blk < 4; ++blk) {
; #pragma unroll
;                     for (int r = 0; r < 16; ++r) acc[blk][r] = 0.f;
; #pragma unroll
;                     for (int ks = 0; ks < 8; ++ks) { const bf16x8 a = *(const LAS bf16x8*)(lds + (p * 128 + 32 * blk + c) * 272 + (16 * ks + 8 * hh) * 2);
;                         acc[blk] = __builtin_amdgcn_mfma_f32_32x32x16_bf16(a, bq[ks], acc[blk], 0, 0, 0); }
;     ...
;                 for (int i = 0; i < 16; ++i) o[i] = __shfl_xor(v[i], 32);
; #pragma unroll
;                 for (int i = 0; i < 16; ++i) v[i] = fmaxf(v[i], o[15 - i]);
;                 bmerge16_desc<0, 64>(v);
; #pragma unroll
;                 for (int i = 0; i < 16; ++i) { if (p == 0) ta[i] = v[i]; else tb[i] = v[i]; }
	v_max_f32_e32 v29, v30, v30
	v_max_f32_e32 v17, v17, v29
	v_max_f32_e32 v16, v16, v28
	v_max_f32_e32 v18, v18, v27
	v_max_f32_e32 v8, v8, v26
	v_max_f32_e32 v15, v15, v25
	v_max_f32_e32 v11, v11, v24
	v_max_f32_e32 v14, v14, v23
	v_max_f32_e32 v6, v6, v22
	v_max_f32_e32 v12, v12, v21
	v_max_f32_e32 v5, v5, v20
	v_max_f32_e32 v7, v7, v19
	v_max_f32_e32 v2, v2, v3
	v_max_f32_e32 v3, v4, v15
	v_min_f32_e32 v4, v4, v15
	v_max_f32_e32 v15, v9, v11
	v_min_f32_e32 v9, v9, v11
	v_max_f32_e32 v11, v13, v14
	v_min_f32_e32 v13, v13, v14
	v_max_f32_e32 v14, v10, v6
	v_min_f32_e32 v6, v10, v6
	v_max_f32_e32 v10, v17, v12
	v_min_f32_e32 v12, v17, v12
	v_max_f32_e32 v17, v16, v5
	v_min_f32_e32 v5, v16, v5
	v_max_f32_e32 v16, v18, v7
	v_min_f32_e32 v7, v18, v7
	v_max_f32_e32 v18, v8, v2
	v_min_f32_e32 v2, v8, v2
	v_max_f32_e32 v8, v3, v10
	v_min_f32_e32 v3, v3, v10
	v_max_f32_e32 v10, v15, v17
	v_min_f32_e32 v15, v15, v17
	v_max_f32_e32 v17, v11, v16
	v_min_f32_e32 v11, v11, v16
	v_max_f32_e32 v16, v14, v18
	v_min_f32_e32 v14, v14, v18
	v_max_f32_e32 v18, v4, v12
	v_min_f32_e32 v4, v4, v12
	v_max_f32_e32 v12, v9, v5
	v_min_f32_e32 v5, v9, v5
	v_max_f32_e32 v9, v13, v7
	v_min_f32_e32 v7, v13, v7
	v_max_f32_e32 v13, v6, v2
	v_min_f32_e32 v2, v6, v2
	v_max_f32_e32 v6, v8, v17
	v_min_f32_e32 v8, v8, v17
	v_max_f32_e32 v17, v10, v16
	v_min_f32_e32 v10, v10, v16
	v_max_f32_e32 v16, v3, v11
	v_min_f32_e32 v3, v3, v11
	v_max_f32_e32 v11, v15, v14
	v_min_f32_e32 v14, v15, v14
	v_max_f32_e32 v15, v18, v9
	v_min_f32_e32 v9, v18, v9
	v_max_f32_e32 v18, v12, v13
	v_min_f32_e32 v12, v12, v13
	v_max_f32_e32 v13, v4, v7
	v_min_f32_e32 v4, v4, v7
	v_max_f32_e32 v7, v5, v2
	v_min_f32_e32 v2, v5, v2
	v_max_f32_e32 v219, v6, v17
	v_min_f32_e32 v205, v6, v17
	v_max_f32_e32 v204, v8, v10
	v_min_f32_e32 v217, v8, v10
	v_max_f32_e32 v218, v16, v11
	v_min_f32_e32 v215, v16, v11
	v_max_f32_e32 v216, v3, v14
	v_min_f32_e32 v213, v3, v14
	v_max_f32_e32 v214, v15, v18
	v_min_f32_e32 v211, v15, v18
	v_max_f32_e32 v212, v9, v12
	v_min_f32_e32 v209, v9, v12
	v_max_f32_e32 v210, v13, v7
	v_min_f32_e32 v208, v13, v7
	v_max_f32_e32 v207, v4, v2
	v_min_f32_e32 v206, v4, v2
	ds_read_b128 v[2:5], v103 offset:34816
	ds_read_b128 v[18:21], v103 offset:34848
	s_waitcnt vmcnt(7) lgkmcnt(1)
	v_mfma_f32_32x32x16_bf16 v[2:17], v[2:5], v[94:97], 0
	s_waitcnt vmcnt(6) lgkmcnt(0)
	v_mfma_f32_32x32x16_bf16 v[2:17], v[18:21], v[90:93], v[2:17]
	ds_read_b128 v[18:21], v103 offset:34880
	ds_read_b128 v[22:25], v103 offset:34912
	s_waitcnt vmcnt(5) lgkmcnt(1)
	v_mfma_f32_32x32x16_bf16 v[2:17], v[18:21], v[86:89], v[2:17]
	s_waitcnt vmcnt(4) lgkmcnt(0)
	v_mfma_f32_32x32x16_bf16 v[2:17], v[22:25], v[82:85], v[2:17]
	ds_read_b128 v[18:21], v103 offset:34944
	ds_read_b128 v[22:25], v103 offset:34976
	s_waitcnt vmcnt(3) lgkmcnt(1)
	v_mfma_f32_32x32x16_bf16 v[2:17], v[18:21], v[78:81], v[2:17]
	s_waitcnt vmcnt(2) lgkmcnt(0)
	v_mfma_f32_32x32x16_bf16 v[2:17], v[22:25], v[74:77], v[2:17]
	ds_read_b128 v[18:21], v103 offset:35008
	ds_read_b128 v[22:25], v103 offset:35040
	s_waitcnt vmcnt(1) lgkmcnt(1)
	v_mfma_f32_32x32x16_bf16 v[2:17], v[18:21], v[70:73], v[2:17]
	ds_read_b128 v[18:21], v103 offset:43520
	ds_read_b128 v[34:37], v103 offset:43552
	s_waitcnt vmcnt(0) lgkmcnt(2)
	v_mfma_f32_32x32x16_bf16 v[2:17], v[22:25], v[66:69], v[2:17]
	s_waitcnt lgkmcnt(1)
	v_mfma_f32_32x32x16_bf16 v[18:33], v[18:21], v[94:97], 0
	s_waitcnt lgkmcnt(0)
	v_mfma_f32_32x32x16_bf16 v[18:33], v[34:37], v[90:93], v[18:33]
	ds_read_b128 v[34:37], v103 offset:43584
	ds_read_b128 v[38:41], v103 offset:43616
	s_waitcnt lgkmcnt(1)
	v_mfma_f32_32x32x16_bf16 v[18:33], v[34:37], v[86:89], v[18:33]
	s_waitcnt lgkmcnt(0)
	v_mfma_f32_32x32x16_bf16 v[18:33], v[38:41], v[82:85], v[18:33]
	ds_read_b128 v[34:37], v103 offset:43648
	ds_read_b128 v[38:41], v103 offset:43680
	s_waitcnt lgkmcnt(1)
	v_mfma_f32_32x32x16_bf16 v[18:33], v[34:37], v[78:81], v[18:33]
	s_waitcnt lgkmcnt(0)
	v_mfma_f32_32x32x16_bf16 v[18:33], v[38:41], v[74:77], v[18:33]
	ds_read_b128 v[34:37], v103 offset:43712
	ds_read_b128 v[38:41], v103 offset:43744
	s_waitcnt lgkmcnt(1)
	v_mfma_f32_32x32x16_bf16 v[18:33], v[34:37], v[70:73], v[18:33]
	ds_read_b128 v[34:37], v103 offset:52224
	ds_read_b128 v[50:53], v103 offset:52256
	s_waitcnt lgkmcnt(2)
	v_mfma_f32_32x32x16_bf16 v[18:33], v[38:41], v[66:69], v[18:33]
	s_waitcnt lgkmcnt(1)
	v_mfma_f32_32x32x16_bf16 v[34:49], v[34:37], v[94:97], 0
	s_waitcnt lgkmcnt(0)
	v_mfma_f32_32x32x16_bf16 v[34:49], v[50:53], v[90:93], v[34:49]
	ds_read_b128 v[50:53], v103 offset:52288
	ds_read_b128 v[54:57], v103 offset:52320
	s_waitcnt lgkmcnt(1)
	v_mfma_f32_32x32x16_bf16 v[34:49], v[50:53], v[86:89], v[34:49]
	s_waitcnt lgkmcnt(0)
	v_mfma_f32_32x32x16_bf16 v[34:49], v[54:57], v[82:85], v[34:49]
	ds_read_b128 v[50:53], v103 offset:52352
	ds_read_b128 v[54:57], v103 offset:52384
	s_waitcnt lgkmcnt(1)
	v_mfma_f32_32x32x16_bf16 v[34:49], v[50:53], v[78:81], v[34:49]
	s_waitcnt lgkmcnt(0)
	v_mfma_f32_32x32x16_bf16 v[34:49], v[54:57], v[74:77], v[34:49]
	ds_read_b128 v[50:53], v103 offset:52416
	ds_read_b128 v[54:57], v103 offset:52448
	s_waitcnt lgkmcnt(1)
	v_mfma_f32_32x32x16_bf16 v[34:49], v[50:53], v[70:73], v[34:49]
	ds_read_b128 v[50:53], v103 offset:60928
	ds_read_b128 v[220:223], v103 offset:60960
	s_waitcnt lgkmcnt(2)
	v_mfma_f32_32x32x16_bf16 v[34:49], v[54:57], v[66:69], v[34:49]
	s_waitcnt lgkmcnt(1)
	v_mfma_f32_32x32x16_bf16 v[50:65], v[50:53], v[94:97], 0
	s_waitcnt lgkmcnt(0)
	v_mfma_f32_32x32x16_bf16 v[50:65], v[220:223], v[90:93], v[50:65]
	ds_read_b128 v[90:93], v103 offset:60992
	ds_read_b128 v[94:97], v103 offset:61024
	s_waitcnt lgkmcnt(1)
; #define GAS __attribute__((address_space(1)))
; #define LAS __attribute__((address_space(3)))
; __device__ __forceinline__ void phase_topk_fast(LAS unsigned char* lds, const bf16* Q, const bf16* keysb  , int* EID, float* GATE, bool prestaged  ) {
;     ...
; #pragma unroll
;                     for (int ks = 0; ks < 8; ++ks) { const bf16x8 a = *(const LAS bf16x8*)(lds + (p * 128 + 32 * blk + c) * 272 + (16 * ks + 8 * hh) * 2);
;                         acc[blk] = __builtin_amdgcn_mfma_f32_32x32x16_bf16(a, bq[ks], acc[blk], 0, 0, 0); }
;                 }
;                 __builtin_amdgcn_sched_barrier(0);
;                 { const int nit = (p == 0) ? it : it + 1; const int np = (p == 0) ? 1 : 0;
;                   const size_t ntok0 = (size_t)(rank * 8 + wave + 256 * (nit < 4 ? nit : 3)) * 32;
;                   int cq = c; asm volatile("" : "+v"(cq)); const bf16* qrow = Q + (ntok0 + cq) * 2048 + h * 256 + np * 128 + 8 * hh;
; #pragma unroll
;                   for (int ks = 0; ks < 8; ++ks) bq[ks] = *(const GAS bf16x8*)(qrow + 16 * ks); }
;                 __builtin_amdgcn_sched_barrier(0);
;                 float v[64];
; #pragma unroll
;                 for (int blk = 0; blk < 4; ++blk)
; #pragma unroll
;                     for (int r = 0; r < 16; ++r)
;                     { const float sv = acc[blk][r]; v[blk * 16 + r] = __uint_as_float((__float_as_uint(sv) & ~127u) | (unsigned)(32 * blk + (r & 3) + 8 * (r >> 2)) | (unsigned)(hh << 2)); }
;                 __builtin_amdgcn_sched_barrier(0);
;                 bsort16_desc<0, 64>(v); bsort16_desc<16, 64>(v); bsort16_desc<32, 64>(v); bsort16_desc<48, 64>(v);
	v_mfma_f32_32x32x16_bf16 v[50:65], v[90:93], v[86:89], v[50:65]
	s_waitcnt lgkmcnt(0)
	v_mfma_f32_32x32x16_bf16 v[50:65], v[94:97], v[82:85], v[50:65]
	ds_read_b128 v[82:85], v103 offset:61056
	ds_read_b128 v[86:89], v103 offset:61088
	s_waitcnt lgkmcnt(1)
	v_mfma_f32_32x32x16_bf16 v[50:65], v[82:85], v[78:81], v[50:65]
	s_waitcnt lgkmcnt(0)
	v_mfma_f32_32x32x16_bf16 v[50:65], v[86:89], v[74:77], v[50:65]
	ds_read_b128 v[74:77], v103 offset:61120
	ds_read_b128 v[78:81], v103 offset:61152
	s_waitcnt lgkmcnt(1)
	v_mfma_f32_32x32x16_bf16 v[50:65], v[74:77], v[70:73], v[50:65]
	s_waitcnt lgkmcnt(0)
	v_mfma_f32_32x32x16_bf16 v[50:65], v[78:81], v[66:69], v[50:65]
	s_min_u32 s3, s2, 3
	s_lshl_b32 s3, s3, 8
	s_add_i32 s18, s3, s10
	s_ashr_i32 s19, s18, 31
	v_mov_b32_e32 v66, v1
	s_lshl_b64 s[18:19], s[18:19], 17
	s_add_u32 s18, s20, s18
	v_ashrrev_i32_e32 v67, 31, v66
	s_addc_u32 s19, s21, s19
	v_lshlrev_b64 v[66:67], 12, v[66:67]
	v_lshl_add_u64 v[66:67], s[18:19], 0, v[66:67]
	v_lshl_add_u64 v[66:67], v[66:67], 0, s[6:7]
	v_lshl_add_u64 v[70:71], v[66:67], 0, v[98:99]
	global_load_dwordx4 v[90:93], v[70:71], off
	global_load_dwordx4 v[94:97], v[70:71], off offset:32
	global_load_dwordx4 v[82:85], v[70:71], off offset:64
	global_load_dwordx4 v[86:89], v[70:71], off offset:96
	global_load_dwordx4 v[74:77], v[70:71], off offset:128
	global_load_dwordx4 v[78:81], v[70:71], off offset:160
	global_load_dwordx4 v[66:69], v[70:71], off offset:192
	s_nop 0
	global_load_dwordx4 v[70:73], v[70:71], off offset:224
	v_and_or_b32 v2, v2, s28, v101
	v_and_or_b32 v3, v3, s28, v104
	v_and_or_b32 v4, v4, s28, v105
	v_and_or_b32 v5, v5, s28, v106
	v_and_or_b32 v6, v6, s28, v107
	v_and_or_b32 v7, v7, s28, v108
	v_and_or_b32 v8, v8, s28, v109
	v_and_or_b32 v9, v9, s28, v110
	v_and_or_b32 v10, v10, s28, v111
	v_and_or_b32 v11, v11, s28, v112
	v_and_or_b32 v12, v12, s28, v113
	v_and_or_b32 v13, v13, s28, v114
	v_and_or_b32 v14, v14, s28, v115
	v_and_or_b32 v15, v15, s28, v116
	v_and_or_b32 v16, v16, s28, v117
	v_and_or_b32 v17, v17, s28, v118
	v_and_or_b32 v18, v18, s28, v119
	v_and_or_b32 v19, v19, s28, v120
	v_and_or_b32 v20, v20, s28, v121
	v_and_or_b32 v21, v21, s28, v122
	v_and_or_b32 v22, v22, s28, v123
	v_and_or_b32 v23, v23, s28, v124
	v_and_or_b32 v24, v24, s28, v125
	v_and_or_b32 v25, v25, s28, v126
	v_and_or_b32 v26, v26, s28, v127
	v_and_or_b32 v27, v27, s28, v128
	v_and_or_b32 v28, v28, s28, v129
	v_and_or_b32 v29, v29, s28, v130
	v_and_or_b32 v30, v30, s28, v131
	v_and_or_b32 v31, v31, s28, v132
	v_and_or_b32 v32, v32, s28, v133
	v_and_or_b32 v33, v33, s28, v134
	v_and_or_b32 v34, v34, s28, v135
	v_and_or_b32 v35, v35, s28, v136
	v_and_or_b32 v36, v36, s28, v137
	v_and_or_b32 v37, v37, s28, v138
	v_and_or_b32 v38, v38, s28, v139
	v_and_or_b32 v39, v39, s28, v140
	v_and_or_b32 v40, v40, s28, v141
	v_and_or_b32 v41, v41, s28, v142
	v_and_or_b32 v42, v42, s28, v143
	v_and_or_b32 v43, v43, s28, v144
	v_and_or_b32 v44, v44, s28, v145
	v_and_or_b32 v45, v45, s28, v146
	v_and_or_b32 v46, v46, s28, v147
	v_and_or_b32 v47, v47, s28, v148
	v_and_or_b32 v48, v48, s28, v149
	v_and_or_b32 v49, v49, s28, v150
	v_and_or_b32 v50, v50, s28, v151
	v_and_or_b32 v51, v51, s28, v152
	v_and_or_b32 v52, v52, s28, v153
	v_and_or_b32 v53, v53, s28, v154
	v_and_or_b32 v54, v54, s28, v155
	v_and_or_b32 v55, v55, s28, v156
	v_and_or_b32 v56, v56, s28, v157
	v_and_or_b32 v57, v57, s28, v158
	v_and_or_b32 v58, v58, s28, v159
	v_and_or_b32 v59, v59, s28, v160
	v_and_or_b32 v60, v60, s28, v161
	v_and_or_b32 v61, v61, s28, v162
	v_and_or_b32 v62, v62, s28, v163
	v_and_or_b32 v63, v63, s28, v164
	v_and_or_b32 v64, v64, s28, v165
	v_and_or_b32 v65, v65, s28, v166
	v_max_f32_e32 v220, v2, v15
	v_min_f32_e32 v2, v2, v15
	v_max_f32_e32 v15, v3, v14
	v_min_f32_e32 v3, v3, v14
	v_max_f32_e32 v14, v17, v17
	v_max_f32_e32 v228, v18, v31
	v_min_f32_e32 v18, v18, v31
	v_max_f32_e32 v31, v19, v30
	v_min_f32_e32 v19, v19, v30
	v_max_f32_e32 v30, v33, v33
	v_max_f32_e32 v236, v34, v47
	v_min_f32_e32 v34, v34, v47
	v_max_f32_e32 v47, v35, v46
	v_min_f32_e32 v35, v35, v46
	v_max_f32_e32 v46, v49, v49
	v_max_f32_e32 v244, v50, v63
	v_min_f32_e32 v50, v50, v63
	v_max_f32_e32 v63, v51, v62
	v_min_f32_e32 v51, v51, v62
	v_max_f32_e32 v62, v65, v65
	v_max_f32_e32 v17, v4, v14
	v_min_f32_e32 v4, v4, v14
	v_max_f32_e32 v14, v16, v16
	v_max_f32_e32 v33, v20, v30
	v_min_f32_e32 v20, v20, v30
	v_max_f32_e32 v30, v32, v32
	v_max_f32_e32 v49, v36, v46
	v_min_f32_e32 v36, v36, v46
	v_max_f32_e32 v46, v48, v48
	v_max_f32_e32 v65, v52, v62
	v_min_f32_e32 v52, v52, v62
	v_max_f32_e32 v62, v64, v64
	v_max_f32_e32 v16, v5, v14
	v_min_f32_e32 v5, v5, v14
	v_max_f32_e32 v14, v6, v10
	v_min_f32_e32 v6, v6, v10
	v_max_f32_e32 v10, v7, v8
	v_min_f32_e32 v7, v7, v8
	v_max_f32_e32 v8, v13, v13
	v_max_f32_e32 v32, v21, v30
	v_min_f32_e32 v21, v21, v30
	v_max_f32_e32 v30, v22, v26
	v_min_f32_e32 v22, v22, v26
	v_max_f32_e32 v26, v23, v24
	v_min_f32_e32 v23, v23, v24
	v_max_f32_e32 v24, v29, v29
	v_max_f32_e32 v48, v37, v46
	v_min_f32_e32 v37, v37, v46
	v_max_f32_e32 v46, v38, v42
	v_min_f32_e32 v38, v38, v42
	v_max_f32_e32 v42, v39, v40
	v_min_f32_e32 v39, v39, v40
	v_max_f32_e32 v40, v45, v45
	v_max_f32_e32 v64, v53, v62
	v_min_f32_e32 v53, v53, v62
	v_max_f32_e32 v62, v54, v58
	v_min_f32_e32 v54, v54, v58
	v_max_f32_e32 v58, v55, v56
	v_min_f32_e32 v55, v55, v56
	v_max_f32_e32 v56, v61, v61
	v_max_f32_e32 v13, v9, v8
	v_min_f32_e32 v8, v9, v8
	v_max_f32_e32 v9, v12, v12
	v_max_f32_e32 v29, v25, v24
	v_min_f32_e32 v24, v25, v24
	v_max_f32_e32 v25, v28, v28
	v_max_f32_e32 v45, v41, v40
	v_min_f32_e32 v40, v41, v40
; #define CEF_D(a, b) { const float hi_ = fmaxf((a), (b)), lo_ = fminf((a), (b)); (a) = hi_; (b) = lo_; }
; template <int OFF, int NV> __device__ __forceinline__ void bsort16_desc(float (&v)[NV]) {
; #pragma unroll
;     for (int t = 0; t < 60; ++t) CEF_D(v[OFF + sn16_a(t)], v[OFF + sn16_b(t)])
; }
; __device__ __forceinline__ void phase_topk_fast(LAS unsigned char* lds, const bf16* Q, const bf16* keysb  , int* EID, float* GATE, bool prestaged  ) {
;     ...
;                 bsort16_desc<0, 64>(v); bsort16_desc<16, 64>(v); bsort16_desc<32, 64>(v); bsort16_desc<48, 64>(v);
	v_max_f32_e32 v41, v44, v44
	v_max_f32_e32 v61, v57, v56
	v_min_f32_e32 v56, v57, v56
	v_max_f32_e32 v57, v60, v60
	v_max_f32_e32 v12, v11, v9
	v_min_f32_e32 v9, v11, v9
	v_max_f32_e32 v28, v27, v25
	v_min_f32_e32 v25, v27, v25
	v_max_f32_e32 v44, v43, v41
	v_min_f32_e32 v41, v43, v41
	v_max_f32_e32 v60, v59, v57
	v_min_f32_e32 v57, v59, v57
	v_max_f32_e32 v11, v220, v10
	v_min_f32_e32 v10, v220, v10
	v_max_f32_e32 v220, v15, v13
	v_min_f32_e32 v13, v15, v13
	v_max_f32_e32 v15, v17, v12
	v_min_f32_e32 v12, v17, v12
	v_max_f32_e32 v17, v16, v14
	v_min_f32_e32 v14, v16, v14
	v_max_f32_e32 v16, v7, v2
	v_min_f32_e32 v2, v7, v2
	v_max_f32_e32 v7, v6, v5
	v_min_f32_e32 v5, v6, v5
	v_max_f32_e32 v6, v9, v4
	v_min_f32_e32 v4, v9, v4
	v_max_f32_e32 v9, v8, v3
	v_min_f32_e32 v3, v8, v3
	v_max_f32_e32 v27, v228, v26
	v_min_f32_e32 v26, v228, v26
	v_max_f32_e32 v228, v31, v29
	v_min_f32_e32 v29, v31, v29
	v_max_f32_e32 v31, v33, v28
	v_min_f32_e32 v28, v33, v28
	v_max_f32_e32 v33, v32, v30
	v_min_f32_e32 v30, v32, v30
	v_max_f32_e32 v32, v23, v18
	v_min_f32_e32 v18, v23, v18
	v_max_f32_e32 v23, v22, v21
	v_min_f32_e32 v21, v22, v21
	v_max_f32_e32 v22, v25, v20
	v_min_f32_e32 v20, v25, v20
	v_max_f32_e32 v25, v24, v19
	v_min_f32_e32 v19, v24, v19
	v_max_f32_e32 v43, v236, v42
	v_min_f32_e32 v42, v236, v42
	v_max_f32_e32 v236, v47, v45
	v_min_f32_e32 v45, v47, v45
	v_max_f32_e32 v47, v49, v44
	v_min_f32_e32 v44, v49, v44
	v_max_f32_e32 v49, v48, v46
	v_min_f32_e32 v46, v48, v46
	v_max_f32_e32 v48, v39, v34
	v_min_f32_e32 v34, v39, v34
	v_max_f32_e32 v39, v38, v37
	v_min_f32_e32 v37, v38, v37
	v_max_f32_e32 v38, v41, v36
	v_min_f32_e32 v36, v41, v36
	v_max_f32_e32 v41, v40, v35
	v_min_f32_e32 v35, v40, v35
	v_max_f32_e32 v59, v244, v58
	v_min_f32_e32 v58, v244, v58
	v_max_f32_e32 v244, v63, v61
	v_min_f32_e32 v61, v63, v61
	v_max_f32_e32 v63, v65, v60
	v_min_f32_e32 v60, v65, v60
	v_max_f32_e32 v65, v64, v62
	v_min_f32_e32 v62, v64, v62
	v_max_f32_e32 v64, v55, v50
	v_min_f32_e32 v50, v55, v50
	v_max_f32_e32 v55, v54, v53
	v_min_f32_e32 v53, v54, v53
	v_max_f32_e32 v54, v57, v52
	v_min_f32_e32 v52, v57, v52
	v_max_f32_e32 v57, v56, v51
	v_min_f32_e32 v51, v56, v51
	v_max_f32_e32 v8, v11, v220
	v_min_f32_e32 v11, v11, v220
	v_max_f32_e32 v220, v15, v17
	v_min_f32_e32 v15, v15, v17
	v_max_f32_e32 v17, v14, v10
	v_min_f32_e32 v10, v14, v10
	v_max_f32_e32 v14, v16, v7
	v_min_f32_e32 v7, v16, v7
	v_max_f32_e32 v16, v13, v12
	v_min_f32_e32 v12, v13, v12
	v_max_f32_e32 v13, v6, v9
	v_min_f32_e32 v6, v6, v9
	v_max_f32_e32 v9, v3, v2
	v_min_f32_e32 v2, v3, v2
	v_max_f32_e32 v3, v5, v4
	v_min_f32_e32 v4, v5, v4
	v_max_f32_e32 v24, v27, v228
	v_min_f32_e32 v27, v27, v228
	v_max_f32_e32 v228, v31, v33
	v_min_f32_e32 v31, v31, v33
	v_max_f32_e32 v33, v30, v26
	v_min_f32_e32 v26, v30, v26
	v_max_f32_e32 v30, v32, v23
	v_min_f32_e32 v23, v32, v23
	v_max_f32_e32 v32, v29, v28
	v_min_f32_e32 v28, v29, v28
	v_max_f32_e32 v29, v22, v25
	v_min_f32_e32 v22, v22, v25
	v_max_f32_e32 v25, v19, v18
	v_min_f32_e32 v18, v19, v18
	v_max_f32_e32 v19, v21, v20
	v_min_f32_e32 v20, v21, v20
	v_max_f32_e32 v40, v43, v236
	v_min_f32_e32 v43, v43, v236
	v_max_f32_e32 v236, v47, v49
	v_min_f32_e32 v47, v47, v49
	v_max_f32_e32 v49, v46, v42
	v_min_f32_e32 v42, v46, v42
	v_max_f32_e32 v46, v48, v39
	v_min_f32_e32 v39, v48, v39
	v_max_f32_e32 v48, v45, v44
	v_min_f32_e32 v44, v45, v44
	v_max_f32_e32 v45, v38, v41
	v_min_f32_e32 v38, v38, v41
	v_max_f32_e32 v41, v35, v34
	v_min_f32_e32 v34, v35, v34
	v_max_f32_e32 v35, v37, v36
	v_min_f32_e32 v36, v37, v36
	v_max_f32_e32 v56, v59, v244
	v_min_f32_e32 v59, v59, v244
	v_max_f32_e32 v244, v63, v65
	v_min_f32_e32 v63, v63, v65
	v_max_f32_e32 v65, v62, v58
	v_min_f32_e32 v58, v62, v58
	v_max_f32_e32 v62, v64, v55
	v_min_f32_e32 v55, v64, v55
	v_max_f32_e32 v64, v61, v60
	v_min_f32_e32 v60, v61, v60
	v_max_f32_e32 v61, v54, v57
	v_min_f32_e32 v54, v54, v57
	v_max_f32_e32 v57, v51, v50
	v_min_f32_e32 v50, v51, v50
	v_max_f32_e32 v51, v53, v52
	v_min_f32_e32 v52, v53, v52
	v_min_f32_e32 v5, v8, v220
	v_max_f32_e32 v221, v11, v15
	v_min_f32_e32 v11, v11, v15
	v_max_f32_e32 v15, v17, v13
	v_min_f32_e32 v13, v17, v13
	v_max_f32_e32 v17, v10, v6
	v_min_f32_e32 v6, v10, v6
	v_max_f32_e32 v10, v14, v16
	v_min_f32_e32 v14, v14, v16
	v_max_f32_e32 v16, v7, v12
	v_min_f32_e32 v7, v7, v12
	v_max_f32_e32 v12, v9, v3
	v_min_f32_e32 v3, v9, v3
	v_max_f32_e32 v9, v2, v4
	v_min_f32_e32 v21, v24, v228
	v_max_f32_e32 v229, v27, v31
	v_min_f32_e32 v27, v27, v31
	v_max_f32_e32 v31, v33, v29
	v_min_f32_e32 v29, v33, v29
	v_max_f32_e32 v33, v26, v22
	v_min_f32_e32 v22, v26, v22
	v_max_f32_e32 v26, v30, v32
	v_min_f32_e32 v30, v30, v32
	v_max_f32_e32 v32, v23, v28
	v_min_f32_e32 v23, v23, v28
	v_max_f32_e32 v28, v25, v19
	v_min_f32_e32 v19, v25, v19
	v_max_f32_e32 v25, v18, v20
	v_min_f32_e32 v37, v40, v236
	v_max_f32_e32 v237, v43, v47
	v_min_f32_e32 v43, v43, v47
	v_max_f32_e32 v47, v49, v45
	v_min_f32_e32 v45, v49, v45
	v_max_f32_e32 v49, v42, v38
	v_min_f32_e32 v38, v42, v38
	v_max_f32_e32 v42, v46, v48
	v_min_f32_e32 v46, v46, v48
	v_max_f32_e32 v48, v39, v44
	v_min_f32_e32 v39, v39, v44
	v_max_f32_e32 v44, v41, v35
	v_min_f32_e32 v35, v41, v35
	v_max_f32_e32 v41, v34, v36
	v_min_f32_e32 v53, v56, v244
	v_max_f32_e32 v245, v59, v63
	v_min_f32_e32 v59, v59, v63
	v_max_f32_e32 v63, v65, v61
	v_min_f32_e32 v61, v65, v61
	v_max_f32_e32 v65, v58, v54
	v_min_f32_e32 v54, v58, v54
	v_max_f32_e32 v58, v62, v64
	v_min_f32_e32 v62, v62, v64
	v_max_f32_e32 v64, v55, v60
	v_min_f32_e32 v55, v55, v60
	v_max_f32_e32 v60, v57, v51
	v_min_f32_e32 v51, v57, v51
	v_max_f32_e32 v57, v50, v52
; #define CEF_D(a, b) { const float hi_ = fmaxf((a), (b)), lo_ = fminf((a), (b)); (a) = hi_; (b) = lo_; }
; template <int OFF, int NV> __device__ __forceinline__ void bsort16_desc(float (&v)[NV]) {
; #pragma unroll
;     for (int t = 0; t < 60; ++t) CEF_D(v[OFF + sn16_a(t)], v[OFF + sn16_b(t)])
; }
; template <int OA, int NV> __device__ __forceinline__ void bmerge16_desc(float (&v)[NV]) {
; #pragma unroll
;     for (int j = 8; j > 0; j >>= 1) {
; #pragma unroll
;         for (int i = 0; i < 16; ++i) { const int l = i ^ j; if (l > i) CEF_D(v[OA + i], v[OA + l]) }
;     }
; }
; template <int OA, int OB, int NV> __device__ __forceinline__ void merge_top16(float (&v)[NV]) {
; #pragma unroll
;     for (int i = 0; i < 16; ++i) v[OA + i] = fmaxf(v[OA + i], v[OB + 15 - i]);
;     bmerge16_desc<OA, NV>(v);
; }
	v_min_f32_e32 v2, v2, v4
	v_max_f32_e32 v4, v221, v5
	v_min_f32_e32 v5, v221, v5
	v_max_f32_e32 v221, v11, v12
	v_min_f32_e32 v11, v11, v12
	v_max_f32_e32 v12, v15, v10
	v_min_f32_e32 v10, v15, v10
	v_max_f32_e32 v15, v17, v14
	v_min_f32_e32 v14, v17, v14
	v_max_f32_e32 v17, v16, v13
	v_min_f32_e32 v13, v16, v13
	v_max_f32_e32 v16, v7, v6
	v_min_f32_e32 v6, v7, v6
	v_max_f32_e32 v7, v9, v3
	v_min_f32_e32 v18, v18, v20
	v_max_f32_e32 v20, v229, v21
	v_min_f32_e32 v21, v229, v21
	v_max_f32_e32 v229, v27, v28
	v_min_f32_e32 v27, v27, v28
	v_max_f32_e32 v28, v31, v26
	v_min_f32_e32 v26, v31, v26
	v_max_f32_e32 v31, v33, v30
	v_min_f32_e32 v30, v33, v30
	v_max_f32_e32 v33, v32, v29
	v_min_f32_e32 v29, v32, v29
	v_max_f32_e32 v32, v23, v22
	v_min_f32_e32 v22, v23, v22
	v_max_f32_e32 v23, v25, v19
	v_min_f32_e32 v34, v34, v36
	v_max_f32_e32 v36, v237, v37
	v_min_f32_e32 v37, v237, v37
	v_max_f32_e32 v237, v43, v44
	v_min_f32_e32 v43, v43, v44
	v_max_f32_e32 v44, v47, v42
	v_min_f32_e32 v42, v47, v42
	v_max_f32_e32 v47, v49, v46
	v_min_f32_e32 v46, v49, v46
	v_max_f32_e32 v49, v48, v45
	v_min_f32_e32 v45, v48, v45
	v_max_f32_e32 v48, v39, v38
	v_min_f32_e32 v38, v39, v38
	v_max_f32_e32 v39, v41, v35
	v_min_f32_e32 v50, v50, v52
	v_max_f32_e32 v52, v245, v53
	v_min_f32_e32 v53, v245, v53
	v_max_f32_e32 v245, v59, v60
	v_min_f32_e32 v59, v59, v60
	v_max_f32_e32 v60, v63, v58
	v_min_f32_e32 v58, v63, v58
	v_max_f32_e32 v63, v65, v62
	v_min_f32_e32 v62, v65, v62
	v_max_f32_e32 v65, v64, v61
	v_min_f32_e32 v61, v64, v61
	v_max_f32_e32 v64, v55, v54
	v_min_f32_e32 v54, v55, v54
	v_max_f32_e32 v55, v57, v51
	v_min_f32_e32 v3, v9, v3
	v_max_f32_e32 v222, v5, v10
	v_min_f32_e32 v5, v5, v10
	v_max_f32_e32 v10, v15, v17
	v_min_f32_e32 v15, v15, v17
	v_max_f32_e32 v17, v14, v13
	v_min_f32_e32 v13, v14, v13
	v_max_f32_e32 v14, v16, v7
	v_min_f32_e32 v19, v25, v19
	v_max_f32_e32 v230, v21, v26
	v_min_f32_e32 v21, v21, v26
	v_max_f32_e32 v26, v31, v33
	v_min_f32_e32 v31, v31, v33
	v_max_f32_e32 v33, v30, v29
	v_min_f32_e32 v29, v30, v29
	v_max_f32_e32 v30, v32, v23
	v_min_f32_e32 v35, v41, v35
	v_max_f32_e32 v238, v37, v42
	v_min_f32_e32 v37, v37, v42
	v_max_f32_e32 v42, v47, v49
	v_min_f32_e32 v47, v47, v49
	v_max_f32_e32 v49, v46, v45
	v_min_f32_e32 v45, v46, v45
	v_max_f32_e32 v46, v48, v39
	v_min_f32_e32 v51, v57, v51
	v_max_f32_e32 v246, v53, v58
	v_min_f32_e32 v53, v53, v58
	v_max_f32_e32 v58, v63, v65
	v_min_f32_e32 v63, v63, v65
	v_max_f32_e32 v65, v62, v61
	v_min_f32_e32 v61, v62, v61
	v_max_f32_e32 v62, v64, v55
	v_min_f32_e32 v7, v16, v7
	v_max_f32_e32 v16, v6, v3
	v_max_f32_e32 v223, v221, v5
	v_min_f32_e32 v5, v221, v5
	v_max_f32_e32 v221, v14, v11
	v_min_f32_e32 v11, v14, v11
	v_min_f32_e32 v23, v32, v23
	v_max_f32_e32 v32, v22, v19
	v_max_f32_e32 v231, v229, v21
	v_min_f32_e32 v21, v229, v21
	v_max_f32_e32 v229, v30, v27
	v_min_f32_e32 v27, v30, v27
	v_min_f32_e32 v39, v48, v39
	v_max_f32_e32 v48, v38, v35
	v_max_f32_e32 v239, v237, v37
	v_min_f32_e32 v37, v237, v37
	v_max_f32_e32 v237, v46, v43
	v_min_f32_e32 v43, v46, v43
	v_min_f32_e32 v55, v64, v55
	v_max_f32_e32 v64, v54, v51
	v_max_f32_e32 v247, v245, v53
	v_min_f32_e32 v53, v245, v53
	v_max_f32_e32 v245, v62, v59
	v_min_f32_e32 v59, v62, v59
	v_min_f32_e32 v9, v4, v12
	v_max_f32_e32 v14, v16, v7
	v_min_f32_e32 v7, v16, v7
	v_max_f32_e32 v16, v223, v10
	v_min_f32_e32 v10, v223, v10
	v_max_f32_e32 v223, v5, v15
	v_min_f32_e32 v5, v5, v15
	v_max_f32_e32 v15, v17, v221
	v_min_f32_e32 v17, v17, v221
	v_max_f32_e32 v221, v13, v11
	v_min_f32_e32 v25, v20, v28
	v_max_f32_e32 v30, v32, v23
	v_min_f32_e32 v23, v32, v23
	v_max_f32_e32 v32, v231, v26
	v_min_f32_e32 v26, v231, v26
	v_max_f32_e32 v231, v21, v31
	v_min_f32_e32 v21, v21, v31
	v_max_f32_e32 v31, v33, v229
	v_min_f32_e32 v33, v33, v229
	v_max_f32_e32 v229, v29, v27
	v_min_f32_e32 v41, v36, v44
	v_max_f32_e32 v46, v48, v39
	v_min_f32_e32 v39, v48, v39
	v_max_f32_e32 v48, v239, v42
	v_min_f32_e32 v42, v239, v42
	v_max_f32_e32 v239, v37, v47
	v_min_f32_e32 v37, v37, v47
	v_max_f32_e32 v47, v49, v237
	v_min_f32_e32 v49, v49, v237
	v_max_f32_e32 v237, v45, v43
	v_min_f32_e32 v57, v52, v60
	v_max_f32_e32 v62, v64, v55
	v_min_f32_e32 v55, v64, v55
	v_max_f32_e32 v64, v247, v58
	v_min_f32_e32 v58, v247, v58
	v_max_f32_e32 v247, v53, v63
	v_min_f32_e32 v53, v53, v63
	v_max_f32_e32 v63, v65, v245
	v_min_f32_e32 v65, v65, v245
	v_max_f32_e32 v245, v61, v59
	v_min_f32_e32 v3, v6, v3
	v_min_f32_e32 v6, v222, v9
	v_min_f32_e32 v11, v13, v11
	v_min_f32_e32 v224, v10, v223
	v_max_f32_e32 v225, v15, v5
	v_min_f32_e32 v5, v15, v5
	v_max_f32_e32 v15, v17, v221
	v_min_f32_e32 v19, v22, v19
	v_min_f32_e32 v22, v230, v25
	v_min_f32_e32 v27, v29, v27
	v_min_f32_e32 v232, v26, v231
	v_max_f32_e32 v233, v31, v21
	v_min_f32_e32 v21, v31, v21
	v_max_f32_e32 v31, v33, v229
	v_min_f32_e32 v35, v38, v35
	v_min_f32_e32 v38, v238, v41
	v_min_f32_e32 v43, v45, v43
	v_min_f32_e32 v240, v42, v239
	v_max_f32_e32 v241, v47, v37
	v_min_f32_e32 v37, v47, v37
	v_max_f32_e32 v47, v49, v237
	v_min_f32_e32 v51, v54, v51
	v_min_f32_e32 v54, v246, v57
	v_min_f32_e32 v59, v61, v59
	v_min_f32_e32 v248, v58, v247
	v_max_f32_e32 v249, v63, v53
	v_min_f32_e32 v53, v63, v53
	v_max_f32_e32 v63, v65, v245
	v_min_f32_e32 v13, v16, v6
	v_min_f32_e32 v17, v17, v221
	v_min_f32_e32 v221, v14, v11
	v_min_f32_e32 v226, v224, v225
	v_min_f32_e32 v227, v5, v15
	v_min_f32_e32 v29, v32, v22
	v_min_f32_e32 v33, v33, v229
	v_min_f32_e32 v229, v30, v27
	v_min_f32_e32 v234, v232, v233
	v_min_f32_e32 v235, v21, v31
	v_min_f32_e32 v45, v48, v38
	v_min_f32_e32 v49, v49, v237
	v_min_f32_e32 v237, v46, v43
; template <int OA, int OB, int NV> __device__ __forceinline__ void merge_top16(float (&v)[NV]) {
; #pragma unroll
;     for (int i = 0; i < 16; ++i) v[OA + i] = fmaxf(v[OA + i], v[OB + 15 - i]);
;     bmerge16_desc<OA, NV>(v);
; }
; __device__ __forceinline__ void phase_topk_fast(LAS unsigned char* lds, const bf16* Q, const bf16* keysb  , int* EID, float* GATE, bool prestaged  ) {
;     ...
;                 merge_top16<0, 16, 64>(v); merge_top16<32, 48, 64>(v); merge_top16<0, 32, 64>(v);
;                 float o[16];
; #pragma unroll
;                 for (int i = 0; i < 16; ++i) o[i] = __shfl_xor(v[i], 32);
; #pragma unroll
;                 for (int i = 0; i < 16; ++i) v[i] = fmaxf(v[i], o[15 - i]);
;                 bmerge16_desc<0, 64>(v);
	v_min_f32_e32 v242, v240, v241
	v_min_f32_e32 v243, v37, v47
	v_min_f32_e32 v61, v64, v54
	v_min_f32_e32 v65, v65, v245
	v_min_f32_e32 v245, v62, v59
	v_min_f32_e32 v250, v248, v249
	v_min_f32_e32 v251, v53, v63
	v_max3_f32 v8, v8, v220, v18
	v_max3_f32 v4, v4, v12, v19
	v_max3_f32 v9, v222, v9, v23
	v_max3_f32 v6, v16, v6, v229
	v_max3_f32 v12, v13, v30, v27
	v_max3_f32 v10, v10, v223, v33
	v_max3_f32 v13, v224, v225, v235
	v_max3_f32 v16, v226, v21, v31
	v_max3_f32 v5, v5, v15, v234
	v_max3_f32 v15, v227, v232, v233
	v_max3_f32 v17, v17, v26, v231
	v_max3_f32 v11, v14, v11, v29
	v_max3_f32 v14, v221, v32, v22
	v_max3_f32 v7, v7, v230, v25
	v_max3_f32 v3, v3, v20, v28
	v_max3_f32 v2, v2, v24, v228
	v_max3_f32 v26, v40, v236, v50
	v_max3_f32 v27, v36, v44, v51
	v_max3_f32 v28, v238, v41, v55
	v_max3_f32 v29, v48, v38, v245
	v_max3_f32 v30, v45, v62, v59
	v_max3_f32 v31, v42, v239, v65
	v_max3_f32 v32, v240, v241, v251
	v_max3_f32 v33, v242, v53, v63
	v_max3_f32 v36, v37, v47, v250
	v_max3_f32 v37, v243, v248, v249
	v_max3_f32 v38, v49, v58, v247
	v_max3_f32 v40, v46, v43, v61
	v_max3_f32 v41, v237, v64, v54
	v_max3_f32 v39, v39, v246, v57
	v_max3_f32 v35, v35, v52, v60
	v_max3_f32 v34, v34, v56, v244
	v_max_f32_e32 v18, v8, v5
	v_min_f32_e32 v5, v8, v5
	v_max_f32_e32 v8, v4, v15
	v_min_f32_e32 v4, v4, v15
	v_max_f32_e32 v15, v9, v17
	v_min_f32_e32 v9, v9, v17
	v_max_f32_e32 v17, v6, v11
	v_min_f32_e32 v6, v6, v11
	v_max_f32_e32 v11, v12, v14
	v_min_f32_e32 v12, v12, v14
	v_max_f32_e32 v14, v10, v7
	v_min_f32_e32 v7, v10, v7
	v_max_f32_e32 v10, v13, v3
	v_min_f32_e32 v3, v13, v3
	v_max_f32_e32 v13, v16, v2
	v_min_f32_e32 v2, v16, v2
	v_max_f32_e32 v42, v26, v36
	v_min_f32_e32 v26, v26, v36
	v_max_f32_e32 v36, v27, v37
	v_min_f32_e32 v27, v27, v37
	v_max_f32_e32 v37, v28, v38
	v_min_f32_e32 v28, v28, v38
	v_max_f32_e32 v38, v29, v40
	v_min_f32_e32 v29, v29, v40
	v_max_f32_e32 v40, v30, v41
	v_min_f32_e32 v30, v30, v41
	v_max_f32_e32 v41, v31, v39
	v_min_f32_e32 v31, v31, v39
	v_max_f32_e32 v39, v32, v35
	v_min_f32_e32 v32, v32, v35
	v_max_f32_e32 v35, v33, v34
	v_min_f32_e32 v33, v33, v34
	v_max_f32_e32 v16, v18, v11
	v_min_f32_e32 v11, v18, v11
	v_max_f32_e32 v18, v8, v14
	v_min_f32_e32 v8, v8, v14
	v_max_f32_e32 v14, v15, v10
	v_min_f32_e32 v10, v15, v10
	v_max_f32_e32 v15, v17, v13
	v_min_f32_e32 v13, v17, v13
	v_max_f32_e32 v17, v5, v12
	v_min_f32_e32 v5, v5, v12
	v_max_f32_e32 v12, v4, v7
	v_min_f32_e32 v4, v4, v7
	v_max_f32_e32 v7, v9, v3
	v_min_f32_e32 v3, v9, v3
	v_max_f32_e32 v9, v6, v2
	v_min_f32_e32 v2, v6, v2
	v_max_f32_e32 v34, v42, v40
	v_min_f32_e32 v40, v42, v40
	v_max_f32_e32 v42, v36, v41
	v_min_f32_e32 v36, v36, v41
	v_max_f32_e32 v41, v37, v39
	v_min_f32_e32 v37, v37, v39
	v_max_f32_e32 v39, v38, v35
	v_min_f32_e32 v35, v38, v35
	v_max_f32_e32 v38, v26, v30
	v_min_f32_e32 v26, v26, v30
	v_max_f32_e32 v30, v27, v31
	v_min_f32_e32 v27, v27, v31
	v_max_f32_e32 v31, v28, v32
	v_min_f32_e32 v28, v28, v32
	v_max_f32_e32 v32, v29, v33
	v_min_f32_e32 v29, v29, v33
	v_max_f32_e32 v6, v16, v14
	v_min_f32_e32 v14, v16, v14
	v_max_f32_e32 v16, v18, v15
	v_min_f32_e32 v15, v18, v15
	v_max_f32_e32 v18, v11, v10
	v_min_f32_e32 v10, v11, v10
	v_max_f32_e32 v11, v8, v13
	v_min_f32_e32 v8, v8, v13
	v_max_f32_e32 v13, v17, v7
	v_min_f32_e32 v7, v17, v7
	v_max_f32_e32 v17, v12, v9
	v_min_f32_e32 v9, v12, v9
	v_max_f32_e32 v12, v5, v3
	v_min_f32_e32 v3, v5, v3
	v_max_f32_e32 v5, v4, v2
	v_min_f32_e32 v2, v4, v2
	v_max_f32_e32 v33, v34, v41
	v_min_f32_e32 v34, v34, v41
	v_max_f32_e32 v41, v42, v39
	v_min_f32_e32 v39, v42, v39
	v_max_f32_e32 v42, v40, v37
	v_min_f32_e32 v37, v40, v37
	v_max_f32_e32 v40, v36, v35
	v_min_f32_e32 v35, v36, v35
	v_max_f32_e32 v36, v38, v31
	v_min_f32_e32 v31, v38, v31
	v_max_f32_e32 v38, v30, v32
	v_min_f32_e32 v30, v30, v32
	v_max_f32_e32 v32, v26, v28
	v_min_f32_e32 v26, v26, v28
	v_max_f32_e32 v28, v27, v29
	v_min_f32_e32 v27, v27, v29
	v_min_f32_e32 v4, v6, v16
	v_min_f32_e32 v19, v14, v15
	v_min_f32_e32 v20, v18, v11
	v_min_f32_e32 v21, v10, v8
	v_min_f32_e32 v22, v13, v17
	v_min_f32_e32 v23, v7, v9
	v_min_f32_e32 v24, v12, v5
	v_min_f32_e32 v25, v3, v2
	v_min_f32_e32 v29, v33, v41
	v_min_f32_e32 v43, v34, v39
	v_min_f32_e32 v44, v42, v40
	v_min_f32_e32 v45, v37, v35
	v_min_f32_e32 v46, v36, v38
	v_min_f32_e32 v47, v31, v30
	v_min_f32_e32 v48, v32, v28
	v_min_f32_e32 v49, v26, v27
	v_max3_f32 v6, v6, v16, v49
	v_max3_f32 v4, v4, v26, v27
	v_max3_f32 v14, v14, v15, v48
	v_max3_f32 v15, v19, v32, v28
	v_max3_f32 v11, v18, v11, v47
	v_max3_f32 v16, v20, v31, v30
	v_max3_f32 v8, v10, v8, v46
	v_max3_f32 v10, v21, v36, v38
	v_max3_f32 v13, v13, v17, v45
	v_max3_f32 v17, v22, v37, v35
	v_max3_f32 v7, v7, v9, v44
	v_max3_f32 v9, v23, v42, v40
	v_max3_f32 v5, v12, v5, v43
	v_max3_f32 v12, v24, v34, v39
	v_max3_f32 v2, v3, v2, v29
	v_max3_f32 v3, v25, v33, v41
	v_max_f32_e32 v18, v6, v13
	v_min_f32_e32 v6, v6, v13
	v_max_f32_e32 v13, v4, v17
	v_min_f32_e32 v4, v4, v17
	v_max_f32_e32 v17, v14, v7
	v_min_f32_e32 v7, v14, v7
	v_max_f32_e32 v14, v15, v9
	v_min_f32_e32 v9, v15, v9
	v_max_f32_e32 v15, v11, v5
	v_min_f32_e32 v5, v11, v5
	v_max_f32_e32 v11, v16, v12
	v_min_f32_e32 v12, v16, v12
	v_max_f32_e32 v16, v8, v2
	v_min_f32_e32 v2, v8, v2
	v_max_f32_e32 v8, v10, v3
	v_min_f32_e32 v3, v10, v3
	v_max_f32_e32 v10, v18, v15
	v_min_f32_e32 v15, v18, v15
	v_max_f32_e32 v18, v13, v11
	v_min_f32_e32 v11, v13, v11
	v_max_f32_e32 v13, v17, v16
	v_min_f32_e32 v16, v17, v16
	v_max_f32_e32 v17, v14, v8
	v_min_f32_e32 v8, v14, v8
	v_max_f32_e32 v14, v6, v5
	v_min_f32_e32 v5, v6, v5
	v_max_f32_e32 v6, v4, v12
	v_min_f32_e32 v4, v4, v12
; #define LAS __attribute__((address_space(3)))
; __device__ __forceinline__ void phase_topk_fast(LAS unsigned char* lds, const bf16* Q, const bf16* keysb  , int* EID, float* GATE, bool prestaged  ) {
;     ...
;                 for (int i = 0; i < 16; ++i) o[i] = __shfl_xor(v[i], 32);
; #pragma unroll
;                 for (int i = 0; i < 16; ++i) v[i] = fmaxf(v[i], o[15 - i]);
;                 bmerge16_desc<0, 64>(v);
; #pragma unroll
;                 for (int i = 0; i < 16; ++i) { if (p == 0) ta[i] = v[i]; else tb[i] = v[i]; }
;                 __builtin_amdgcn_sched_barrier(0);
;             }
;             float av[16], bv[16]; int ai[16], bi[16];
; #pragma unroll
;             for (int i = 0; i < 16; ++i) { const unsigned ua = __builtin_bit_cast(unsigned, ta[i]), ub = __builtin_bit_cast(unsigned, tb[i]);
;                 av[i] = __builtin_bit_cast(float, ua & ~127u); ai[i] = (int)(ua & 127u); bv[i] = __builtin_bit_cast(float, ub & ~127u); bi[i] = (int)(ub & 127u); }
;             LAS int* etab = (LAS int*)(lds + 69632 + wave * 8192) + c * 64;
; #pragma unroll
;             for (int s2 = 0; s2 < 32; ++s2) {
;                 const int p0 = (ai[pair_i(s2)] << 7) | bi[pair_j(s2)]; int p1 = 0;
;                 if (s2 + 32 < 50) p1 = (ai[pair_i(s2 + 32 < 50 ? s2 + 32 : 0)] << 7) | bi[pair_j(s2 + 32 < 50 ? s2 + 32 : 0)];
;                 etab[s2 + 32 * hh] = hh ? p1 : p0;
	v_max_f32_e32 v12, v7, v2
	v_min_f32_e32 v2, v7, v2
	v_max_f32_e32 v7, v9, v3
	v_min_f32_e32 v3, v9, v3
	v_max_f32_e32 v9, v10, v13
	v_min_f32_e32 v10, v10, v13
	v_max_f32_e32 v13, v18, v17
	v_min_f32_e32 v17, v18, v17
	v_max_f32_e32 v18, v15, v16
	v_min_f32_e32 v15, v15, v16
	v_max_f32_e32 v16, v11, v8
	v_min_f32_e32 v8, v11, v8
	v_max_f32_e32 v11, v14, v12
	v_min_f32_e32 v12, v14, v12
	v_max_f32_e32 v14, v6, v7
	v_min_f32_e32 v6, v6, v7
	v_max_f32_e32 v7, v5, v2
	v_min_f32_e32 v2, v5, v2
	v_max_f32_e32 v5, v4, v3
	v_min_f32_e32 v3, v4, v3
	v_max_f32_e32 v4, v9, v13
	v_min_f32_e32 v9, v9, v13
	v_max_f32_e32 v13, v10, v17
	v_min_f32_e32 v10, v10, v17
	v_max_f32_e32 v17, v18, v16
	v_min_f32_e32 v16, v18, v16
	v_max_f32_e32 v18, v15, v8
	v_min_f32_e32 v8, v15, v8
	v_max_f32_e32 v15, v11, v14
	v_min_f32_e32 v11, v11, v14
	v_max_f32_e32 v14, v12, v6
	v_min_f32_e32 v6, v12, v6
	v_max_f32_e32 v12, v7, v5
	v_min_f32_e32 v5, v7, v5
	v_max_f32_e32 v7, v2, v3
	v_min_f32_e32 v2, v2, v3
	ds_bpermute_b32 v29, v203, v2
	ds_bpermute_b32 v31, v203, v7
	ds_bpermute_b32 v33, v203, v5
	ds_bpermute_b32 v32, v203, v12
	ds_bpermute_b32 v3, v203, v4
	ds_bpermute_b32 v19, v203, v9
	ds_bpermute_b32 v20, v203, v13
	ds_bpermute_b32 v21, v203, v10
	ds_bpermute_b32 v22, v203, v17
	ds_bpermute_b32 v23, v203, v16
	ds_bpermute_b32 v24, v203, v18
	ds_bpermute_b32 v25, v203, v8
	ds_bpermute_b32 v26, v203, v15
	ds_bpermute_b32 v27, v203, v11
	ds_bpermute_b32 v28, v203, v14
	ds_bpermute_b32 v30, v203, v6
	s_waitcnt lgkmcnt(14)
	v_max_f32_e32 v4, v4, v29
	v_max_f32_e32 v29, v31, v31
	v_max_f32_e32 v9, v9, v29
	s_waitcnt lgkmcnt(13)
	v_max_f32_e32 v29, v33, v33
	v_max_f32_e32 v13, v13, v29
	s_waitcnt lgkmcnt(12)
	v_max_f32_e32 v29, v32, v32
	v_max_f32_e32 v10, v10, v29
	s_waitcnt lgkmcnt(0)
	v_max_f32_e32 v29, v30, v30
	v_max_f32_e32 v17, v17, v29
	v_max_f32_e32 v16, v16, v28
	v_max_f32_e32 v18, v18, v27
	v_max_f32_e32 v8, v8, v26
	v_max_f32_e32 v15, v15, v25
	v_max_f32_e32 v11, v11, v24
	v_max_f32_e32 v14, v14, v23
	v_max_f32_e32 v6, v6, v22
	v_max_f32_e32 v12, v12, v21
	v_max_f32_e32 v5, v5, v20
	v_max_f32_e32 v7, v7, v19
	v_max_f32_e32 v2, v2, v3
	v_max_f32_e32 v3, v4, v15
	v_min_f32_e32 v4, v4, v15
	v_max_f32_e32 v15, v9, v11
	v_min_f32_e32 v9, v9, v11
	v_max_f32_e32 v11, v13, v14
	v_min_f32_e32 v13, v13, v14
	v_max_f32_e32 v14, v10, v6
	v_min_f32_e32 v6, v10, v6
	v_max_f32_e32 v10, v17, v12
	v_min_f32_e32 v12, v17, v12
	v_max_f32_e32 v17, v16, v5
	v_min_f32_e32 v5, v16, v5
	v_max_f32_e32 v16, v18, v7
	v_min_f32_e32 v7, v18, v7
	v_max_f32_e32 v18, v8, v2
	v_min_f32_e32 v2, v8, v2
	v_max_f32_e32 v8, v3, v10
	v_min_f32_e32 v3, v3, v10
	v_max_f32_e32 v10, v15, v17
	v_min_f32_e32 v15, v15, v17
	v_max_f32_e32 v17, v11, v16
	v_min_f32_e32 v11, v11, v16
	v_max_f32_e32 v16, v14, v18
	v_min_f32_e32 v14, v14, v18
	v_max_f32_e32 v18, v4, v12
	v_min_f32_e32 v4, v4, v12
	v_max_f32_e32 v12, v9, v5
	v_min_f32_e32 v5, v9, v5
	v_max_f32_e32 v9, v13, v7
	v_min_f32_e32 v7, v13, v7
	v_max_f32_e32 v13, v6, v2
	v_min_f32_e32 v2, v6, v2
	v_max_f32_e32 v6, v8, v17
	v_min_f32_e32 v8, v8, v17
	v_max_f32_e32 v17, v10, v16
	v_min_f32_e32 v10, v10, v16
	v_max_f32_e32 v16, v3, v11
	v_min_f32_e32 v3, v3, v11
	v_max_f32_e32 v11, v15, v14
	v_min_f32_e32 v14, v15, v14
	v_max_f32_e32 v15, v18, v9
	v_min_f32_e32 v9, v18, v9
	v_max_f32_e32 v18, v12, v13
	v_min_f32_e32 v12, v12, v13
	v_max_f32_e32 v13, v4, v7
	v_min_f32_e32 v4, v4, v7
	v_max_f32_e32 v7, v5, v2
	v_min_f32_e32 v2, v5, v2
	v_max_f32_e32 v5, v6, v17
	v_min_f32_e32 v6, v6, v17
	v_max_f32_e32 v17, v8, v10
	v_min_f32_e32 v8, v8, v10
	v_max_f32_e32 v10, v16, v11
	v_min_f32_e32 v11, v16, v11
	v_max_f32_e32 v16, v3, v14
	v_min_f32_e32 v3, v3, v14
	v_max_f32_e32 v14, v15, v18
	v_min_f32_e32 v15, v15, v18
	v_max_f32_e32 v18, v9, v12
	v_min_f32_e32 v12, v9, v12
	v_max_f32_e32 v19, v13, v7
	v_min_f32_e32 v13, v13, v7
	v_max_f32_e32 v20, v4, v2
	v_min_f32_e32 v21, v4, v2
	v_and_b32_e32 v27, 0xffffff80, v3
	v_and_b32_e32 v28, 0x7f, v3
	v_lshlrev_b32_e32 v2, 7, v219
	v_and_b32_e32 v35, 0xffffff80, v5
	v_and_b32_e32 v36, 0xffffff80, v6
	v_and_b32_e32 v7, 0x7f, v6
	v_and_b32_e32 v6, 0x7f, v5
	v_lshlrev_b32_e32 v3, 7, v218
	v_lshlrev_b32_e32 v5, 7, v217
	v_and_b32_e32 v34, 0x3f80, v2
	v_and_b32_e32 v39, 0x7f, v8
	v_and_b32_e32 v41, 0x3f80, v3
	v_and_b32_e32 v42, 0x3f80, v5
	v_and_b32_e32 v25, 0xffffff80, v17
	v_and_b32_e32 v17, 0x7f, v17
	v_or_b32_e32 v2, v7, v34
	v_or_b32_e32 v4, v6, v34
	v_or_b32_e32 v3, v6, v41
	v_or_b32_e32 v5, v39, v42
	v_cndmask_b32_e64 v3, v3, v2, s[4:5]
	v_cndmask_b32_e64 v2, v5, v4, s[4:5]
	v_or_b32_e32 v4, v17, v34
	v_or_b32_e32 v5, v7, v41
	v_cndmask_b32_e64 v4, v5, v4, s[4:5]
	v_or_b32_e32 v5, v39, v34
	v_or_b32_e32 v41, v17, v41
	v_cndmask_b32_e64 v5, v41, v5, s[4:5]
	ds_write_b128 v201, v[2:5]
	v_lshlrev_b32_e32 v3, 7, v216
	v_lshlrev_b32_e32 v4, 7, v215
	v_and_b32_e32 v26, 0xffffff80, v10
	v_and_b32_e32 v10, 0x7f, v10
	v_and_b32_e32 v38, 0xffffff80, v8
	v_pk_mov_b32 v[8:9], v[6:7], v[6:7] op_sel:[1,0]
	v_and_b32_e32 v43, 0xffffff80, v11
	v_and_b32_e32 v11, 0x7f, v11
	v_and_b32_e32 v5, 0x3f80, v3
	v_and_b32_e32 v3, 0x3f80, v4
	v_or_b32_e32 v2, v10, v34
	v_and_b32_e32 v45, 0xffffff80, v16
	v_and_b32_e32 v16, 0x7f, v16
	v_or_b32_e32 v4, v6, v3
	v_or_b32_e32 v46, v11, v34
	v_or_b32_e32 v3, v8, v3
	v_cndmask_b32_e64 v2, v4, v2, s[4:5]
	v_or_b32_e32 v4, v16, v34
	v_or_b32_e32 v47, v9, v5
	v_cndmask_b32_e64 v3, v3, v46, s[4:5]
	v_or_b32_e32 v46, v28, v34
	v_or_b32_e32 v5, v7, v5
	v_cndmask_b32_e64 v4, v47, v4, s[4:5]
	v_cndmask_b32_e64 v5, v5, v46, s[4:5]
	ds_write_b128 v201, v[2:5] offset:16
	v_and_b32_e32 v47, 0xffffff80, v18
; __device__ __forceinline__ void phase_topk_fast(LAS unsigned char* lds, const bf16* Q, const bf16* keysb  , int* EID, float* GATE, bool prestaged  ) {
;     ...
;             for (int s2 = 0; s2 < 32; ++s2) {
;                 const int p0 = (ai[pair_i(s2)] << 7) | bi[pair_j(s2)]; int p1 = 0;
;                 if (s2 + 32 < 50) p1 = (ai[pair_i(s2 + 32 < 50 ? s2 + 32 : 0)] << 7) | bi[pair_j(s2 + 32 < 50 ? s2 + 32 : 0)];
;                 etab[s2 + 32 * hh] = hh ? p1 : p0;
;             }
;             __builtin_amdgcn_sched_barrier(0);
;             float ck[32];
; #pragma unroll
;             for (int s2 = 0; s2 < 32; ++s2) {
;                 const float k0 = av[pair_i(s2)] + bv[pair_j(s2)]; float k1 = -3.0e38f;
;                 if (s2 + 32 < 50) k1 = av[pair_i(s2 + 32 < 50 ? s2 + 32 : 0)] + bv[pair_j(s2 + 32 < 50 ? s2 + 32 : 0)];
;                 const float kk = hh ? k1 : k0;
;                 ck[s2] = __uint_as_float((__float_as_uint(kk) & ~63u) | (unsigned)(s2 + 32 * hh));
	v_and_b32_e32 v3, 0x7f, v18
	v_lshlrev_b32_e32 v18, 7, v213
	v_and_b32_e32 v46, 0xffffff80, v15
	v_and_b32_e32 v4, 0x7f, v15
	v_lshlrev_b32_e32 v15, 7, v214
	v_and_b32_e32 v18, 0x3f80, v18
	v_and_or_b32 v2, v14, s29, v34
	v_and_b32_e32 v15, 0x3f80, v15
	v_or_b32_e32 v48, v6, v18
	v_cndmask_b32_e64 v2, v48, v2, s[4:5]
	v_or_b32_e32 v3, v3, v34
	v_or_b32_e32 v48, v4, v34
	v_or_b32_e32 v4, v9, v15
	v_or_b32_e32 v8, v8, v18
	v_cndmask_b32_e64 v4, v4, v3, s[4:5]
	v_cndmask_b32_e64 v3, v8, v48, s[4:5]
	v_lshlrev_b32_e32 v18, 7, v211
	ds_write_b96 v201, v[2:4] offset:32
	v_and_b32_e32 v4, 0xffffff80, v12
	v_and_b32_e32 v12, 0x7f, v12
	v_lshlrev_b32_e32 v15, 7, v212
	v_and_b32_e32 v18, 0x3f80, v18
	v_and_b32_e32 v9, 0x7f, v19
	v_or_b32_e32 v12, v12, v34
	v_and_b32_e32 v15, 0x3f80, v15
	v_or_b32_e32 v18, v6, v18
	v_and_b32_e32 v8, 0xffffff80, v19
	v_or_b32_e32 v9, v9, v34
	v_or_b32_e32 v15, v6, v15
	v_cndmask_b32_e64 v12, v18, v12, s[4:5]
	v_and_b32_e32 v18, 0xffffff80, v20
	v_and_b32_e32 v19, 0x7f, v20
	v_lshlrev_b32_e32 v20, 7, v210
	v_lshlrev_b32_e32 v48, 7, v209
	v_cndmask_b32_e64 v9, v15, v9, s[4:5]
	v_and_b32_e32 v15, 0xffffff80, v13
	v_and_b32_e32 v13, 0x7f, v13
	v_and_b32_e32 v20, 0x3f80, v20
	v_and_b32_e32 v48, 0x3f80, v48
	v_or_b32_e32 v19, v19, v34
	v_or_b32_e32 v13, v13, v34
	v_or_b32_e32 v20, v6, v20
	v_or_b32_e32 v48, v6, v48
	v_cndmask_b32_e64 v19, v20, v19, s[4:5]
	v_cndmask_b32_e64 v13, v48, v13, s[4:5]
	ds_write2_b32 v201, v13, v19 offset0:13 offset1:14
	v_lshlrev_b32_e32 v19, 7, v208
	v_and_or_b32 v13, v21, s29, v34
	v_and_or_b32 v19, v19, s30, v6
	v_cndmask_b32_e64 v13, v19, v13, s[4:5]
	v_lshlrev_b32_e32 v19, 7, v205
	v_lshlrev_b32_e32 v20, 7, v207
	v_and_b32_e32 v19, 0x3f80, v19
	v_and_b32_e32 v20, 0x3f80, v20
	v_cndmask_b32_e64 v20, v20, v19, s[4:5]
	v_or_b32_e32 v20, v6, v20
	ds_write2_b32 v201, v13, v20 offset0:15 offset1:16
	v_lshlrev_b32_e32 v20, 7, v206
	v_or_b32_e32 v13, v7, v19
	v_and_or_b32 v20, v20, s30, v6
	v_cndmask_b32_e64 v13, v20, v13, s[4:5]
	v_or_b32_e32 v20, v17, v19
	v_cndmask_b32_e64 v20, 0, v20, s[4:5]
	ds_write2_b32 v201, v13, v20 offset0:17 offset1:18
	v_or_b32_e32 v13, v39, v19
	v_or_b32_e32 v20, v10, v19
	v_cndmask_b32_e64 v13, 0, v13, s[4:5]
	v_cndmask_b32_e64 v20, 0, v20, s[4:5]
	ds_write2_b32 v201, v13, v20 offset0:19 offset1:20
	v_or_b32_e32 v11, v11, v19
	v_or_b32_e32 v13, v16, v19
	v_cndmask_b32_e64 v11, 0, v11, s[4:5]
	v_cndmask_b32_e64 v13, 0, v13, s[4:5]
	ds_write2_b32 v201, v11, v13 offset0:21 offset1:22
	v_lshlrev_b32_e32 v13, 7, v204
	v_and_b32_e32 v13, 0x3f80, v13
	v_or_b32_e32 v11, v28, v19
	v_or_b32_e32 v16, v6, v13
	v_cndmask_b32_e64 v11, 0, v11, s[4:5]
	v_cndmask_b32_e64 v16, 0, v16, s[4:5]
	ds_write2_b32 v201, v11, v16 offset0:23 offset1:24
	v_or_b32_e32 v11, v7, v13
	v_or_b32_e32 v16, v17, v13
	v_or_b32_e32 v6, v6, v42
	v_or_b32_e32 v7, v7, v42
	v_cndmask_b32_e64 v11, 0, v11, s[4:5]
	v_cndmask_b32_e64 v16, 0, v16, s[4:5]
	v_cndmask_b32_e64 v6, 0, v6, s[4:5]
	v_cndmask_b32_e64 v7, 0, v7, s[4:5]
	ds_write2_b32 v201, v11, v16 offset0:25 offset1:26
	v_or_b32_e32 v11, v39, v13
	v_or_b32_e32 v10, v10, v13
	ds_write2_b32 v201, v6, v7 offset0:29 offset1:30
	v_or_b32_e32 v6, v17, v42
	v_and_b32_e32 v22, 0xffffff80, v219
	v_and_b32_e32 v23, 0xffffff80, v205
	v_and_b32_e32 v24, 0xffffff80, v204
	v_and_b32_e32 v29, 0xffffff80, v14
	v_and_b32_e32 v30, 0xffffff80, v208
	v_and_b32_e32 v31, 0xffffff80, v207
	v_and_b32_e32 v32, 0xffffff80, v206
	v_and_b32_e32 v33, 0xffffff80, v21
	v_and_b32_e32 v5, 0xffffff80, v213
	v_and_b32_e32 v14, 0xffffff80, v214
	v_and_b32_e32 v2, 0xffffff80, v211
	v_and_b32_e32 v3, 0xffffff80, v212
	ds_write2_b32 v201, v12, v9 offset0:11 offset1:12
	v_and_b32_e32 v9, 0xffffff80, v209
	v_and_b32_e32 v12, 0xffffff80, v210
	v_cndmask_b32_e64 v11, 0, v11, s[4:5]
	v_cndmask_b32_e64 v10, 0, v10, s[4:5]
	v_cndmask_b32_e64 v6, 0, v6, s[4:5]
	v_and_b32_e32 v37, 0xffffff80, v217
	v_and_b32_e32 v40, 0xffffff80, v218
	v_and_b32_e32 v41, 0xffffff80, v215
	v_and_b32_e32 v44, 0xffffff80, v216
	ds_write2_b32 v201, v11, v10 offset0:27 offset1:28
	ds_write_b32 v201, v6 offset:124
	v_add_f32_e32 v6, v22, v35
	v_add_f32_e32 v7, v37, v38
	v_cndmask_b32_e64 v6, v7, v6, s[4:5]
	v_add_f32_e32 v7, v22, v36
	v_add_f32_e32 v10, v40, v35
	v_cndmask_b32_e64 v7, v10, v7, s[4:5]
	v_add_f32_e32 v10, v22, v25
	v_add_f32_e32 v11, v40, v36
	v_cndmask_b32_e64 v10, v11, v10, s[4:5]
	v_add_f32_e32 v11, v22, v38
	v_add_f32_e32 v13, v40, v25
	v_cndmask_b32_e64 v11, v13, v11, s[4:5]
	v_add_f32_e32 v13, v22, v26
	v_add_f32_e32 v16, v41, v35
	v_cndmask_b32_e64 v13, v16, v13, s[4:5]
	v_add_f32_e32 v16, v22, v43
	v_add_f32_e32 v17, v41, v36
	v_cndmask_b32_e64 v16, v17, v16, s[4:5]
	v_add_f32_e32 v17, v22, v45
	v_add_f32_e32 v19, v44, v35
	v_add_f32_e32 v4, v22, v4
	v_add_f32_e32 v2, v2, v35
	v_cndmask_b32_e64 v17, v19, v17, s[4:5]
	v_add_f32_e32 v19, v22, v27
	v_add_f32_e32 v20, v44, v36
	v_cndmask_b32_e64 v2, v2, v4, s[4:5]
	v_add_f32_e32 v4, v22, v8
	v_add_f32_e32 v3, v3, v35
	v_cndmask_b32_e64 v19, v20, v19, s[4:5]
	v_add_f32_e32 v20, v22, v29
	v_add_f32_e32 v21, v5, v35
	v_cndmask_b32_e64 v3, v3, v4, s[4:5]
	v_add_f32_e32 v4, v22, v15
	v_add_f32_e32 v8, v9, v35
	v_cndmask_b32_e64 v20, v21, v20, s[4:5]
	v_add_f32_e32 v21, v22, v46
	v_add_f32_e32 v5, v5, v36
	v_cndmask_b32_e64 v4, v8, v4, s[4:5]
	v_add_f32_e32 v8, v22, v18
	v_add_f32_e32 v9, v12, v35
	v_cndmask_b32_e64 v5, v5, v21, s[4:5]
	v_add_f32_e32 v21, v22, v47
	v_add_f32_e32 v14, v14, v35
	v_cndmask_b32_e64 v8, v9, v8, s[4:5]
	v_add_f32_e32 v9, v22, v33
	v_add_f32_e32 v12, v30, v35
	v_add_f32_e32 v15, v23, v36
	v_add_f32_e32 v18, v32, v35
; __device__ __forceinline__ void phase_topk_fast(LAS unsigned char* lds, const bf16* Q, const bf16* keysb  , int* EID, float* GATE, bool prestaged  ) {
;     ...
;             float ck[32];
; #pragma unroll
;             for (int s2 = 0; s2 < 32; ++s2) {
;                 const float k0 = av[pair_i(s2)] + bv[pair_j(s2)]; float k1 = -3.0e38f;
;                 if (s2 + 32 < 50) k1 = av[pair_i(s2 + 32 < 50 ? s2 + 32 : 0)] + bv[pair_j(s2 + 32 < 50 ? s2 + 32 : 0)];
;                 const float kk = hh ? k1 : k0;
;                 ck[s2] = __uint_as_float((__float_as_uint(kk) & ~63u) | (unsigned)(s2 + 32 * hh));
;             }
;             __builtin_amdgcn_sched_barrier(0);
;             bsort16_desc<0, 32>(ck); bsort16_desc<16, 32>(ck);
	v_cndmask_b32_e64 v14, v14, v21, s[4:5]
	v_cndmask_b32_e64 v9, v12, v9, s[4:5]
	v_cndmask_b32_e64 v12, v31, v23, s[4:5]
	v_cndmask_b32_e64 v15, v18, v15, s[4:5]
	v_add_f32_e32 v18, v23, v25
	v_add_f32_e32 v21, v23, v38
	v_add_f32_e32 v22, v23, v26
	v_add_f32_e32 v28, v23, v43
	v_add_f32_e32 v29, v23, v45
	v_add_f32_e32 v23, v23, v27
	v_add_f32_e32 v27, v24, v35
	v_add_f32_e32 v30, v24, v36
	v_add_f32_e32 v31, v24, v25
	v_add_f32_e32 v32, v24, v38
	v_add_f32_e32 v24, v24, v26
	v_add_f32_e32 v26, v37, v35
	v_add_f32_e32 v33, v37, v36
	v_add_f32_e32 v25, v37, v25
	v_and_b32_e32 v18, 0xffffffc0, v18
	v_and_b32_e32 v21, 0xffffffc0, v21
	v_and_b32_e32 v22, 0xffffffc0, v22
	v_and_b32_e32 v28, 0xffffffc0, v28
	v_and_b32_e32 v29, 0xffffffc0, v29
	v_and_b32_e32 v23, 0xffffffc0, v23
	v_and_b32_e32 v27, 0xffffffc0, v27
	v_and_b32_e32 v30, 0xffffffc0, v30
	v_and_b32_e32 v31, 0xffffffc0, v31
	v_and_b32_e32 v32, 0xffffffc0, v32
	v_and_b32_e32 v24, 0xffffffc0, v24
	v_and_b32_e32 v26, 0xffffffc0, v26
	v_and_b32_e32 v33, 0xffffffc0, v33
	v_and_b32_e32 v25, 0xffffffc0, v25
	v_add_f32_e32 v12, v12, v35
	v_cndmask_b32_e64 v18, v202, v18, s[4:5]
	v_cndmask_b32_e64 v21, v202, v21, s[4:5]
	v_cndmask_b32_e64 v22, v202, v22, s[4:5]
	v_cndmask_b32_e64 v28, v202, v28, s[4:5]
	v_cndmask_b32_e64 v29, v202, v29, s[4:5]
	v_cndmask_b32_e64 v23, v202, v23, s[4:5]
	v_cndmask_b32_e64 v27, v202, v27, s[4:5]
	v_cndmask_b32_e64 v30, v202, v30, s[4:5]
	v_cndmask_b32_e64 v31, v202, v31, s[4:5]
	v_cndmask_b32_e64 v32, v202, v32, s[4:5]
	v_cndmask_b32_e64 v24, v202, v24, s[4:5]
	v_cndmask_b32_e64 v26, v202, v26, s[4:5]
	v_cndmask_b32_e64 v33, v202, v33, s[4:5]
	v_cndmask_b32_e64 v25, v202, v25, s[4:5]
	v_and_or_b32 v6, v6, s31, v102
	v_and_or_b32 v7, v7, s31, v168
	v_and_or_b32 v10, v10, s31, v169
	v_and_or_b32 v11, v11, s31, v170
	v_and_or_b32 v13, v13, s31, v171
	v_and_or_b32 v16, v16, s31, v172
	v_and_or_b32 v17, v17, s31, v173
	v_and_or_b32 v19, v19, s31, v174
	v_and_or_b32 v20, v20, s31, v175
	v_and_or_b32 v5, v5, s31, v176
	v_and_or_b32 v14, v14, s31, v177
	v_and_or_b32 v2, v2, s31, v178
	v_and_or_b32 v3, v3, s31, v179
	v_and_or_b32 v4, v4, s31, v180
	v_and_or_b32 v8, v8, s31, v181
	v_and_or_b32 v9, v9, s31, v182
	v_and_or_b32 v12, v12, s31, v183
	v_and_or_b32 v15, v15, s31, v184
	v_or_b32_e32 v18, v18, v185
	v_or_b32_e32 v21, v21, v187
	v_or_b32_e32 v22, v22, v188
	v_or_b32_e32 v28, v28, v189
	v_or_b32_e32 v29, v29, v190
	v_or_b32_e32 v23, v23, v191
	v_or_b32_e32 v27, v27, v192
	v_or_b32_e32 v30, v30, v193
	v_or_b32_e32 v31, v31, v194
	v_or_b32_e32 v32, v32, v195
	v_or_b32_e32 v24, v24, v196
	v_or_b32_e32 v26, v26, v197
	v_or_b32_e32 v33, v33, v198
	v_or_b32_e32 v25, v25, v199
	v_max_f32_e32 v34, v6, v4
	v_min_f32_e32 v4, v6, v4
	v_max_f32_e32 v6, v7, v7
	v_max_f32_e32 v42, v12, v26
	v_min_f32_e32 v12, v12, v26
	v_max_f32_e32 v26, v15, v24
	v_min_f32_e32 v15, v15, v24
	v_max_f32_e32 v24, v25, v25
	v_max_f32_e32 v7, v6, v3
	v_min_f32_e32 v3, v6, v3
	v_max_f32_e32 v6, v9, v9
	v_max_f32_e32 v9, v10, v10
	v_max_f32_e32 v25, v18, v24
	v_min_f32_e32 v18, v18, v24
	v_max_f32_e32 v24, v33, v33
	v_max_f32_e32 v10, v9, v6
	v_min_f32_e32 v6, v9, v6
	v_max_f32_e32 v9, v11, v11
	v_max_f32_e32 v33, v21, v24
	v_min_f32_e32 v21, v21, v24
	v_max_f32_e32 v24, v27, v27
	v_max_f32_e32 v11, v9, v8
	v_min_f32_e32 v8, v9, v8
	v_max_f32_e32 v9, v20, v20
	v_max_f32_e32 v27, v22, v24
	v_min_f32_e32 v22, v22, v24
	v_max_f32_e32 v24, v29, v29
	v_max_f32_e32 v20, v13, v9
	v_min_f32_e32 v9, v13, v9
	v_max_f32_e32 v13, v17, v17
	v_max_f32_e32 v29, v28, v24
	v_min_f32_e32 v24, v28, v24
	v_max_f32_e32 v28, v32, v32
	v_max_f32_e32 v17, v16, v13
	v_min_f32_e32 v13, v16, v13
	v_max_f32_e32 v16, v19, v19
	v_max_f32_e32 v32, v23, v28
	v_min_f32_e32 v23, v23, v28
	v_max_f32_e32 v28, v31, v31
	v_max_f32_e32 v19, v16, v2
	v_min_f32_e32 v2, v16, v2
	v_max_f32_e32 v16, v5, v14
	v_min_f32_e32 v5, v5, v14
	v_max_f32_e32 v31, v30, v28
	v_min_f32_e32 v28, v30, v28
	v_max_f32_e32 v14, v34, v17
	v_min_f32_e32 v17, v34, v17
	v_max_f32_e32 v34, v7, v19
	v_min_f32_e32 v7, v7, v19
	v_max_f32_e32 v19, v10, v16
	v_min_f32_e32 v10, v10, v16
	v_max_f32_e32 v16, v11, v20
	v_min_f32_e32 v11, v11, v20
	v_max_f32_e32 v20, v13, v4
	v_min_f32_e32 v4, v13, v4
	v_max_f32_e32 v13, v9, v8
	v_min_f32_e32 v8, v9, v8
	v_max_f32_e32 v9, v5, v6
	v_min_f32_e32 v5, v5, v6
	v_max_f32_e32 v6, v2, v3
	v_min_f32_e32 v2, v2, v3
	v_max_f32_e32 v30, v42, v29
	v_min_f32_e32 v29, v42, v29
	v_max_f32_e32 v42, v26, v32
	v_min_f32_e32 v26, v26, v32
	v_max_f32_e32 v32, v25, v31
	v_min_f32_e32 v25, v25, v31
	v_max_f32_e32 v31, v33, v27
	v_min_f32_e32 v27, v33, v27
	v_max_f32_e32 v33, v24, v12
	v_min_f32_e32 v12, v24, v12
	v_max_f32_e32 v24, v22, v21
	v_min_f32_e32 v21, v22, v21
	v_max_f32_e32 v22, v28, v18
	v_min_f32_e32 v18, v28, v18
	v_max_f32_e32 v28, v23, v15
	v_min_f32_e32 v15, v23, v15
	v_max_f32_e32 v3, v14, v34
	v_min_f32_e32 v14, v14, v34
	v_max_f32_e32 v34, v19, v16
	v_min_f32_e32 v16, v19, v16
	v_max_f32_e32 v19, v11, v17
	v_min_f32_e32 v11, v11, v17
	v_max_f32_e32 v17, v20, v13
	v_min_f32_e32 v13, v20, v13
	v_max_f32_e32 v20, v7, v10
	v_min_f32_e32 v7, v7, v10
	v_max_f32_e32 v10, v9, v6
	v_min_f32_e32 v6, v9, v6
	v_max_f32_e32 v9, v2, v4
	v_min_f32_e32 v2, v2, v4
	v_max_f32_e32 v4, v8, v5
	v_min_f32_e32 v5, v8, v5
	v_max_f32_e32 v23, v30, v42
	v_min_f32_e32 v30, v30, v42
	v_max_f32_e32 v42, v32, v31
	v_min_f32_e32 v31, v32, v31
	v_max_f32_e32 v32, v27, v29
	v_min_f32_e32 v27, v27, v29
	v_max_f32_e32 v29, v33, v24
	v_min_f32_e32 v24, v33, v24
	v_max_f32_e32 v33, v26, v25
	v_min_f32_e32 v25, v26, v25
	v_max_f32_e32 v26, v22, v28
	v_min_f32_e32 v22, v22, v28
; __device__ __forceinline__ void phase_topk_fast(LAS unsigned char* lds, const bf16* Q, const bf16* keysb  , int* EID, float* GATE, bool prestaged  ) {
;     ...
;             bsort16_desc<0, 32>(ck); bsort16_desc<16, 32>(ck);
;             merge_top16<0, 16, 32>(ck);
;             { float ok[16];
; #pragma unroll
;               for (int i = 0; i < 16; ++i) ok[i] = __shfl_xor(ck[i], 32);
; #pragma unroll
;               for (int i = 0; i < 16; ++i) ck[i] = fmaxf(ck[i], ok[15 - i]); }
;             bmerge16_desc<0, 32>(ck);
	v_max_f32_e32 v28, v15, v12
	v_min_f32_e32 v12, v15, v12
	v_max_f32_e32 v15, v21, v18
	v_min_f32_e32 v18, v21, v18
	v_min_f32_e32 v8, v3, v34
	v_max_f32_e32 v35, v14, v16
	v_min_f32_e32 v14, v14, v16
	v_max_f32_e32 v16, v19, v10
	v_min_f32_e32 v10, v19, v10
	v_max_f32_e32 v19, v11, v6
	v_min_f32_e32 v6, v11, v6
	v_max_f32_e32 v11, v17, v20
	v_min_f32_e32 v17, v17, v20
	v_max_f32_e32 v20, v13, v7
	v_min_f32_e32 v7, v13, v7
	v_max_f32_e32 v13, v9, v4
	v_min_f32_e32 v4, v9, v4
	v_max_f32_e32 v9, v2, v5
	v_min_f32_e32 v21, v23, v42
	v_max_f32_e32 v43, v30, v31
	v_min_f32_e32 v30, v30, v31
	v_max_f32_e32 v31, v32, v26
	v_min_f32_e32 v26, v32, v26
	v_max_f32_e32 v32, v27, v22
	v_min_f32_e32 v22, v27, v22
	v_max_f32_e32 v27, v29, v33
	v_min_f32_e32 v29, v29, v33
	v_max_f32_e32 v33, v24, v25
	v_min_f32_e32 v24, v24, v25
	v_max_f32_e32 v25, v28, v15
	v_min_f32_e32 v15, v28, v15
	v_max_f32_e32 v28, v12, v18
	v_min_f32_e32 v2, v2, v5
	v_max_f32_e32 v5, v35, v8
	v_min_f32_e32 v8, v35, v8
	v_max_f32_e32 v35, v14, v13
	v_min_f32_e32 v13, v14, v13
	v_max_f32_e32 v14, v16, v11
	v_min_f32_e32 v11, v16, v11
	v_max_f32_e32 v16, v19, v17
	v_min_f32_e32 v17, v19, v17
	v_max_f32_e32 v19, v20, v10
	v_min_f32_e32 v10, v20, v10
	v_max_f32_e32 v20, v7, v6
	v_min_f32_e32 v6, v7, v6
	v_max_f32_e32 v7, v9, v4
	v_min_f32_e32 v12, v12, v18
	v_max_f32_e32 v18, v43, v21
	v_min_f32_e32 v21, v43, v21
	v_max_f32_e32 v43, v30, v25
	v_min_f32_e32 v25, v30, v25
	v_max_f32_e32 v30, v31, v27
	v_min_f32_e32 v27, v31, v27
	v_max_f32_e32 v31, v32, v29
	v_min_f32_e32 v29, v32, v29
	v_max_f32_e32 v32, v33, v26
	v_min_f32_e32 v26, v33, v26
	v_max_f32_e32 v33, v24, v22
	v_min_f32_e32 v22, v24, v22
	v_max_f32_e32 v24, v28, v15
	v_min_f32_e32 v4, v9, v4
	v_max_f32_e32 v36, v8, v11
	v_min_f32_e32 v8, v8, v11
	v_max_f32_e32 v11, v16, v19
	v_min_f32_e32 v16, v16, v19
	v_max_f32_e32 v19, v17, v10
	v_min_f32_e32 v10, v17, v10
	v_max_f32_e32 v17, v20, v7
	v_min_f32_e32 v15, v28, v15
	v_max_f32_e32 v44, v21, v27
	v_min_f32_e32 v21, v21, v27
	v_max_f32_e32 v27, v31, v32
	v_min_f32_e32 v31, v31, v32
	v_max_f32_e32 v32, v29, v26
	v_min_f32_e32 v26, v29, v26
	v_max_f32_e32 v29, v33, v24
	v_min_f32_e32 v7, v20, v7
	v_max_f32_e32 v20, v6, v4
	v_max_f32_e32 v37, v35, v8
	v_min_f32_e32 v8, v35, v8
	v_max_f32_e32 v35, v17, v13
	v_min_f32_e32 v13, v17, v13
	v_min_f32_e32 v24, v33, v24
	v_max_f32_e32 v33, v22, v15
	v_max_f32_e32 v45, v43, v21
	v_min_f32_e32 v21, v43, v21
	v_max_f32_e32 v43, v29, v25
	v_min_f32_e32 v25, v29, v25
	v_min_f32_e32 v9, v5, v14
	v_max_f32_e32 v17, v20, v7
	v_min_f32_e32 v7, v20, v7
	v_max_f32_e32 v20, v37, v11
	v_min_f32_e32 v11, v37, v11
	v_max_f32_e32 v37, v8, v16
	v_min_f32_e32 v8, v8, v16
	v_max_f32_e32 v16, v19, v35
	v_min_f32_e32 v19, v19, v35
	v_max_f32_e32 v35, v10, v13
	v_min_f32_e32 v28, v18, v30
	v_max_f32_e32 v29, v33, v24
	v_min_f32_e32 v24, v33, v24
	v_max_f32_e32 v33, v45, v27
	v_min_f32_e32 v27, v45, v27
	v_max_f32_e32 v45, v21, v31
	v_min_f32_e32 v21, v21, v31
	v_max_f32_e32 v31, v32, v43
	v_min_f32_e32 v32, v32, v43
	v_max_f32_e32 v43, v26, v25
	v_min_f32_e32 v4, v6, v4
	v_min_f32_e32 v6, v36, v9
	v_min_f32_e32 v10, v10, v13
	v_min_f32_e32 v38, v11, v37
	v_max_f32_e32 v39, v16, v8
	v_min_f32_e32 v8, v16, v8
	v_max_f32_e32 v16, v19, v35
	v_min_f32_e32 v15, v22, v15
	v_min_f32_e32 v22, v44, v28
	v_min_f32_e32 v25, v26, v25
	v_min_f32_e32 v46, v27, v45
	v_max_f32_e32 v47, v31, v21
	v_min_f32_e32 v21, v31, v21
	v_max_f32_e32 v31, v32, v43
	v_min_f32_e32 v13, v20, v6
	v_min_f32_e32 v19, v19, v35
	v_min_f32_e32 v35, v17, v10
	v_min_f32_e32 v40, v38, v39
	v_min_f32_e32 v41, v8, v16
	v_min_f32_e32 v26, v33, v22
	v_min_f32_e32 v32, v32, v43
	v_min_f32_e32 v43, v29, v25
	v_min_f32_e32 v48, v46, v47
	v_min_f32_e32 v49, v21, v31
	v_max3_f32 v3, v3, v34, v12
	v_max3_f32 v5, v5, v14, v15
	v_max3_f32 v9, v36, v9, v24
	v_max3_f32 v6, v20, v6, v43
	v_max3_f32 v12, v13, v29, v25
	v_max3_f32 v11, v11, v37, v32
	v_max3_f32 v13, v38, v39, v49
	v_max3_f32 v14, v40, v21, v31
	v_max3_f32 v8, v8, v16, v48
	v_max3_f32 v15, v41, v46, v47
	v_max3_f32 v16, v19, v27, v45
	v_max3_f32 v10, v17, v10, v26
	v_max3_f32 v17, v35, v33, v22
	v_max3_f32 v7, v7, v44, v28
	v_max3_f32 v4, v4, v18, v30
	v_max3_f32 v2, v2, v23, v42
	v_max_f32_e32 v18, v3, v8
	v_min_f32_e32 v3, v3, v8
	v_max_f32_e32 v8, v5, v15
	v_min_f32_e32 v5, v5, v15
	v_max_f32_e32 v15, v9, v16
	v_min_f32_e32 v9, v9, v16
	v_max_f32_e32 v16, v6, v10
	v_min_f32_e32 v6, v6, v10
	v_max_f32_e32 v10, v12, v17
	v_min_f32_e32 v12, v12, v17
	v_max_f32_e32 v17, v11, v7
	v_min_f32_e32 v7, v11, v7
	v_max_f32_e32 v11, v13, v4
	v_min_f32_e32 v4, v13, v4
	v_max_f32_e32 v13, v14, v2
	v_min_f32_e32 v2, v14, v2
	v_max_f32_e32 v14, v18, v10
	v_min_f32_e32 v10, v18, v10
	v_max_f32_e32 v18, v8, v17
	v_min_f32_e32 v8, v8, v17
	v_max_f32_e32 v17, v15, v11
	v_min_f32_e32 v11, v15, v11
	v_max_f32_e32 v15, v16, v13
	v_min_f32_e32 v13, v16, v13
	v_max_f32_e32 v16, v3, v12
	v_min_f32_e32 v3, v3, v12
	v_max_f32_e32 v12, v5, v7
	v_min_f32_e32 v5, v5, v7
	v_max_f32_e32 v7, v9, v4
	v_min_f32_e32 v4, v9, v4
	v_max_f32_e32 v9, v6, v2
	v_min_f32_e32 v2, v6, v2
	v_max_f32_e32 v6, v14, v17
	v_min_f32_e32 v14, v14, v17
	v_max_f32_e32 v17, v18, v15
	v_min_f32_e32 v15, v18, v15
	v_max_f32_e32 v18, v10, v11
	v_min_f32_e32 v10, v10, v11
	v_max_f32_e32 v11, v8, v13
	v_min_f32_e32 v13, v8, v13
	v_max_f32_e32 v19, v16, v7
	v_min_f32_e32 v21, v16, v7
	v_max_f32_e32 v20, v12, v9
	v_min_f32_e32 v9, v12, v9
	v_max_f32_e32 v24, v3, v4
	v_min_f32_e32 v4, v3, v4
	v_max_f32_e32 v26, v5, v2
	v_min_f32_e32 v5, v5, v2
	v_max_f32_e32 v23, v6, v17
	v_min_f32_e32 v8, v6, v17
	v_max_f32_e32 v16, v14, v15
	v_min_f32_e32 v3, v14, v15
	v_max_f32_e32 v22, v18, v11
	v_min_f32_e32 v7, v18, v11
	v_max_f32_e32 v15, v10, v13
	v_min_f32_e32 v2, v10, v13
	v_max_f32_e32 v28, v19, v20
	v_min_f32_e32 v12, v19, v20
	v_max_f32_e32 v20, v21, v9
	v_min_f32_e32 v6, v21, v9
	v_max_f32_e32 v25, v24, v26
	v_min_f32_e32 v9, v24, v26
	v_max_f32_e32 v17, v4, v5
	v_min_f32_e32 v4, v4, v5
	ds_bpermute_b32 v5, v203, v23
	ds_bpermute_b32 v21, v203, v8
	ds_bpermute_b32 v13, v203, v16
	ds_bpermute_b32 v29, v203, v3
	ds_bpermute_b32 v10, v203, v22
	ds_bpermute_b32 v26, v203, v7
	ds_bpermute_b32 v18, v203, v15
	ds_bpermute_b32 v31, v203, v2
	ds_bpermute_b32 v11, v203, v28
	ds_bpermute_b32 v27, v203, v12
	ds_bpermute_b32 v19, v203, v20
	ds_bpermute_b32 v32, v203, v6
	ds_bpermute_b32 v14, v203, v25
	ds_bpermute_b32 v30, v203, v9
	ds_bpermute_b32 v24, v203, v17
	ds_bpermute_b32 v33, v203, v4
	s_and_saveexec_b64 s[18:19], s[4:5]
	s_cbranch_execz .LBB0_1809
; #define GAS __attribute__((address_space(1)))
; __device__ __forceinline__ void phase_topk_fast(LAS unsigned char* lds, const bf16* Q, const bf16* keysb  , int* EID, float* GATE, bool prestaged  ) {
;     ...
;             { float ok[16];
; #pragma unroll
;               for (int i = 0; i < 16; ++i) ok[i] = __shfl_xor(ck[i], 32);
; #pragma unroll
;               for (int i = 0; i < 16; ++i) ck[i] = fmaxf(ck[i], ok[15 - i]); }
;             bmerge16_desc<0, 32>(ck);
;             int cp[16];
; #pragma unroll
;             for (int i = 0; i < 16; ++i) { const unsigned u = __float_as_uint(ck[i]); cp[i] = etab[u & 63u]; ck[i] = __uint_as_float(u & ~63u); }
;             float ex[16]; float sum = 0.f;
; #pragma unroll
;             for (int i = 0; i < 16; ++i) { ex[i] = __expf(ck[i] - ck[0]); sum += ex[i]; }
;             const float inv = 1.f / sum;
;             if (hh == 0) {
;                 int* eo = EID + (tok0 + c) * 128 + h * 16; float* go = GATE + (tok0 + c) * 128 + h * 16;
; #pragma unroll
;                 for (int i = 0; i < 4; ++i) { *(GAS v4u*)(eo + 4 * i) = (v4u){(unsigned)cp[4 * i], (unsigned)cp[4 * i + 1], (unsigned)cp[4 * i + 2], (unsigned)cp[4 * i + 3]};
;                     *(GAS f32x4*)(go + 4 * i) = (f32x4){ex[4 * i] * inv, ex[4 * i + 1] * inv, ex[4 * i + 2] * inv, ex[4 * i + 3] * inv}; }
	s_waitcnt lgkmcnt(1)
	s_waitcnt lgkmcnt(0)
	v_max_f32_e32 v8, v8, v24
	v_max_f32_e32 v12, v12, v18
	v_max_f32_e32 v7, v7, v19
	v_max_f32_e32 v9, v9, v13
	v_max_f32_e32 v3, v3, v14
	v_max_f32_e32 v6, v6, v10
	v_max_f32_e32 v2, v2, v11
	v_max_f32_e32 v4, v4, v5
	v_max_f32_e32 v23, v23, v33
	v_max_f32_e32 v28, v28, v31
	v_max_f32_e32 v22, v22, v32
	v_max_f32_e32 v25, v25, v29
	v_max_f32_e32 v16, v16, v30
	v_max_f32_e32 v20, v20, v26
	v_max_f32_e32 v15, v15, v27
	v_max_f32_e32 v17, v17, v21
	v_max_f32_e32 v18, v8, v12
	v_max_f32_e32 v13, v7, v9
	v_max_f32_e32 v10, v3, v6
	v_max_f32_e32 v5, v2, v4
	v_max_f32_e32 v31, v23, v28
	v_max_f32_e32 v29, v22, v25
	v_max_f32_e32 v26, v16, v20
	v_max_f32_e32 v21, v15, v17
	v_max_f32_e32 v19, v18, v13
	v_max_f32_e32 v11, v10, v5
	v_max_f32_e32 v32, v31, v29
	v_max_f32_e32 v27, v26, v21
	v_max_f32_e32 v14, v19, v11
	v_min_f32_e32 v11, v19, v11
	v_min_f32_e32 v19, v31, v29
	v_min_f32_e32 v21, v26, v21
	v_min_f32_e32 v13, v18, v13
	v_min_f32_e32 v5, v10, v5
	v_max_f32_e32 v30, v32, v27
	v_max_f32_e32 v10, v13, v5
	v_min_f32_e32 v18, v19, v21
	v_min_f32_e32 v5, v13, v5
	v_max_f32_e32 v35, v30, v14
	v_min_f32_e32 v14, v30, v14
	v_max_f32_e32 v13, v18, v5
	v_min_f32_e32 v30, v18, v5
	v_min_f32_e32 v5, v23, v28
	v_min_f32_e32 v18, v22, v25
	v_min_f32_e32 v16, v16, v20
	v_min_f32_e32 v15, v15, v17
	v_min_f32_e32 v8, v8, v12
	v_min_f32_e32 v7, v7, v9
	v_min_f32_e32 v3, v3, v6
	v_min_f32_e32 v2, v2, v4
	v_max_f32_e32 v26, v19, v21
	v_max_f32_e32 v19, v5, v18
	v_max_f32_e32 v17, v16, v15
	v_max_f32_e32 v9, v8, v7
	v_max_f32_e32 v4, v3, v2
	v_min_f32_e32 v5, v5, v18
	v_min_f32_e32 v15, v16, v15
	v_min_f32_e32 v7, v8, v7
	v_min_f32_e32 v2, v3, v2
	v_max_f32_e32 v16, v5, v15
	v_max_f32_e32 v3, v7, v2
	v_min_f32_e32 v5, v5, v15
	v_min_f32_e32 v2, v7, v2
	v_max_f32_e32 v7, v5, v2
	v_min_f32_e32 v2, v5, v2
	v_max_f32_e32 v8, v16, v3
	v_min_f32_e32 v3, v16, v3
	v_and_b32_e32 v16, 0xffffffc0, v35
	v_and_b32_e32 v5, 0xffffffc0, v2
	v_sub_f32_e32 v5, v5, v16
	v_mul_f32_e32 v5, 0x3fb8aa3b, v5
	v_and_b32_e32 v15, 0xffffffc0, v7
	v_exp_f32_e32 v21, v5
	v_and_b32_e32 v5, 63, v7
	v_sub_f32_e32 v15, v15, v16
	v_lshl_add_u32 v7, v5, 2, v167
	v_and_b32_e32 v5, 0xffffffc0, v8
	v_max_f32_e32 v20, v19, v17
	v_max_f32_e32 v6, v9, v4
	v_mul_f32_e32 v15, 0x3fb8aa3b, v15
	v_sub_f32_e32 v5, v5, v16
	v_max_f32_e32 v12, v20, v6
	v_min_f32_e32 v6, v20, v6
	v_exp_f32_e32 v20, v15
	v_and_b32_e32 v15, 0xffffffc0, v3
	v_mul_f32_e32 v5, 0x3fb8aa3b, v5
	v_exp_f32_e32 v22, v5
	v_sub_f32_e32 v5, v15, v16
	v_min_f32_e32 v17, v19, v17
	v_min_f32_e32 v4, v9, v4
	v_mul_f32_e32 v5, 0x3fb8aa3b, v5
	v_max_f32_e32 v9, v17, v4
	v_exp_f32_e32 v23, v5
	v_and_b32_e32 v5, 63, v8
	v_lshl_add_u32 v8, v5, 2, v167
	v_and_b32_e32 v5, 0xffffffc0, v9
	v_min_f32_e32 v4, v17, v4
	v_sub_f32_e32 v17, v16, v16
	v_sub_f32_e32 v5, v5, v16
	v_and_b32_e32 v24, 0xffffffc0, v14
	v_mul_f32_e32 v17, 0x3fb8aa3b, v17
	v_and_b32_e32 v15, 0xffffffc0, v4
	v_mul_f32_e32 v5, 0x3fb8aa3b, v5
	v_exp_f32_e32 v18, v17
	v_sub_f32_e32 v17, v24, v16
	v_exp_f32_e32 v24, v5
	v_sub_f32_e32 v5, v15, v16
	v_mul_f32_e32 v5, 0x3fb8aa3b, v5
	v_and_b32_e32 v4, 63, v4
	v_exp_f32_e32 v25, v5
	v_and_b32_e32 v5, 63, v9
	v_lshl_add_u32 v9, v4, 2, v167
	v_and_b32_e32 v4, 0xffffffc0, v12
	v_sub_f32_e32 v4, v4, v16
	v_lshl_add_u32 v15, v5, 2, v167
	v_and_b32_e32 v5, 0xffffffc0, v6
	v_mul_f32_e32 v4, 0x3fb8aa3b, v4
	v_max_f32_e32 v34, v26, v10
	v_min_f32_e32 v10, v26, v10
	v_exp_f32_e32 v26, v4
	v_sub_f32_e32 v4, v5, v16
	v_min_f32_e32 v27, v32, v27
	v_mul_f32_e32 v4, 0x3fb8aa3b, v4
	v_max_f32_e32 v36, v27, v11
	v_min_f32_e32 v11, v27, v11
	v_and_b32_e32 v2, 63, v2
	v_and_b32_e32 v3, 63, v3
	v_exp_f32_e32 v27, v4
	v_and_b32_e32 v4, 63, v12
	v_and_b32_e32 v5, 63, v6
	v_lshl_add_u32 v2, v2, 2, v167
	v_lshl_add_u32 v3, v3, 2, v167
	v_lshl_add_u32 v6, v5, 2, v167
	v_lshl_add_u32 v12, v4, 2, v167
	ds_read_b32 v5, v2
	ds_read_b32 v4, v7
	ds_read_b32 v3, v3
	ds_read_b32 v2, v8
	ds_read_b32 v9, v9
	ds_read_b32 v8, v15
	ds_read_b32 v7, v6
	ds_read_b32 v6, v12
	v_and_b32_e32 v12, 0xffffffc0, v13
	v_sub_f32_e32 v12, v12, v16
	v_and_b32_e32 v15, 0xffffffc0, v30
	v_mul_f32_e32 v12, 0x3fb8aa3b, v12
	v_exp_f32_e32 v28, v12
	v_sub_f32_e32 v12, v15, v16
	v_and_b32_e32 v15, 0xffffffc0, v34
	v_sub_f32_e32 v15, v15, v16
	v_mul_f32_e32 v12, 0x3fb8aa3b, v12
	v_and_b32_e32 v31, 0xffffffc0, v10
	v_mul_f32_e32 v15, 0x3fb8aa3b, v15
	v_exp_f32_e32 v29, v12
	v_and_b32_e32 v12, 63, v13
	v_and_b32_e32 v13, 63, v30
	v_exp_f32_e32 v30, v15
	v_sub_f32_e32 v15, v31, v16
	v_and_b32_e32 v31, 0xffffffc0, v36
	v_mul_f32_e32 v17, 0x3fb8aa3b, v17
	v_and_b32_e32 v33, 0xffffffc0, v11
	v_sub_f32_e32 v31, v31, v16
	v_exp_f32_e32 v19, v17
	v_mul_f32_e32 v31, 0x3fb8aa3b, v31
	v_sub_f32_e32 v16, v33, v16
	v_exp_f32_e32 v32, v31
	v_mul_f32_e32 v16, 0x3fb8aa3b, v16
	v_exp_f32_e32 v33, v16
	v_add_f32_e32 v17, 0, v18
	v_mul_f32_e32 v15, 0x3fb8aa3b, v15
	v_add_f32_e32 v17, v19, v17
	v_exp_f32_e32 v31, v15
	v_add_f32_e32 v16, v32, v17
	v_add_f32_e32 v16, v33, v16
	v_add_f32_e32 v16, v30, v16
	v_add_f32_e32 v16, v31, v16
	v_add_f32_e32 v16, v28, v16
	v_add_f32_e32 v16, v29, v16
	v_add_f32_e32 v16, v26, v16
	v_add_f32_e32 v16, v27, v16
	v_add_f32_e32 v16, v24, v16
	v_add_f32_e32 v16, v25, v16
	v_add_f32_e32 v16, v22, v16
	v_add_f32_e32 v16, v23, v16
	v_add_f32_e32 v16, v20, v16
	v_add_f32_e32 v16, v21, v16
	v_div_scale_f32 v17, s[34:35], v16, v16, 1.0
	v_and_b32_e32 v15, 63, v34
	v_rcp_f32_e32 v34, v17
	v_and_b32_e32 v11, 63, v11
	v_and_b32_e32 v10, 63, v10
	v_lshl_add_u32 v13, v13, 2, v167
	v_fma_f32 v37, -v17, v34, 1.0
	v_fmac_f32_e32 v34, v37, v34
	v_div_scale_f32 v37, vcc, 1.0, v16, 1.0
	v_mul_f32_e32 v38, v37, v34
	v_fma_f32 v39, -v17, v38, v37
	v_fmac_f32_e32 v38, v39, v34
	v_fma_f32 v17, -v17, v38, v37
	v_div_fmas_f32 v17, v17, v34, v38
	v_div_fixup_f32 v34, v17, v16, 1.0
	v_and_b32_e32 v16, 63, v36
	v_lshl_add_u32 v17, v11, 2, v167
	v_and_b32_e32 v11, 63, v14
	v_lshl_add_u32 v12, v12, 2, v167
	v_lshl_add_u32 v10, v10, 2, v167
	v_lshl_add_u32 v15, v15, 2, v167
	v_lshl_add_u32 v16, v16, 2, v167
	v_lshl_add_u32 v14, v11, 2, v167
	v_and_b32_e32 v11, 63, v35
	v_lshl_add_u32 v35, v11, 2, v167
	ds_read_b32 v13, v13
	ds_read_b32 v12, v12
	ds_read_b32 v11, v10
	ds_read_b32 v10, v15
	ds_read_b32 v17, v17
	ds_read_b32 v16, v16
	ds_read_b32 v15, v14
	ds_read_b32 v14, v35
	s_lshl_b64 s[34:35], s[16:17], 14
	v_lshl_or_b32 v36, v100, 2, s34
	v_mov_b32_e32 v37, s35
	v_lshl_add_u64 v[38:39], s[12:13], 0, v[36:37]
	v_lshl_add_u64 v[36:37], s[14:15], 0, v[36:37]
	s_waitcnt lgkmcnt(0)
; #define GAS __attribute__((address_space(1)))
; __device__ __forceinline__ void phase_topk_fast(LAS unsigned char* lds, const bf16* Q, const bf16* keysb  , int* EID, float* GATE, bool prestaged  ) {
;     ...
;             if (hh == 0) {
;                 int* eo = EID + (tok0 + c) * 128 + h * 16; float* go = GATE + (tok0 + c) * 128 + h * 16;
; #pragma unroll
;                 for (int i = 0; i < 4; ++i) { *(GAS v4u*)(eo + 4 * i) = (v4u){(unsigned)cp[4 * i], (unsigned)cp[4 * i + 1], (unsigned)cp[4 * i + 2], (unsigned)cp[4 * i + 3]};
;                     *(GAS f32x4*)(go + 4 * i) = (f32x4){ex[4 * i] * inv, ex[4 * i + 1] * inv, ex[4 * i + 2] * inv, ex[4 * i + 3] * inv}; }
	global_store_dwordx4 v[38:39], v[14:17], off
	s_nop 1
	v_pk_mul_f32 v[16:17], v[32:33], v[34:35] op_sel_hi:[1,0]
	v_pk_mul_f32 v[14:15], v[18:19], v[34:35] op_sel_hi:[1,0]
	global_store_dwordx4 v[36:37], v[14:17], off
	global_store_dwordx4 v[38:39], v[10:13], off offset:16
	s_nop 1
	v_pk_mul_f32 v[12:13], v[28:29], v[34:35] op_sel_hi:[1,0]
	v_pk_mul_f32 v[10:11], v[30:31], v[34:35] op_sel_hi:[1,0]
	global_store_dwordx4 v[36:37], v[10:13], off offset:16
	global_store_dwordx4 v[38:39], v[6:9], off offset:32
	s_nop 1
	v_pk_mul_f32 v[8:9], v[24:25], v[34:35] op_sel_hi:[1,0]
	v_pk_mul_f32 v[6:7], v[26:27], v[34:35] op_sel_hi:[1,0]
	global_store_dwordx4 v[36:37], v[6:9], off offset:32
	global_store_dwordx4 v[38:39], v[2:5], off offset:48
	s_nop 1
	v_pk_mul_f32 v[4:5], v[20:21], v[34:35] op_sel_hi:[1,0]
	v_pk_mul_f32 v[2:3], v[22:23], v[34:35] op_sel_hi:[1,0]
	global_store_dwordx4 v[36:37], v[2:5], off offset:48
	s_branch .LBB0_1809
